# gemm-loops: setprio moved outside barrier pair, redundant lgkmcnt(0) and mid-block prio flips removed
# speedup vs baseline: 1.0046x; 1.0046x over previous
; #define PG8_STAGE(bufoff, gbase, voff) do { _Pragma("unroll") for (int _i = 0; _i < 2; ++_i) \
;         __builtin_amdgcn_global_load_lds((const unsigned*)((const char*)(gbase) + (voff)[_i]), (PG8_LAS unsigned*)(lds + (bufoff) + ldsw + _i * 8192), 16, 0, 0); } while (0)
; #define PG8_LDA(dst, b, h) do { _Pragma("unroll") for (int m = 0; m < 4; ++m) _Pragma("unroll") for (int k = 0; k < 2; ++k) dst[m][k] = *(const PG8_LAS bf16x8*)(lds + PG8_SA(b, h) + aoff + m * 2048 + k * 1024); } while (0)
; #define PG8_LDB(dst, b, h) do { _Pragma("unroll") for (int n = 0; n < 2; ++n) _Pragma("unroll") for (int k = 0; k < 2; ++k) dst[n][k] = *(const PG8_LAS bf16x8*)(lds + PG8_SB(b, h) + boff + n * 2048 + k * 1024); } while (0)
; #define PG8_MMA(ai, bj, At, Bt) do { __builtin_amdgcn_s_setprio(1); _Pragma("unroll") for (int m = 0; m < 4; ++m) _Pragma("unroll") for (int n = 0; n < 2; ++n) _Pragma("unroll") for (int k = 0; k < 2; ++k) \
;         acc[ai][bj][m][n] = __builtin_amdgcn_mfma_f32_16x16x32_bf16(Bt[n][k], At[m][k], acc[ai][bj][m][n], 0, 0, 0); __builtin_amdgcn_s_setprio(0); } while (0)
; #define PG8_WAIT_V(n) asm volatile("s_waitcnt vmcnt(" #n ")" ::: "memory")
; template <class Epi, class Sched, bool ALIGN_EPI = false, bool SP2 = false>
; __device__ __forceinline__ void gemm_phase(PG8_LAS unsigned char* lds, const Gemm g, const Sched& S, const Epi& E) {
;     ...
;             PG8_LDB(B0, 0, 0); PG8_LDB(B1, 0, 1); PG8_SCHED; PG8_LDA(At, 0, 0); PG8_STAGE(PG8_SA(1, 1), a1 + hstepA, voffA);
;             PG8_WAIT_V(8); PG8_WAIT_L(0); PG8_BAR; PG8_MMA(0, 0, At, B0); PG8_MMA(0, 1, At, B1); PG8_BAR; PG8_SCHED;
;             PG8_LDA(At, 0, 1); PG8_STAGE(PG8_SB(0, 0), b2, voffB); PG8_STAGE(PG8_SB(0, 1), b2 + hstepB, voffB); PG8_STAGE(PG8_SA(0, 0), a2, voffA);
;             PG8_WAIT_V(8); PG8_WAIT_L(0); PG8_BAR; PG8_MMA(1, 0, At, B0); PG8_MMA(1, 1, At, B1); PG8_BAR; PG8_SCHED;
;             PG8_LDB(B0, 1, 0); PG8_LDB(B1, 1, 1); PG8_SCHED; PG8_LDA(At, 1, 0); PG8_STAGE(PG8_SA(0, 1), a2 + hstepA, voffA);
;             PG8_WAIT_V(8); PG8_WAIT_L(0); PG8_BAR; PG8_MMA(0, 0, At, B0); PG8_MMA(0, 1, At, B1); PG8_BAR; PG8_SCHED;
;             PG8_LDA(At, 1, 1); PG8_STAGE(PG8_SB(1, 0), b3, voffB); PG8_STAGE(PG8_SB(1, 1), b3 + hstepB, voffB); PG8_STAGE(PG8_SA(1, 0), a3, voffA);
;             PG8_WAIT_V(8); PG8_WAIT_L(0); PG8_BAR; PG8_MMA(1, 0, At, B0); PG8_MMA(1, 1, At, B1); PG8_BAR; PG8_SCHED;
.LBB0_135:
	ds_read_b128 v[130:133], v151
	ds_read_b128 v[134:137], v151 offset:1024
	ds_read_b128 v[168:171], v151 offset:2048
	ds_read_b128 v[172:175], v151 offset:3072
	ds_read_b128 v[176:179], v153
	ds_read_b128 v[180:183], v153 offset:1024
	ds_read_b128 v[186:189], v153 offset:2048
	ds_read_b128 v[190:193], v153 offset:3072
	s_add_u32 s4, s12, 0xfffc0080
	s_addc_u32 s14, s13, -1
	s_cmp_eq_u32 s51, 12
	s_cselect_b32 s17, s11, s14
	s_cselect_b32 s16, s33, s4
	s_cselect_b32 s15, s36, s49
	s_cselect_b32 s14, s37, s38
	v_lshl_add_u64 v[226:227], s[12:13], 0, v[160:161]
	s_add_i32 m0, s35, 0xc000
	ds_read_b128 v[194:197], v155
	ds_read_b128 v[198:201], v155 offset:1024
	ds_read_b128 v[202:205], v155 offset:2048
	ds_read_b128 v[206:209], v155 offset:3072
	ds_read_b128 v[210:213], v155 offset:4096
	ds_read_b128 v[214:217], v155 offset:5120
	ds_read_b128 v[218:221], v155 offset:6144
	ds_read_b128 v[222:225], v155 offset:7168
	global_load_lds_dwordx4 v[226:227], off
	v_lshl_add_u64 v[226:227], s[12:13], 0, v[162:163]
	s_add_i32 m0, s35, 0xe000
	s_nop 0
	global_load_lds_dwordx4 v[226:227], off
	s_waitcnt vmcnt(8)
	s_waitcnt lgkmcnt(0)
	s_setprio 1
	s_barrier
	v_mfma_f32_16x16x32_bf16 v[126:129], v[130:133], v[194:197], v[126:129]
	v_mfma_f32_16x16x32_bf16 v[118:121], v[168:171], v[194:197], v[118:121]
	v_mfma_f32_16x16x32_bf16 v[110:113], v[130:133], v[202:205], v[110:113]
	v_mfma_f32_16x16x32_bf16 v[102:105], v[168:171], v[202:205], v[102:105]
	v_mfma_f32_16x16x32_bf16 v[94:97], v[130:133], v[210:213], v[94:97]
	v_mfma_f32_16x16x32_bf16 v[86:89], v[168:171], v[210:213], v[86:89]
	v_mfma_f32_16x16x32_bf16 v[78:81], v[130:133], v[218:221], v[78:81]
	v_mfma_f32_16x16x32_bf16 v[70:73], v[168:171], v[218:221], v[70:73]
	v_mfma_f32_16x16x32_bf16 v[126:129], v[134:137], v[198:201], v[126:129]
	v_mfma_f32_16x16x32_bf16 v[118:121], v[172:175], v[198:201], v[118:121]
	v_mfma_f32_16x16x32_bf16 v[110:113], v[134:137], v[206:209], v[110:113]
	v_mfma_f32_16x16x32_bf16 v[102:105], v[172:175], v[206:209], v[102:105]
	v_mfma_f32_16x16x32_bf16 v[94:97], v[134:137], v[214:217], v[94:97]
	v_mfma_f32_16x16x32_bf16 v[86:89], v[172:175], v[214:217], v[86:89]
	v_mfma_f32_16x16x32_bf16 v[78:81], v[134:137], v[222:225], v[78:81]
	v_mfma_f32_16x16x32_bf16 v[70:73], v[172:175], v[222:225], v[70:73]
	v_mfma_f32_16x16x32_bf16 v[122:125], v[176:179], v[194:197], v[122:125]
	v_mfma_f32_16x16x32_bf16 v[114:117], v[186:189], v[194:197], v[114:117]
	v_mfma_f32_16x16x32_bf16 v[106:109], v[176:179], v[202:205], v[106:109]
	v_mfma_f32_16x16x32_bf16 v[98:101], v[186:189], v[202:205], v[98:101]
	v_mfma_f32_16x16x32_bf16 v[90:93], v[176:179], v[210:213], v[90:93]
	v_mfma_f32_16x16x32_bf16 v[82:85], v[186:189], v[210:213], v[82:85]
	v_mfma_f32_16x16x32_bf16 v[74:77], v[176:179], v[218:221], v[74:77]
	v_mfma_f32_16x16x32_bf16 v[66:69], v[186:189], v[218:221], v[66:69]
	v_mfma_f32_16x16x32_bf16 v[122:125], v[180:183], v[198:201], v[122:125]
	v_mfma_f32_16x16x32_bf16 v[114:117], v[190:193], v[198:201], v[114:117]
	v_mfma_f32_16x16x32_bf16 v[106:109], v[180:183], v[206:209], v[106:109]
	v_mfma_f32_16x16x32_bf16 v[98:101], v[190:193], v[206:209], v[98:101]
	v_mfma_f32_16x16x32_bf16 v[90:93], v[180:183], v[214:217], v[90:93]
	v_mfma_f32_16x16x32_bf16 v[82:85], v[190:193], v[214:217], v[82:85]
	v_mfma_f32_16x16x32_bf16 v[74:77], v[180:183], v[222:225], v[74:77]
	v_mfma_f32_16x16x32_bf16 v[66:69], v[190:193], v[222:225], v[66:69]
	s_barrier
	s_setprio 0
	s_add_i32 s4, s89, s3
	v_lshl_add_u64 v[226:227], s[14:15], 0, v[140:141]
	s_mov_b32 m0, s4
	ds_read_b128 v[194:197], v155 offset:16384
	ds_read_b128 v[198:201], v155 offset:17408
	ds_read_b128 v[202:205], v155 offset:18432
	ds_read_b128 v[206:209], v155 offset:19456
	ds_read_b128 v[210:213], v155 offset:20480
	ds_read_b128 v[214:217], v155 offset:21504
	ds_read_b128 v[218:221], v155 offset:22528
	ds_read_b128 v[222:225], v155 offset:23552
	global_load_lds_dwordx4 v[226:227], off
	s_add_i32 m0, s4, 0x2000
	s_add_u32 s70, s14, 0x40000
	v_lshl_add_u64 v[228:229], s[14:15], 0, v[144:145]
	s_addc_u32 s71, s15, 0
	s_add_i32 s4, s90, s3
	global_load_lds_dwordx4 v[228:229], off
	v_lshl_add_u64 v[230:231], s[70:71], 0, v[140:141]
	s_mov_b32 m0, s4
	v_lshl_add_u64 v[232:233], s[16:17], 0, v[142:143]
	global_load_lds_dwordx4 v[230:231], off
	v_lshl_add_u64 v[230:231], s[70:71], 0, v[144:145]
	s_add_i32 m0, s4, 0x2000
	s_nop 0
	global_load_lds_dwordx4 v[230:231], off
	v_lshl_add_u64 v[230:231], s[16:17], 0, v[138:139]
	s_mov_b32 m0, s35
	s_nop 0
	global_load_lds_dwordx4 v[230:231], off
	s_mov_b32 m0, s47
	s_nop 0
	global_load_lds_dwordx4 v[232:233], off
	s_waitcnt vmcnt(8)
	s_waitcnt lgkmcnt(0)
	s_setprio 1
	s_barrier
; #define PG8_STAGE(bufoff, gbase, voff) do { _Pragma("unroll") for (int _i = 0; _i < 2; ++_i) \
;         __builtin_amdgcn_global_load_lds((const unsigned*)((const char*)(gbase) + (voff)[_i]), (PG8_LAS unsigned*)(lds + (bufoff) + ldsw + _i * 8192), 16, 0, 0); } while (0)
; #define PG8_LDA(dst, b, h) do { _Pragma("unroll") for (int m = 0; m < 4; ++m) _Pragma("unroll") for (int k = 0; k < 2; ++k) dst[m][k] = *(const PG8_LAS bf16x8*)(lds + PG8_SA(b, h) + aoff + m * 2048 + k * 1024); } while (0)
; #define PG8_LDB(dst, b, h) do { _Pragma("unroll") for (int n = 0; n < 2; ++n) _Pragma("unroll") for (int k = 0; k < 2; ++k) dst[n][k] = *(const PG8_LAS bf16x8*)(lds + PG8_SB(b, h) + boff + n * 2048 + k * 1024); } while (0)
; #define PG8_MMA(ai, bj, At, Bt) do { __builtin_amdgcn_s_setprio(1); _Pragma("unroll") for (int m = 0; m < 4; ++m) _Pragma("unroll") for (int n = 0; n < 2; ++n) _Pragma("unroll") for (int k = 0; k < 2; ++k) \
;         acc[ai][bj][m][n] = __builtin_amdgcn_mfma_f32_16x16x32_bf16(Bt[n][k], At[m][k], acc[ai][bj][m][n], 0, 0, 0); __builtin_amdgcn_s_setprio(0); } while (0)
; #define PG8_WAIT_V(n) asm volatile("s_waitcnt vmcnt(" #n ")" ::: "memory")
; template <class Epi, class Sched, bool ALIGN_EPI = false, bool SP2 = false>
; __device__ __forceinline__ void gemm_phase(PG8_LAS unsigned char* lds, const Gemm g, const Sched& S, const Epi& E) {
;     ...
;             PG8_LDB(B0, 0, 0); PG8_LDB(B1, 0, 1); PG8_SCHED; PG8_LDA(At, 0, 0); PG8_STAGE(PG8_SA(1, 1), a1 + hstepA, voffA);
;             PG8_WAIT_V(8); PG8_WAIT_L(0); PG8_BAR; PG8_MMA(0, 0, At, B0); PG8_MMA(0, 1, At, B1); PG8_BAR; PG8_SCHED;
;             PG8_LDA(At, 0, 1); PG8_STAGE(PG8_SB(0, 0), b2, voffB); PG8_STAGE(PG8_SB(0, 1), b2 + hstepB, voffB); PG8_STAGE(PG8_SA(0, 0), a2, voffA);
;             PG8_WAIT_V(8); PG8_WAIT_L(0); PG8_BAR; PG8_MMA(1, 0, At, B0); PG8_MMA(1, 1, At, B1); PG8_BAR; PG8_SCHED;
;             PG8_LDB(B0, 1, 0); PG8_LDB(B1, 1, 1); PG8_SCHED; PG8_LDA(At, 1, 0); PG8_STAGE(PG8_SA(0, 1), a2 + hstepA, voffA);
;             PG8_WAIT_V(8); PG8_WAIT_L(0); PG8_BAR; PG8_MMA(0, 0, At, B0); PG8_MMA(0, 1, At, B1); PG8_BAR; PG8_SCHED;
;             PG8_LDA(At, 1, 1); PG8_STAGE(PG8_SB(1, 0), b3, voffB); PG8_STAGE(PG8_SB(1, 1), b3 + hstepB, voffB); PG8_STAGE(PG8_SA(1, 0), a3, voffA);
;             PG8_WAIT_V(8); PG8_WAIT_L(0); PG8_BAR; PG8_MMA(1, 0, At, B0); PG8_MMA(1, 1, At, B1); PG8_BAR; PG8_SCHED;
	v_mfma_f32_16x16x32_bf16 v[62:65], v[130:133], v[194:197], v[62:65]
	v_mfma_f32_16x16x32_bf16 v[54:57], v[168:171], v[194:197], v[54:57]
	v_mfma_f32_16x16x32_bf16 v[46:49], v[130:133], v[202:205], v[46:49]
	v_mfma_f32_16x16x32_bf16 v[38:41], v[168:171], v[202:205], v[38:41]
	v_mfma_f32_16x16x32_bf16 v[30:33], v[130:133], v[210:213], v[30:33]
	v_mfma_f32_16x16x32_bf16 v[22:25], v[168:171], v[210:213], v[22:25]
	v_mfma_f32_16x16x32_bf16 v[14:17], v[130:133], v[218:221], v[14:17]
	v_mfma_f32_16x16x32_bf16 v[6:9], v[168:171], v[218:221], v[6:9]
	v_mfma_f32_16x16x32_bf16 v[62:65], v[134:137], v[198:201], v[62:65]
	v_mfma_f32_16x16x32_bf16 v[54:57], v[172:175], v[198:201], v[54:57]
	v_mfma_f32_16x16x32_bf16 v[46:49], v[134:137], v[206:209], v[46:49]
	v_mfma_f32_16x16x32_bf16 v[38:41], v[172:175], v[206:209], v[38:41]
	v_mfma_f32_16x16x32_bf16 v[30:33], v[134:137], v[214:217], v[30:33]
	v_mfma_f32_16x16x32_bf16 v[22:25], v[172:175], v[214:217], v[22:25]
	v_mfma_f32_16x16x32_bf16 v[14:17], v[134:137], v[222:225], v[14:17]
	v_mfma_f32_16x16x32_bf16 v[6:9], v[172:175], v[222:225], v[6:9]
	v_mfma_f32_16x16x32_bf16 v[58:61], v[176:179], v[194:197], v[58:61]
	v_mfma_f32_16x16x32_bf16 v[50:53], v[186:189], v[194:197], v[50:53]
	v_mfma_f32_16x16x32_bf16 v[42:45], v[176:179], v[202:205], v[42:45]
	v_mfma_f32_16x16x32_bf16 v[34:37], v[186:189], v[202:205], v[34:37]
	v_mfma_f32_16x16x32_bf16 v[26:29], v[176:179], v[210:213], v[26:29]
	v_mfma_f32_16x16x32_bf16 v[18:21], v[186:189], v[210:213], v[18:21]
	v_mfma_f32_16x16x32_bf16 v[10:13], v[176:179], v[218:221], v[10:13]
	v_mfma_f32_16x16x32_bf16 v[2:5], v[186:189], v[218:221], v[2:5]
	v_mfma_f32_16x16x32_bf16 v[58:61], v[180:183], v[198:201], v[58:61]
	v_mfma_f32_16x16x32_bf16 v[50:53], v[190:193], v[198:201], v[50:53]
	v_mfma_f32_16x16x32_bf16 v[42:45], v[180:183], v[206:209], v[42:45]
	v_mfma_f32_16x16x32_bf16 v[34:37], v[190:193], v[206:209], v[34:37]
	v_mfma_f32_16x16x32_bf16 v[26:29], v[180:183], v[214:217], v[26:29]
	v_mfma_f32_16x16x32_bf16 v[18:21], v[190:193], v[214:217], v[18:21]
	v_mfma_f32_16x16x32_bf16 v[10:13], v[180:183], v[222:225], v[10:13]
	v_mfma_f32_16x16x32_bf16 v[2:5], v[190:193], v[222:225], v[2:5]
	s_barrier
	s_setprio 0
	s_add_i32 s4, 0, 0x18000
	v_add_u32_e32 v146, s4, v149
	s_add_i32 s70, 0, 0x1c000
	ds_read_b128 v[130:133], v146
	ds_read_b128 v[134:137], v146 offset:1024
	ds_read_b128 v[168:171], v146 offset:2048
	ds_read_b128 v[172:175], v146 offset:3072
	v_add_u32_e32 v146, s70, v149
	ds_read_b128 v[176:179], v146
	ds_read_b128 v[180:183], v146 offset:1024
	ds_read_b128 v[186:189], v146 offset:2048
	ds_read_b128 v[190:193], v146 offset:3072
	s_add_u32 s16, s16, 0x40000
	s_addc_u32 s17, s17, 0
	s_mov_b32 m0, s82
	v_lshl_add_u64 v[236:237], s[16:17], 0, v[138:139]
	ds_read_b128 v[194:197], v155 offset:32768
	ds_read_b128 v[198:201], v155 offset:33792
	ds_read_b128 v[202:205], v155 offset:34816
	ds_read_b128 v[206:209], v155 offset:35840
	ds_read_b128 v[210:213], v155 offset:36864
	ds_read_b128 v[214:217], v155 offset:37888
	ds_read_b128 v[218:221], v155 offset:38912
	ds_read_b128 v[222:225], v155 offset:39936
	global_load_lds_dwordx4 v[236:237], off
	v_lshl_add_u64 v[236:237], s[16:17], 0, v[142:143]
	s_mov_b32 m0, s83
	s_nop 0
	global_load_lds_dwordx4 v[236:237], off
	s_waitcnt vmcnt(8)
	s_waitcnt lgkmcnt(0)
	s_setprio 1
	s_barrier
	v_mfma_f32_16x16x32_bf16 v[126:129], v[130:133], v[194:197], v[126:129]
	v_mfma_f32_16x16x32_bf16 v[118:121], v[168:171], v[194:197], v[118:121]
	v_mfma_f32_16x16x32_bf16 v[110:113], v[130:133], v[202:205], v[110:113]
	v_mfma_f32_16x16x32_bf16 v[102:105], v[168:171], v[202:205], v[102:105]
	v_mfma_f32_16x16x32_bf16 v[94:97], v[130:133], v[210:213], v[94:97]
	v_mfma_f32_16x16x32_bf16 v[86:89], v[168:171], v[210:213], v[86:89]
	v_mfma_f32_16x16x32_bf16 v[78:81], v[130:133], v[218:221], v[78:81]
	v_mfma_f32_16x16x32_bf16 v[70:73], v[168:171], v[218:221], v[70:73]
	v_mfma_f32_16x16x32_bf16 v[126:129], v[134:137], v[198:201], v[126:129]
	v_mfma_f32_16x16x32_bf16 v[118:121], v[172:175], v[198:201], v[118:121]
	v_mfma_f32_16x16x32_bf16 v[110:113], v[134:137], v[206:209], v[110:113]
	v_mfma_f32_16x16x32_bf16 v[102:105], v[172:175], v[206:209], v[102:105]
	v_mfma_f32_16x16x32_bf16 v[94:97], v[134:137], v[214:217], v[94:97]
	v_mfma_f32_16x16x32_bf16 v[86:89], v[172:175], v[214:217], v[86:89]
	v_mfma_f32_16x16x32_bf16 v[78:81], v[134:137], v[222:225], v[78:81]
	v_mfma_f32_16x16x32_bf16 v[70:73], v[172:175], v[222:225], v[70:73]
	v_mfma_f32_16x16x32_bf16 v[122:125], v[176:179], v[194:197], v[122:125]
	v_mfma_f32_16x16x32_bf16 v[114:117], v[186:189], v[194:197], v[114:117]
	v_mfma_f32_16x16x32_bf16 v[106:109], v[176:179], v[202:205], v[106:109]
	v_mfma_f32_16x16x32_bf16 v[98:101], v[186:189], v[202:205], v[98:101]
	v_mfma_f32_16x16x32_bf16 v[90:93], v[176:179], v[210:213], v[90:93]
	v_mfma_f32_16x16x32_bf16 v[82:85], v[186:189], v[210:213], v[82:85]
	v_mfma_f32_16x16x32_bf16 v[74:77], v[176:179], v[218:221], v[74:77]
	v_mfma_f32_16x16x32_bf16 v[66:69], v[186:189], v[218:221], v[66:69]
	v_mfma_f32_16x16x32_bf16 v[122:125], v[180:183], v[198:201], v[122:125]
	v_mfma_f32_16x16x32_bf16 v[114:117], v[190:193], v[198:201], v[114:117]
	v_mfma_f32_16x16x32_bf16 v[106:109], v[180:183], v[206:209], v[106:109]
	v_mfma_f32_16x16x32_bf16 v[98:101], v[190:193], v[206:209], v[98:101]
	v_mfma_f32_16x16x32_bf16 v[90:93], v[180:183], v[214:217], v[90:93]
	v_mfma_f32_16x16x32_bf16 v[82:85], v[190:193], v[214:217], v[82:85]
	v_mfma_f32_16x16x32_bf16 v[74:77], v[180:183], v[222:225], v[74:77]
	v_mfma_f32_16x16x32_bf16 v[66:69], v[190:193], v[222:225], v[66:69]
	s_barrier
; #define PG8_STAGE(bufoff, gbase, voff) do { _Pragma("unroll") for (int _i = 0; _i < 2; ++_i) \
;         __builtin_amdgcn_global_load_lds((const unsigned*)((const char*)(gbase) + (voff)[_i]), (PG8_LAS unsigned*)(lds + (bufoff) + ldsw + _i * 8192), 16, 0, 0); } while (0)
; #define PG8_LDA(dst, b, h) do { _Pragma("unroll") for (int m = 0; m < 4; ++m) _Pragma("unroll") for (int k = 0; k < 2; ++k) dst[m][k] = *(const PG8_LAS bf16x8*)(lds + PG8_SA(b, h) + aoff + m * 2048 + k * 1024); } while (0)
; #define PG8_LDB(dst, b, h) do { _Pragma("unroll") for (int n = 0; n < 2; ++n) _Pragma("unroll") for (int k = 0; k < 2; ++k) dst[n][k] = *(const PG8_LAS bf16x8*)(lds + PG8_SB(b, h) + boff + n * 2048 + k * 1024); } while (0)
; #define PG8_MMA(ai, bj, At, Bt) do { __builtin_amdgcn_s_setprio(1); _Pragma("unroll") for (int m = 0; m < 4; ++m) _Pragma("unroll") for (int n = 0; n < 2; ++n) _Pragma("unroll") for (int k = 0; k < 2; ++k) \
;         acc[ai][bj][m][n] = __builtin_amdgcn_mfma_f32_16x16x32_bf16(Bt[n][k], At[m][k], acc[ai][bj][m][n], 0, 0, 0); __builtin_amdgcn_s_setprio(0); } while (0)
; #define PG8_WAIT_V(n) asm volatile("s_waitcnt vmcnt(" #n ")" ::: "memory")
; template <class Epi, class Sched, bool ALIGN_EPI = false, bool SP2 = false>
; __device__ __forceinline__ void gemm_phase(PG8_LAS unsigned char* lds, const Gemm g, const Sched& S, const Epi& E) {
;     ...
;             PG8_LDB(B0, 0, 0); PG8_LDB(B1, 0, 1); PG8_SCHED; PG8_LDA(At, 0, 0); PG8_STAGE(PG8_SA(1, 1), a1 + hstepA, voffA);
;             PG8_WAIT_V(8); PG8_WAIT_L(0); PG8_BAR; PG8_MMA(0, 0, At, B0); PG8_MMA(0, 1, At, B1); PG8_BAR; PG8_SCHED;
;             PG8_LDA(At, 0, 1); PG8_STAGE(PG8_SB(0, 0), b2, voffB); PG8_STAGE(PG8_SB(0, 1), b2 + hstepB, voffB); PG8_STAGE(PG8_SA(0, 0), a2, voffA);
;             PG8_WAIT_V(8); PG8_WAIT_L(0); PG8_BAR; PG8_MMA(1, 0, At, B0); PG8_MMA(1, 1, At, B1); PG8_BAR; PG8_SCHED;
;             PG8_LDB(B0, 1, 0); PG8_LDB(B1, 1, 1); PG8_SCHED; PG8_LDA(At, 1, 0); PG8_STAGE(PG8_SA(0, 1), a2 + hstepA, voffA);
;             PG8_WAIT_V(8); PG8_WAIT_L(0); PG8_BAR; PG8_MMA(0, 0, At, B0); PG8_MMA(0, 1, At, B1); PG8_BAR; PG8_SCHED;
;             PG8_LDA(At, 1, 1); PG8_STAGE(PG8_SB(1, 0), b3, voffB); PG8_STAGE(PG8_SB(1, 1), b3 + hstepB, voffB); PG8_STAGE(PG8_SA(1, 0), a3, voffA);
;             PG8_WAIT_V(8); PG8_WAIT_L(0); PG8_BAR; PG8_MMA(1, 0, At, B0); PG8_MMA(1, 1, At, B1); PG8_BAR; PG8_SCHED;
	s_setprio 0
	s_add_i32 s4, s4, s3
	v_lshl_add_u64 v[226:227], v[226:227], 0, s[42:43]
	s_mov_b32 m0, s4
	ds_read_b128 v[194:197], v155 offset:49152
	ds_read_b128 v[198:201], v155 offset:50176
	ds_read_b128 v[202:205], v155 offset:51200
	ds_read_b128 v[206:209], v155 offset:52224
	ds_read_b128 v[210:213], v155 offset:53248
	ds_read_b128 v[214:217], v155 offset:54272
	ds_read_b128 v[218:221], v155 offset:55296
	ds_read_b128 v[222:225], v155 offset:56320
	global_load_lds_dwordx4 v[226:227], off
	s_add_i32 m0, s4, 0x2000
	s_add_u32 s14, s14, 0x40080
	v_lshl_add_u64 v[226:227], v[228:229], 0, s[42:43]
	s_addc_u32 s15, s15, 0
	s_add_i32 s4, s70, s3
	global_load_lds_dwordx4 v[226:227], off
	v_lshl_add_u64 v[226:227], s[14:15], 0, v[140:141]
	s_mov_b32 m0, s4
	s_nop 0
	global_load_lds_dwordx4 v[226:227], off
	v_lshl_add_u64 v[226:227], s[14:15], 0, v[144:145]
	s_add_i32 m0, s4, 0x2000
	s_nop 0
	global_load_lds_dwordx4 v[226:227], off
	v_lshl_add_u64 v[226:227], v[230:231], 0, s[42:43]
	s_mov_b32 m0, s87
	s_nop 0
	global_load_lds_dwordx4 v[226:227], off
	v_lshl_add_u64 v[226:227], v[232:233], 0, s[42:43]
	s_mov_b32 m0, s88
	s_nop 0
	global_load_lds_dwordx4 v[226:227], off
	s_waitcnt vmcnt(8)
	s_waitcnt lgkmcnt(0)
	s_setprio 1
	s_barrier
	v_mfma_f32_16x16x32_bf16 v[62:65], v[130:133], v[194:197], v[62:65]
	v_mfma_f32_16x16x32_bf16 v[54:57], v[168:171], v[194:197], v[54:57]
	v_mfma_f32_16x16x32_bf16 v[46:49], v[130:133], v[202:205], v[46:49]
	v_mfma_f32_16x16x32_bf16 v[38:41], v[168:171], v[202:205], v[38:41]
	v_mfma_f32_16x16x32_bf16 v[30:33], v[130:133], v[210:213], v[30:33]
	v_mfma_f32_16x16x32_bf16 v[22:25], v[168:171], v[210:213], v[22:25]
	v_mfma_f32_16x16x32_bf16 v[14:17], v[130:133], v[218:221], v[14:17]
	v_mfma_f32_16x16x32_bf16 v[6:9], v[168:171], v[218:221], v[6:9]
	v_mfma_f32_16x16x32_bf16 v[62:65], v[134:137], v[198:201], v[62:65]
	v_mfma_f32_16x16x32_bf16 v[54:57], v[172:175], v[198:201], v[54:57]
	v_mfma_f32_16x16x32_bf16 v[46:49], v[134:137], v[206:209], v[46:49]
	v_mfma_f32_16x16x32_bf16 v[38:41], v[172:175], v[206:209], v[38:41]
	v_mfma_f32_16x16x32_bf16 v[30:33], v[134:137], v[214:217], v[30:33]
	v_mfma_f32_16x16x32_bf16 v[22:25], v[172:175], v[214:217], v[22:25]
	v_mfma_f32_16x16x32_bf16 v[14:17], v[134:137], v[222:225], v[14:17]
	v_mfma_f32_16x16x32_bf16 v[6:9], v[172:175], v[222:225], v[6:9]
	v_mfma_f32_16x16x32_bf16 v[58:61], v[176:179], v[194:197], v[58:61]
	v_mfma_f32_16x16x32_bf16 v[50:53], v[186:189], v[194:197], v[50:53]
	v_mfma_f32_16x16x32_bf16 v[42:45], v[176:179], v[202:205], v[42:45]
	v_mfma_f32_16x16x32_bf16 v[34:37], v[186:189], v[202:205], v[34:37]
	v_mfma_f32_16x16x32_bf16 v[26:29], v[176:179], v[210:213], v[26:29]
	v_mfma_f32_16x16x32_bf16 v[18:21], v[186:189], v[210:213], v[18:21]
	v_mfma_f32_16x16x32_bf16 v[10:13], v[176:179], v[218:221], v[10:13]
	v_mfma_f32_16x16x32_bf16 v[2:5], v[186:189], v[218:221], v[2:5]
	v_mfma_f32_16x16x32_bf16 v[58:61], v[180:183], v[198:201], v[58:61]
	v_mfma_f32_16x16x32_bf16 v[50:53], v[190:193], v[198:201], v[50:53]
	v_mfma_f32_16x16x32_bf16 v[42:45], v[180:183], v[206:209], v[42:45]
	v_mfma_f32_16x16x32_bf16 v[34:37], v[190:193], v[206:209], v[34:37]
	v_mfma_f32_16x16x32_bf16 v[26:29], v[180:183], v[214:217], v[26:29]
	v_mfma_f32_16x16x32_bf16 v[18:21], v[190:193], v[214:217], v[18:21]
	v_mfma_f32_16x16x32_bf16 v[10:13], v[180:183], v[222:225], v[10:13]
	v_mfma_f32_16x16x32_bf16 v[2:5], v[190:193], v[222:225], v[2:5]
	s_barrier
	s_setprio 0
	s_add_i32 s51, s51, 2
	s_add_u32 s12, s12, 0x100
	s_addc_u32 s13, s13, 0
	s_add_u32 s38, s38, 0x100
	s_addc_u32 s49, s49, 0
	s_cmp_gt_u32 s51, 13
	s_cbranch_scc0 .LBB0_135
	s_and_b64 vcc, exec, s[44:45]
	s_cbranch_vccz .LBB0_138
	s_barrier

; #define PG8_STAGE(bufoff, gbase, voff) do { _Pragma("unroll") for (int _i = 0; _i < 2; ++_i) \
;         __builtin_amdgcn_global_load_lds((const unsigned*)((const char*)(gbase) + (voff)[_i]), (PG8_LAS unsigned*)(lds + (bufoff) + ldsw + _i * 8192), 16, 0, 0); } while (0)
; #define PG8_LDA(dst, b, h) do { _Pragma("unroll") for (int m = 0; m < 4; ++m) _Pragma("unroll") for (int k = 0; k < 2; ++k) dst[m][k] = *(const PG8_LAS bf16x8*)(lds + PG8_SA(b, h) + aoff + m * 2048 + k * 1024); } while (0)
; #define PG8_LDB(dst, b, h) do { _Pragma("unroll") for (int n = 0; n < 2; ++n) _Pragma("unroll") for (int k = 0; k < 2; ++k) dst[n][k] = *(const PG8_LAS bf16x8*)(lds + PG8_SB(b, h) + boff + n * 2048 + k * 1024); } while (0)
; #define PG8_MMA(ai, bj, At, Bt) do { __builtin_amdgcn_s_setprio(1); _Pragma("unroll") for (int m = 0; m < 4; ++m) _Pragma("unroll") for (int n = 0; n < 2; ++n) _Pragma("unroll") for (int k = 0; k < 2; ++k) \
;         acc[ai][bj][m][n] = __builtin_amdgcn_mfma_f32_16x16x32_bf16(Bt[n][k], At[m][k], acc[ai][bj][m][n], 0, 0, 0); __builtin_amdgcn_s_setprio(0); } while (0)
; #define PG8_WAIT_V(n) asm volatile("s_waitcnt vmcnt(" #n ")" ::: "memory")
; template <class Epi, class Sched, bool ALIGN_EPI = false, bool SP2 = false>
; __device__ __forceinline__ void gemm_phase(PG8_LAS unsigned char* lds, const Gemm g, const Sched& S, const Epi& E) {
;     ...
;             PG8_LDB(B0, 0, 0); PG8_LDB(B1, 0, 1); PG8_SCHED; PG8_LDA(At, 0, 0); PG8_STAGE(PG8_SA(1, 1), a1 + hstepA, voffA);
;             PG8_WAIT_V(8); PG8_WAIT_L(0); PG8_BAR; PG8_MMA(0, 0, At, B0); PG8_MMA(0, 1, At, B1); PG8_BAR; PG8_SCHED;
;             PG8_LDA(At, 0, 1); PG8_STAGE(PG8_SB(0, 0), b2, voffB); PG8_STAGE(PG8_SB(0, 1), b2 + hstepB, voffB); PG8_STAGE(PG8_SA(0, 0), a2, voffA);
;             PG8_WAIT_V(8); PG8_WAIT_L(0); PG8_BAR; PG8_MMA(1, 0, At, B0); PG8_MMA(1, 1, At, B1); PG8_BAR; PG8_SCHED;
;             PG8_LDB(B0, 1, 0); PG8_LDB(B1, 1, 1); PG8_SCHED; PG8_LDA(At, 1, 0); PG8_STAGE(PG8_SA(0, 1), a2 + hstepA, voffA);
;             PG8_WAIT_V(8); PG8_WAIT_L(0); PG8_BAR; PG8_MMA(0, 0, At, B0); PG8_MMA(0, 1, At, B1); PG8_BAR; PG8_SCHED;
;             PG8_LDA(At, 1, 1); PG8_STAGE(PG8_SB(1, 0), b3, voffB); PG8_STAGE(PG8_SB(1, 1), b3 + hstepB, voffB); PG8_STAGE(PG8_SA(1, 0), a3, voffA);
;             PG8_WAIT_V(8); PG8_WAIT_L(0); PG8_BAR; PG8_MMA(1, 0, At, B0); PG8_MMA(1, 1, At, B1); PG8_BAR; PG8_SCHED;
.LBB0_691:
	ds_read_b128 v[130:133], v151
	ds_read_b128 v[134:137], v151 offset:1024
	ds_read_b128 v[166:169], v151 offset:2048
	ds_read_b128 v[170:173], v151 offset:3072
	ds_read_b128 v[174:177], v153
	ds_read_b128 v[178:181], v153 offset:1024
	ds_read_b128 v[182:185], v153 offset:2048
	ds_read_b128 v[186:189], v153 offset:3072
	s_add_u32 s4, s8, 0xfffc0080
	s_addc_u32 s10, s9, -1
	s_cmp_eq_u32 s67, 12
	s_cselect_b32 s87, s3, s10
	s_cselect_b32 s86, s7, s4
	s_cselect_b32 s11, s33, s66
	s_cselect_b32 s10, s35, s46
	v_lshl_add_u64 v[222:223], s[8:9], 0, v[160:161]
	s_add_i32 m0, s38, 0xc000
	ds_read_b128 v[190:193], v155
	ds_read_b128 v[194:197], v155 offset:1024
	ds_read_b128 v[198:201], v155 offset:2048
	ds_read_b128 v[202:205], v155 offset:3072
	ds_read_b128 v[206:209], v155 offset:4096
	ds_read_b128 v[210:213], v155 offset:5120
	ds_read_b128 v[214:217], v155 offset:6144
	ds_read_b128 v[218:221], v155 offset:7168
	global_load_lds_dwordx4 v[222:223], off
	v_lshl_add_u64 v[222:223], s[8:9], 0, v[162:163]
	s_add_i32 m0, s38, 0xe000
	s_nop 0
	global_load_lds_dwordx4 v[222:223], off
	s_waitcnt vmcnt(8)
	s_waitcnt lgkmcnt(0)
	s_setprio 1
	s_barrier
	v_mfma_f32_16x16x32_bf16 v[126:129], v[130:133], v[190:193], v[126:129]
	v_mfma_f32_16x16x32_bf16 v[118:121], v[166:169], v[190:193], v[118:121]
	v_mfma_f32_16x16x32_bf16 v[110:113], v[130:133], v[198:201], v[110:113]
	v_mfma_f32_16x16x32_bf16 v[102:105], v[166:169], v[198:201], v[102:105]
	v_mfma_f32_16x16x32_bf16 v[94:97], v[130:133], v[206:209], v[94:97]
	v_mfma_f32_16x16x32_bf16 v[86:89], v[166:169], v[206:209], v[86:89]
	v_mfma_f32_16x16x32_bf16 v[78:81], v[130:133], v[214:217], v[78:81]
	v_mfma_f32_16x16x32_bf16 v[70:73], v[166:169], v[214:217], v[70:73]
	v_mfma_f32_16x16x32_bf16 v[126:129], v[134:137], v[194:197], v[126:129]
	v_mfma_f32_16x16x32_bf16 v[118:121], v[170:173], v[194:197], v[118:121]
	v_mfma_f32_16x16x32_bf16 v[110:113], v[134:137], v[202:205], v[110:113]
	v_mfma_f32_16x16x32_bf16 v[102:105], v[170:173], v[202:205], v[102:105]
	v_mfma_f32_16x16x32_bf16 v[94:97], v[134:137], v[210:213], v[94:97]
	v_mfma_f32_16x16x32_bf16 v[86:89], v[170:173], v[210:213], v[86:89]
	v_mfma_f32_16x16x32_bf16 v[78:81], v[134:137], v[218:221], v[78:81]
	v_mfma_f32_16x16x32_bf16 v[70:73], v[170:173], v[218:221], v[70:73]
	v_mfma_f32_16x16x32_bf16 v[122:125], v[174:177], v[190:193], v[122:125]
	v_mfma_f32_16x16x32_bf16 v[114:117], v[182:185], v[190:193], v[114:117]
	v_mfma_f32_16x16x32_bf16 v[106:109], v[174:177], v[198:201], v[106:109]
	v_mfma_f32_16x16x32_bf16 v[98:101], v[182:185], v[198:201], v[98:101]
	v_mfma_f32_16x16x32_bf16 v[90:93], v[174:177], v[206:209], v[90:93]
	v_mfma_f32_16x16x32_bf16 v[82:85], v[182:185], v[206:209], v[82:85]
	v_mfma_f32_16x16x32_bf16 v[74:77], v[174:177], v[214:217], v[74:77]
	v_mfma_f32_16x16x32_bf16 v[66:69], v[182:185], v[214:217], v[66:69]
	v_mfma_f32_16x16x32_bf16 v[122:125], v[178:181], v[194:197], v[122:125]
	v_mfma_f32_16x16x32_bf16 v[114:117], v[186:189], v[194:197], v[114:117]
	v_mfma_f32_16x16x32_bf16 v[106:109], v[178:181], v[202:205], v[106:109]
	v_mfma_f32_16x16x32_bf16 v[98:101], v[186:189], v[202:205], v[98:101]
	v_mfma_f32_16x16x32_bf16 v[90:93], v[178:181], v[210:213], v[90:93]
	v_mfma_f32_16x16x32_bf16 v[82:85], v[186:189], v[210:213], v[82:85]
	v_mfma_f32_16x16x32_bf16 v[74:77], v[178:181], v[218:221], v[74:77]
	v_mfma_f32_16x16x32_bf16 v[66:69], v[186:189], v[218:221], v[66:69]
	s_barrier
	s_setprio 0
	s_add_i32 s4, s47, s37
	v_lshl_add_u64 v[222:223], s[10:11], 0, v[140:141]
	s_mov_b32 m0, s4
	ds_read_b128 v[190:193], v155 offset:16384
	ds_read_b128 v[194:197], v155 offset:17408
	ds_read_b128 v[198:201], v155 offset:18432
	ds_read_b128 v[202:205], v155 offset:19456
	ds_read_b128 v[206:209], v155 offset:20480
	ds_read_b128 v[210:213], v155 offset:21504
	ds_read_b128 v[214:217], v155 offset:22528
	ds_read_b128 v[218:221], v155 offset:23552
	global_load_lds_dwordx4 v[222:223], off
	s_add_i32 m0, s4, 0x2000
	s_add_u32 s88, s10, 0x40000
	v_lshl_add_u64 v[224:225], s[10:11], 0, v[144:145]
	s_addc_u32 s89, s11, 0
	s_add_i32 s4, s48, s37
	global_load_lds_dwordx4 v[224:225], off
	v_lshl_add_u64 v[226:227], s[88:89], 0, v[140:141]
	s_mov_b32 m0, s4
	v_lshl_add_u64 v[228:229], s[86:87], 0, v[142:143]
	global_load_lds_dwordx4 v[226:227], off
	v_lshl_add_u64 v[226:227], s[88:89], 0, v[144:145]
	s_add_i32 m0, s4, 0x2000
	s_nop 0
	global_load_lds_dwordx4 v[226:227], off
	v_lshl_add_u64 v[226:227], s[86:87], 0, v[138:139]
	s_mov_b32 m0, s38
	s_nop 0
	global_load_lds_dwordx4 v[226:227], off
	s_mov_b32 m0, s39
	s_nop 0
	global_load_lds_dwordx4 v[228:229], off
	s_waitcnt vmcnt(8)
	s_waitcnt lgkmcnt(0)
	s_setprio 1
	s_barrier
; #define PG8_STAGE(bufoff, gbase, voff) do { _Pragma("unroll") for (int _i = 0; _i < 2; ++_i) \
;         __builtin_amdgcn_global_load_lds((const unsigned*)((const char*)(gbase) + (voff)[_i]), (PG8_LAS unsigned*)(lds + (bufoff) + ldsw + _i * 8192), 16, 0, 0); } while (0)
; #define PG8_LDA(dst, b, h) do { _Pragma("unroll") for (int m = 0; m < 4; ++m) _Pragma("unroll") for (int k = 0; k < 2; ++k) dst[m][k] = *(const PG8_LAS bf16x8*)(lds + PG8_SA(b, h) + aoff + m * 2048 + k * 1024); } while (0)
; #define PG8_LDB(dst, b, h) do { _Pragma("unroll") for (int n = 0; n < 2; ++n) _Pragma("unroll") for (int k = 0; k < 2; ++k) dst[n][k] = *(const PG8_LAS bf16x8*)(lds + PG8_SB(b, h) + boff + n * 2048 + k * 1024); } while (0)
; #define PG8_MMA(ai, bj, At, Bt) do { __builtin_amdgcn_s_setprio(1); _Pragma("unroll") for (int m = 0; m < 4; ++m) _Pragma("unroll") for (int n = 0; n < 2; ++n) _Pragma("unroll") for (int k = 0; k < 2; ++k) \
;         acc[ai][bj][m][n] = __builtin_amdgcn_mfma_f32_16x16x32_bf16(Bt[n][k], At[m][k], acc[ai][bj][m][n], 0, 0, 0); __builtin_amdgcn_s_setprio(0); } while (0)
; #define PG8_WAIT_V(n) asm volatile("s_waitcnt vmcnt(" #n ")" ::: "memory")
; template <class Epi, class Sched, bool ALIGN_EPI = false, bool SP2 = false>
; __device__ __forceinline__ void gemm_phase(PG8_LAS unsigned char* lds, const Gemm g, const Sched& S, const Epi& E) {
;     ...
;             PG8_LDB(B0, 0, 0); PG8_LDB(B1, 0, 1); PG8_SCHED; PG8_LDA(At, 0, 0); PG8_STAGE(PG8_SA(1, 1), a1 + hstepA, voffA);
;             PG8_WAIT_V(8); PG8_WAIT_L(0); PG8_BAR; PG8_MMA(0, 0, At, B0); PG8_MMA(0, 1, At, B1); PG8_BAR; PG8_SCHED;
;             PG8_LDA(At, 0, 1); PG8_STAGE(PG8_SB(0, 0), b2, voffB); PG8_STAGE(PG8_SB(0, 1), b2 + hstepB, voffB); PG8_STAGE(PG8_SA(0, 0), a2, voffA);
;             PG8_WAIT_V(8); PG8_WAIT_L(0); PG8_BAR; PG8_MMA(1, 0, At, B0); PG8_MMA(1, 1, At, B1); PG8_BAR; PG8_SCHED;
;             PG8_LDB(B0, 1, 0); PG8_LDB(B1, 1, 1); PG8_SCHED; PG8_LDA(At, 1, 0); PG8_STAGE(PG8_SA(0, 1), a2 + hstepA, voffA);
;             PG8_WAIT_V(8); PG8_WAIT_L(0); PG8_BAR; PG8_MMA(0, 0, At, B0); PG8_MMA(0, 1, At, B1); PG8_BAR; PG8_SCHED;
;             PG8_LDA(At, 1, 1); PG8_STAGE(PG8_SB(1, 0), b3, voffB); PG8_STAGE(PG8_SB(1, 1), b3 + hstepB, voffB); PG8_STAGE(PG8_SA(1, 0), a3, voffA);
;             PG8_WAIT_V(8); PG8_WAIT_L(0); PG8_BAR; PG8_MMA(1, 0, At, B0); PG8_MMA(1, 1, At, B1); PG8_BAR; PG8_SCHED;
	v_mfma_f32_16x16x32_bf16 v[62:65], v[130:133], v[190:193], v[62:65]
	v_mfma_f32_16x16x32_bf16 v[54:57], v[166:169], v[190:193], v[54:57]
	v_mfma_f32_16x16x32_bf16 v[46:49], v[130:133], v[198:201], v[46:49]
	v_mfma_f32_16x16x32_bf16 v[38:41], v[166:169], v[198:201], v[38:41]
	v_mfma_f32_16x16x32_bf16 v[30:33], v[130:133], v[206:209], v[30:33]
	v_mfma_f32_16x16x32_bf16 v[22:25], v[166:169], v[206:209], v[22:25]
	v_mfma_f32_16x16x32_bf16 v[14:17], v[130:133], v[214:217], v[14:17]
	v_mfma_f32_16x16x32_bf16 v[6:9], v[166:169], v[214:217], v[6:9]
	v_mfma_f32_16x16x32_bf16 v[62:65], v[134:137], v[194:197], v[62:65]
	v_mfma_f32_16x16x32_bf16 v[54:57], v[170:173], v[194:197], v[54:57]
	v_mfma_f32_16x16x32_bf16 v[46:49], v[134:137], v[202:205], v[46:49]
	v_mfma_f32_16x16x32_bf16 v[38:41], v[170:173], v[202:205], v[38:41]
	v_mfma_f32_16x16x32_bf16 v[30:33], v[134:137], v[210:213], v[30:33]
	v_mfma_f32_16x16x32_bf16 v[22:25], v[170:173], v[210:213], v[22:25]
	v_mfma_f32_16x16x32_bf16 v[14:17], v[134:137], v[218:221], v[14:17]
	v_mfma_f32_16x16x32_bf16 v[6:9], v[170:173], v[218:221], v[6:9]
	v_mfma_f32_16x16x32_bf16 v[58:61], v[174:177], v[190:193], v[58:61]
	v_mfma_f32_16x16x32_bf16 v[50:53], v[182:185], v[190:193], v[50:53]
	v_mfma_f32_16x16x32_bf16 v[42:45], v[174:177], v[198:201], v[42:45]
	v_mfma_f32_16x16x32_bf16 v[34:37], v[182:185], v[198:201], v[34:37]
	v_mfma_f32_16x16x32_bf16 v[26:29], v[174:177], v[206:209], v[26:29]
	v_mfma_f32_16x16x32_bf16 v[18:21], v[182:185], v[206:209], v[18:21]
	v_mfma_f32_16x16x32_bf16 v[10:13], v[174:177], v[214:217], v[10:13]
	v_mfma_f32_16x16x32_bf16 v[2:5], v[182:185], v[214:217], v[2:5]
	v_mfma_f32_16x16x32_bf16 v[58:61], v[178:181], v[194:197], v[58:61]
	v_mfma_f32_16x16x32_bf16 v[50:53], v[186:189], v[194:197], v[50:53]
	v_mfma_f32_16x16x32_bf16 v[42:45], v[178:181], v[202:205], v[42:45]
	v_mfma_f32_16x16x32_bf16 v[34:37], v[186:189], v[202:205], v[34:37]
	v_mfma_f32_16x16x32_bf16 v[26:29], v[178:181], v[210:213], v[26:29]
	v_mfma_f32_16x16x32_bf16 v[18:21], v[186:189], v[210:213], v[18:21]
	v_mfma_f32_16x16x32_bf16 v[10:13], v[178:181], v[218:221], v[10:13]
	v_mfma_f32_16x16x32_bf16 v[2:5], v[186:189], v[218:221], v[2:5]
	s_barrier
	s_setprio 0
	s_add_i32 s4, 0, 0x18000
	v_add_u32_e32 v146, s4, v149
	s_add_i32 s68, 0, 0x1c000
	ds_read_b128 v[130:133], v146
	ds_read_b128 v[134:137], v146 offset:1024
	ds_read_b128 v[166:169], v146 offset:2048
	ds_read_b128 v[170:173], v146 offset:3072
	v_add_u32_e32 v146, s68, v149
	ds_read_b128 v[174:177], v146
	ds_read_b128 v[178:181], v146 offset:1024
	ds_read_b128 v[182:185], v146 offset:2048
	ds_read_b128 v[186:189], v146 offset:3072
	s_add_u32 s86, s86, 0x40000
	s_addc_u32 s87, s87, 0
	s_mov_b32 m0, s40
	v_lshl_add_u64 v[230:231], s[86:87], 0, v[138:139]
	ds_read_b128 v[190:193], v155 offset:32768
	ds_read_b128 v[194:197], v155 offset:33792
	ds_read_b128 v[198:201], v155 offset:34816
	ds_read_b128 v[202:205], v155 offset:35840
	ds_read_b128 v[206:209], v155 offset:36864
	ds_read_b128 v[210:213], v155 offset:37888
	ds_read_b128 v[214:217], v155 offset:38912
	ds_read_b128 v[218:221], v155 offset:39936
	global_load_lds_dwordx4 v[230:231], off
	v_lshl_add_u64 v[230:231], s[86:87], 0, v[142:143]
	s_mov_b32 m0, s41
	s_nop 0
	global_load_lds_dwordx4 v[230:231], off
	s_waitcnt vmcnt(8)
	s_waitcnt lgkmcnt(0)
	s_setprio 1
	s_barrier
	v_mfma_f32_16x16x32_bf16 v[126:129], v[130:133], v[190:193], v[126:129]
	v_mfma_f32_16x16x32_bf16 v[118:121], v[166:169], v[190:193], v[118:121]
	v_mfma_f32_16x16x32_bf16 v[110:113], v[130:133], v[198:201], v[110:113]
	v_mfma_f32_16x16x32_bf16 v[102:105], v[166:169], v[198:201], v[102:105]
	v_mfma_f32_16x16x32_bf16 v[94:97], v[130:133], v[206:209], v[94:97]
	v_mfma_f32_16x16x32_bf16 v[86:89], v[166:169], v[206:209], v[86:89]
	v_mfma_f32_16x16x32_bf16 v[78:81], v[130:133], v[214:217], v[78:81]
	v_mfma_f32_16x16x32_bf16 v[70:73], v[166:169], v[214:217], v[70:73]
	v_mfma_f32_16x16x32_bf16 v[126:129], v[134:137], v[194:197], v[126:129]
	v_mfma_f32_16x16x32_bf16 v[118:121], v[170:173], v[194:197], v[118:121]
	v_mfma_f32_16x16x32_bf16 v[110:113], v[134:137], v[202:205], v[110:113]
	v_mfma_f32_16x16x32_bf16 v[102:105], v[170:173], v[202:205], v[102:105]
	v_mfma_f32_16x16x32_bf16 v[94:97], v[134:137], v[210:213], v[94:97]
	v_mfma_f32_16x16x32_bf16 v[86:89], v[170:173], v[210:213], v[86:89]
	v_mfma_f32_16x16x32_bf16 v[78:81], v[134:137], v[218:221], v[78:81]
	v_mfma_f32_16x16x32_bf16 v[70:73], v[170:173], v[218:221], v[70:73]
	v_mfma_f32_16x16x32_bf16 v[122:125], v[174:177], v[190:193], v[122:125]
	v_mfma_f32_16x16x32_bf16 v[114:117], v[182:185], v[190:193], v[114:117]
	v_mfma_f32_16x16x32_bf16 v[106:109], v[174:177], v[198:201], v[106:109]
	v_mfma_f32_16x16x32_bf16 v[98:101], v[182:185], v[198:201], v[98:101]
	v_mfma_f32_16x16x32_bf16 v[90:93], v[174:177], v[206:209], v[90:93]
	v_mfma_f32_16x16x32_bf16 v[82:85], v[182:185], v[206:209], v[82:85]
	v_mfma_f32_16x16x32_bf16 v[74:77], v[174:177], v[214:217], v[74:77]
	v_mfma_f32_16x16x32_bf16 v[66:69], v[182:185], v[214:217], v[66:69]
	v_mfma_f32_16x16x32_bf16 v[122:125], v[178:181], v[194:197], v[122:125]
	v_mfma_f32_16x16x32_bf16 v[114:117], v[186:189], v[194:197], v[114:117]
	v_mfma_f32_16x16x32_bf16 v[106:109], v[178:181], v[202:205], v[106:109]
	v_mfma_f32_16x16x32_bf16 v[98:101], v[186:189], v[202:205], v[98:101]
	v_mfma_f32_16x16x32_bf16 v[90:93], v[178:181], v[210:213], v[90:93]
	v_mfma_f32_16x16x32_bf16 v[82:85], v[186:189], v[210:213], v[82:85]
	v_mfma_f32_16x16x32_bf16 v[74:77], v[178:181], v[218:221], v[74:77]
	v_mfma_f32_16x16x32_bf16 v[66:69], v[186:189], v[218:221], v[66:69]
	s_barrier
; #define PG8_STAGE(bufoff, gbase, voff) do { _Pragma("unroll") for (int _i = 0; _i < 2; ++_i) \
;         __builtin_amdgcn_global_load_lds((const unsigned*)((const char*)(gbase) + (voff)[_i]), (PG8_LAS unsigned*)(lds + (bufoff) + ldsw + _i * 8192), 16, 0, 0); } while (0)
; #define PG8_LDA(dst, b, h) do { _Pragma("unroll") for (int m = 0; m < 4; ++m) _Pragma("unroll") for (int k = 0; k < 2; ++k) dst[m][k] = *(const PG8_LAS bf16x8*)(lds + PG8_SA(b, h) + aoff + m * 2048 + k * 1024); } while (0)
; #define PG8_LDB(dst, b, h) do { _Pragma("unroll") for (int n = 0; n < 2; ++n) _Pragma("unroll") for (int k = 0; k < 2; ++k) dst[n][k] = *(const PG8_LAS bf16x8*)(lds + PG8_SB(b, h) + boff + n * 2048 + k * 1024); } while (0)
; #define PG8_MMA(ai, bj, At, Bt) do { __builtin_amdgcn_s_setprio(1); _Pragma("unroll") for (int m = 0; m < 4; ++m) _Pragma("unroll") for (int n = 0; n < 2; ++n) _Pragma("unroll") for (int k = 0; k < 2; ++k) \
;         acc[ai][bj][m][n] = __builtin_amdgcn_mfma_f32_16x16x32_bf16(Bt[n][k], At[m][k], acc[ai][bj][m][n], 0, 0, 0); __builtin_amdgcn_s_setprio(0); } while (0)
; #define PG8_WAIT_V(n) asm volatile("s_waitcnt vmcnt(" #n ")" ::: "memory")
; template <class Epi, class Sched, bool ALIGN_EPI = false, bool SP2 = false>
; __device__ __forceinline__ void gemm_phase(PG8_LAS unsigned char* lds, const Gemm g, const Sched& S, const Epi& E) {
;     ...
;             PG8_LDB(B0, 0, 0); PG8_LDB(B1, 0, 1); PG8_SCHED; PG8_LDA(At, 0, 0); PG8_STAGE(PG8_SA(1, 1), a1 + hstepA, voffA);
;             PG8_WAIT_V(8); PG8_WAIT_L(0); PG8_BAR; PG8_MMA(0, 0, At, B0); PG8_MMA(0, 1, At, B1); PG8_BAR; PG8_SCHED;
;             PG8_LDA(At, 0, 1); PG8_STAGE(PG8_SB(0, 0), b2, voffB); PG8_STAGE(PG8_SB(0, 1), b2 + hstepB, voffB); PG8_STAGE(PG8_SA(0, 0), a2, voffA);
;             PG8_WAIT_V(8); PG8_WAIT_L(0); PG8_BAR; PG8_MMA(1, 0, At, B0); PG8_MMA(1, 1, At, B1); PG8_BAR; PG8_SCHED;
;             PG8_LDB(B0, 1, 0); PG8_LDB(B1, 1, 1); PG8_SCHED; PG8_LDA(At, 1, 0); PG8_STAGE(PG8_SA(0, 1), a2 + hstepA, voffA);
;             PG8_WAIT_V(8); PG8_WAIT_L(0); PG8_BAR; PG8_MMA(0, 0, At, B0); PG8_MMA(0, 1, At, B1); PG8_BAR; PG8_SCHED;
;             PG8_LDA(At, 1, 1); PG8_STAGE(PG8_SB(1, 0), b3, voffB); PG8_STAGE(PG8_SB(1, 1), b3 + hstepB, voffB); PG8_STAGE(PG8_SA(1, 0), a3, voffA);
;             PG8_WAIT_V(8); PG8_WAIT_L(0); PG8_BAR; PG8_MMA(1, 0, At, B0); PG8_MMA(1, 1, At, B1); PG8_BAR; PG8_SCHED;
	s_setprio 0
	s_add_i32 s4, s4, s37
	v_lshl_add_u64 v[222:223], v[222:223], 0, s[72:73]
	s_mov_b32 m0, s4
	ds_read_b128 v[190:193], v155 offset:49152
	ds_read_b128 v[194:197], v155 offset:50176
	ds_read_b128 v[198:201], v155 offset:51200
	ds_read_b128 v[202:205], v155 offset:52224
	ds_read_b128 v[206:209], v155 offset:53248
	ds_read_b128 v[210:213], v155 offset:54272
	ds_read_b128 v[214:217], v155 offset:55296
	ds_read_b128 v[218:221], v155 offset:56320
	global_load_lds_dwordx4 v[222:223], off
	s_add_i32 m0, s4, 0x2000
	s_add_u32 s10, s10, 0x40080
	v_lshl_add_u64 v[222:223], v[224:225], 0, s[72:73]
	s_addc_u32 s11, s11, 0
	s_add_i32 s4, s68, s37
	global_load_lds_dwordx4 v[222:223], off
	v_lshl_add_u64 v[222:223], s[10:11], 0, v[140:141]
	s_mov_b32 m0, s4
	s_nop 0
	global_load_lds_dwordx4 v[222:223], off
	v_lshl_add_u64 v[222:223], s[10:11], 0, v[144:145]
	s_add_i32 m0, s4, 0x2000
	s_nop 0
	global_load_lds_dwordx4 v[222:223], off
	v_lshl_add_u64 v[222:223], v[226:227], 0, s[72:73]
	s_mov_b32 m0, s44
	s_nop 0
	global_load_lds_dwordx4 v[222:223], off
	v_lshl_add_u64 v[222:223], v[228:229], 0, s[72:73]
	s_mov_b32 m0, s45
	s_nop 0
	global_load_lds_dwordx4 v[222:223], off
	s_waitcnt vmcnt(8)
	s_waitcnt lgkmcnt(0)
	s_setprio 1
	s_barrier
	v_mfma_f32_16x16x32_bf16 v[62:65], v[130:133], v[190:193], v[62:65]
	v_mfma_f32_16x16x32_bf16 v[54:57], v[166:169], v[190:193], v[54:57]
	v_mfma_f32_16x16x32_bf16 v[46:49], v[130:133], v[198:201], v[46:49]
	v_mfma_f32_16x16x32_bf16 v[38:41], v[166:169], v[198:201], v[38:41]
	v_mfma_f32_16x16x32_bf16 v[30:33], v[130:133], v[206:209], v[30:33]
	v_mfma_f32_16x16x32_bf16 v[22:25], v[166:169], v[206:209], v[22:25]
	v_mfma_f32_16x16x32_bf16 v[14:17], v[130:133], v[214:217], v[14:17]
	v_mfma_f32_16x16x32_bf16 v[6:9], v[166:169], v[214:217], v[6:9]
	v_mfma_f32_16x16x32_bf16 v[62:65], v[134:137], v[194:197], v[62:65]
	v_mfma_f32_16x16x32_bf16 v[54:57], v[170:173], v[194:197], v[54:57]
	v_mfma_f32_16x16x32_bf16 v[46:49], v[134:137], v[202:205], v[46:49]
	v_mfma_f32_16x16x32_bf16 v[38:41], v[170:173], v[202:205], v[38:41]
	v_mfma_f32_16x16x32_bf16 v[30:33], v[134:137], v[210:213], v[30:33]
	v_mfma_f32_16x16x32_bf16 v[22:25], v[170:173], v[210:213], v[22:25]
	v_mfma_f32_16x16x32_bf16 v[14:17], v[134:137], v[218:221], v[14:17]
	v_mfma_f32_16x16x32_bf16 v[6:9], v[170:173], v[218:221], v[6:9]
	v_mfma_f32_16x16x32_bf16 v[58:61], v[174:177], v[190:193], v[58:61]
	v_mfma_f32_16x16x32_bf16 v[50:53], v[182:185], v[190:193], v[50:53]
	v_mfma_f32_16x16x32_bf16 v[42:45], v[174:177], v[198:201], v[42:45]
	v_mfma_f32_16x16x32_bf16 v[34:37], v[182:185], v[198:201], v[34:37]
	v_mfma_f32_16x16x32_bf16 v[26:29], v[174:177], v[206:209], v[26:29]
	v_mfma_f32_16x16x32_bf16 v[18:21], v[182:185], v[206:209], v[18:21]
	v_mfma_f32_16x16x32_bf16 v[10:13], v[174:177], v[214:217], v[10:13]
	v_mfma_f32_16x16x32_bf16 v[2:5], v[182:185], v[214:217], v[2:5]
	v_mfma_f32_16x16x32_bf16 v[58:61], v[178:181], v[194:197], v[58:61]
	v_mfma_f32_16x16x32_bf16 v[50:53], v[186:189], v[194:197], v[50:53]
	v_mfma_f32_16x16x32_bf16 v[42:45], v[178:181], v[202:205], v[42:45]
	v_mfma_f32_16x16x32_bf16 v[34:37], v[186:189], v[202:205], v[34:37]
	v_mfma_f32_16x16x32_bf16 v[26:29], v[178:181], v[210:213], v[26:29]
	v_mfma_f32_16x16x32_bf16 v[18:21], v[186:189], v[210:213], v[18:21]
	v_mfma_f32_16x16x32_bf16 v[10:13], v[178:181], v[218:221], v[10:13]
	v_mfma_f32_16x16x32_bf16 v[2:5], v[186:189], v[218:221], v[2:5]
	s_barrier
	s_setprio 0
	s_add_i32 s67, s67, 2
	s_add_u32 s8, s8, 0x100
	s_addc_u32 s9, s9, 0
	s_add_u32 s46, s46, 0x100
	s_addc_u32 s66, s66, 0
	s_cmp_gt_u32 s67, 13
	s_cbranch_scc0 .LBB0_691
	s_and_b64 vcc, exec, s[74:75]
	s_cbranch_vccz .LBB0_694
	s_barrier

; #define PG8_STAGE(bufoff, gbase, voff) do { _Pragma("unroll") for (int _i = 0; _i < 2; ++_i) \
;         __builtin_amdgcn_global_load_lds((const unsigned*)((const char*)(gbase) + (voff)[_i]), (PG8_LAS unsigned*)(lds + (bufoff) + ldsw + _i * 8192), 16, 0, 0); } while (0)
; #define PG8_LDA(dst, b, h) do { _Pragma("unroll") for (int m = 0; m < 4; ++m) _Pragma("unroll") for (int k = 0; k < 2; ++k) dst[m][k] = *(const PG8_LAS bf16x8*)(lds + PG8_SA(b, h) + aoff + m * 2048 + k * 1024); } while (0)
; #define PG8_LDB(dst, b, h) do { _Pragma("unroll") for (int n = 0; n < 2; ++n) _Pragma("unroll") for (int k = 0; k < 2; ++k) dst[n][k] = *(const PG8_LAS bf16x8*)(lds + PG8_SB(b, h) + boff + n * 2048 + k * 1024); } while (0)
; #define PG8_MMA(ai, bj, At, Bt) do { __builtin_amdgcn_s_setprio(1); _Pragma("unroll") for (int m = 0; m < 4; ++m) _Pragma("unroll") for (int n = 0; n < 2; ++n) _Pragma("unroll") for (int k = 0; k < 2; ++k) \
;         acc[ai][bj][m][n] = __builtin_amdgcn_mfma_f32_16x16x32_bf16(Bt[n][k], At[m][k], acc[ai][bj][m][n], 0, 0, 0); __builtin_amdgcn_s_setprio(0); } while (0)
; #define PG8_WAIT_V(n) asm volatile("s_waitcnt vmcnt(" #n ")" ::: "memory")
; template <class Epi, class Sched, bool ALIGN_EPI = false, bool SP2 = false>
; __device__ __forceinline__ void gemm_phase(PG8_LAS unsigned char* lds, const Gemm g, const Sched& S, const Epi& E) {
;     ...
;             PG8_LDB(B0, 0, 0); PG8_LDB(B1, 0, 1); PG8_SCHED; PG8_LDA(At, 0, 0); PG8_STAGE(PG8_SA(1, 1), a1 + hstepA, voffA);
;             PG8_WAIT_V(8); PG8_WAIT_L(0); PG8_BAR; PG8_MMA(0, 0, At, B0); PG8_MMA(0, 1, At, B1); PG8_BAR; PG8_SCHED;
;             PG8_LDA(At, 0, 1); PG8_STAGE(PG8_SB(0, 0), b2, voffB); PG8_STAGE(PG8_SB(0, 1), b2 + hstepB, voffB); PG8_STAGE(PG8_SA(0, 0), a2, voffA);
;             PG8_WAIT_V(8); PG8_WAIT_L(0); PG8_BAR; PG8_MMA(1, 0, At, B0); PG8_MMA(1, 1, At, B1); PG8_BAR; PG8_SCHED;
;             PG8_LDB(B0, 1, 0); PG8_LDB(B1, 1, 1); PG8_SCHED; PG8_LDA(At, 1, 0); PG8_STAGE(PG8_SA(0, 1), a2 + hstepA, voffA);
;             PG8_WAIT_V(8); PG8_WAIT_L(0); PG8_BAR; PG8_MMA(0, 0, At, B0); PG8_MMA(0, 1, At, B1); PG8_BAR; PG8_SCHED;
;             PG8_LDA(At, 1, 1); PG8_STAGE(PG8_SB(1, 0), b3, voffB); PG8_STAGE(PG8_SB(1, 1), b3 + hstepB, voffB); PG8_STAGE(PG8_SA(1, 0), a3, voffA);
;             PG8_WAIT_V(8); PG8_WAIT_L(0); PG8_BAR; PG8_MMA(1, 0, At, B0); PG8_MMA(1, 1, At, B1); PG8_BAR; PG8_SCHED;
.LBB0_963:
	v_add_u32_e32 v3, s51, v235
	ds_read_b128 v[78:81], v3
	ds_read_b128 v[82:85], v3 offset:1024
	ds_read_b128 v[102:105], v3 offset:2048
	ds_read_b128 v[106:109], v3 offset:3072
	v_add_u32_e32 v3, s62, v235
	ds_read_b128 v[134:137], v3
	ds_read_b128 v[138:141], v3 offset:1024
	ds_read_b128 v[142:145], v3 offset:2048
	ds_read_b128 v[154:157], v3 offset:3072
	s_add_u32 s66, s64, 0xfff80080
	s_addc_u32 s67, s65, -1
	s_cmp_eq_u32 s72, 4
	s_cselect_b32 s69, s37, s67
	s_cselect_b32 s68, s39, s66
	s_cselect_b32 s67, s31, s71
	s_cselect_b32 s66, s49, s70
	v_lshl_add_u64 v[4:5], s[64:65], 0, v[210:211]
	s_add_i32 m0, s33, 0xc000
	ds_read_b128 v[158:161], v237
	ds_read_b128 v[162:165], v237 offset:1024
	ds_read_b128 v[166:169], v237 offset:2048
	ds_read_b128 v[178:181], v237 offset:3072
	ds_read_b128 v[182:185], v237 offset:4096
	ds_read_b128 v[186:189], v237 offset:5120
	ds_read_b128 v[190:193], v237 offset:6144
	ds_read_b128 v[194:197], v237 offset:7168
	global_load_lds_dwordx4 v[4:5], off
	v_lshl_add_u64 v[4:5], s[64:65], 0, v[212:213]
	s_add_i32 m0, s33, 0xe000
	s_nop 0
	global_load_lds_dwordx4 v[4:5], off
	s_waitcnt vmcnt(8)
	s_waitcnt lgkmcnt(0)
	s_setprio 1
	s_barrier
	v_mfma_f32_16x16x32_bf16 v[90:93], v[78:81], v[158:161], v[90:93]
	v_mfma_f32_16x16x32_bf16 v[86:89], v[102:105], v[158:161], v[86:89]
	v_mfma_f32_16x16x32_bf16 v[122:125], v[78:81], v[166:169], v[122:125]
	v_mfma_f32_16x16x32_bf16 v[118:121], v[102:105], v[166:169], v[118:121]
	v_mfma_f32_16x16x32_bf16 v[130:133], v[78:81], v[182:185], v[130:133]
	v_mfma_f32_16x16x32_bf16 v[126:129], v[102:105], v[182:185], v[126:129]
	v_mfma_f32_16x16x32_bf16 v[98:101], v[78:81], v[190:193], v[98:101]
	v_mfma_f32_16x16x32_bf16 v[94:97], v[102:105], v[190:193], v[94:97]
	v_mfma_f32_16x16x32_bf16 v[90:93], v[82:85], v[162:165], v[90:93]
	v_mfma_f32_16x16x32_bf16 v[86:89], v[106:109], v[162:165], v[86:89]
	v_mfma_f32_16x16x32_bf16 v[122:125], v[82:85], v[178:181], v[122:125]
	v_mfma_f32_16x16x32_bf16 v[118:121], v[106:109], v[178:181], v[118:121]
	v_mfma_f32_16x16x32_bf16 v[130:133], v[82:85], v[186:189], v[130:133]
	v_mfma_f32_16x16x32_bf16 v[126:129], v[106:109], v[186:189], v[126:129]
	v_mfma_f32_16x16x32_bf16 v[98:101], v[82:85], v[194:197], v[98:101]
	v_mfma_f32_16x16x32_bf16 v[94:97], v[106:109], v[194:197], v[94:97]
	v_mfma_f32_16x16x32_bf16 v[174:177], v[134:137], v[158:161], v[174:177]
	v_mfma_f32_16x16x32_bf16 v[150:153], v[134:137], v[166:169], v[150:153]
	v_mfma_f32_16x16x32_bf16 v[146:149], v[142:145], v[166:169], v[146:149]
	v_mfma_f32_16x16x32_bf16 v[114:117], v[134:137], v[182:185], v[114:117]
	v_mfma_f32_16x16x32_bf16 v[110:113], v[142:145], v[182:185], v[110:113]
	v_mfma_f32_16x16x32_bf16 v[74:77], v[134:137], v[190:193], v[74:77]
	v_mfma_f32_16x16x32_bf16 v[70:73], v[142:145], v[190:193], v[70:73]
	v_mfma_f32_16x16x32_bf16 v[174:177], v[138:141], v[162:165], v[174:177]
	v_mfma_f32_16x16x32_bf16 v[158:161], v[142:145], v[158:161], v[170:173]
	v_mfma_f32_16x16x32_bf16 v[150:153], v[138:141], v[178:181], v[150:153]
	v_mfma_f32_16x16x32_bf16 v[146:149], v[154:157], v[178:181], v[146:149]
	v_mfma_f32_16x16x32_bf16 v[114:117], v[138:141], v[186:189], v[114:117]
	v_mfma_f32_16x16x32_bf16 v[110:113], v[154:157], v[186:189], v[110:113]
	v_mfma_f32_16x16x32_bf16 v[74:77], v[138:141], v[194:197], v[74:77]
	v_mfma_f32_16x16x32_bf16 v[70:73], v[154:157], v[194:197], v[70:73]
	v_mfma_f32_16x16x32_bf16 v[158:161], v[154:157], v[162:165], v[158:161]
	s_barrier
	s_setprio 0
	s_add_i32 s73, s51, s5
	v_lshl_add_u64 v[218:219], s[66:67], 0, v[204:205]
	s_mov_b32 m0, s73
	ds_read_b128 v[162:165], v237 offset:16384
	ds_read_b128 v[166:169], v237 offset:17408
	ds_read_b128 v[170:173], v237 offset:18432
	ds_read_b128 v[178:181], v237 offset:19456
	ds_read_b128 v[182:185], v237 offset:20480
	ds_read_b128 v[186:189], v237 offset:21504
	ds_read_b128 v[190:193], v237 offset:22528
	ds_read_b128 v[194:197], v237 offset:23552
	global_load_lds_dwordx4 v[218:219], off
	s_add_i32 m0, s73, 0x2000
	s_add_u32 s74, s66, 0x40000
	v_lshl_add_u64 v[220:221], s[66:67], 0, v[208:209]
	s_addc_u32 s75, s67, 0
	s_add_i32 s73, s62, s5
	global_load_lds_dwordx4 v[220:221], off
	v_lshl_add_u64 v[4:5], s[74:75], 0, v[204:205]
	s_mov_b32 m0, s73
	v_lshl_add_u64 v[222:223], s[68:69], 0, v[202:203]
	global_load_lds_dwordx4 v[4:5], off
	v_lshl_add_u64 v[4:5], s[74:75], 0, v[208:209]
	s_add_i32 m0, s73, 0x2000
	v_lshl_add_u64 v[224:225], s[68:69], 0, v[206:207]
	global_load_lds_dwordx4 v[4:5], off
	s_mov_b32 m0, s33
	s_nop 0
	global_load_lds_dwordx4 v[222:223], off
	s_mov_b32 m0, s35
	s_nop 0
	global_load_lds_dwordx4 v[224:225], off
	s_waitcnt vmcnt(8)
	s_waitcnt lgkmcnt(0)
	s_setprio 1
	s_barrier
; #define PG8_STAGE(bufoff, gbase, voff) do { _Pragma("unroll") for (int _i = 0; _i < 2; ++_i) \
;         __builtin_amdgcn_global_load_lds((const unsigned*)((const char*)(gbase) + (voff)[_i]), (PG8_LAS unsigned*)(lds + (bufoff) + ldsw + _i * 8192), 16, 0, 0); } while (0)
; #define PG8_LDA(dst, b, h) do { _Pragma("unroll") for (int m = 0; m < 4; ++m) _Pragma("unroll") for (int k = 0; k < 2; ++k) dst[m][k] = *(const PG8_LAS bf16x8*)(lds + PG8_SA(b, h) + aoff + m * 2048 + k * 1024); } while (0)
; #define PG8_LDB(dst, b, h) do { _Pragma("unroll") for (int n = 0; n < 2; ++n) _Pragma("unroll") for (int k = 0; k < 2; ++k) dst[n][k] = *(const PG8_LAS bf16x8*)(lds + PG8_SB(b, h) + boff + n * 2048 + k * 1024); } while (0)
; #define PG8_MMA(ai, bj, At, Bt) do { __builtin_amdgcn_s_setprio(1); _Pragma("unroll") for (int m = 0; m < 4; ++m) _Pragma("unroll") for (int n = 0; n < 2; ++n) _Pragma("unroll") for (int k = 0; k < 2; ++k) \
;         acc[ai][bj][m][n] = __builtin_amdgcn_mfma_f32_16x16x32_bf16(Bt[n][k], At[m][k], acc[ai][bj][m][n], 0, 0, 0); __builtin_amdgcn_s_setprio(0); } while (0)
; #define PG8_WAIT_V(n) asm volatile("s_waitcnt vmcnt(" #n ")" ::: "memory")
; template <class Epi, class Sched, bool ALIGN_EPI = false, bool SP2 = false>
; __device__ __forceinline__ void gemm_phase(PG8_LAS unsigned char* lds, const Gemm g, const Sched& S, const Epi& E) {
;     ...
;             PG8_LDB(B0, 0, 0); PG8_LDB(B1, 0, 1); PG8_SCHED; PG8_LDA(At, 0, 0); PG8_STAGE(PG8_SA(1, 1), a1 + hstepA, voffA);
;             PG8_WAIT_V(8); PG8_WAIT_L(0); PG8_BAR; PG8_MMA(0, 0, At, B0); PG8_MMA(0, 1, At, B1); PG8_BAR; PG8_SCHED;
;             PG8_LDA(At, 0, 1); PG8_STAGE(PG8_SB(0, 0), b2, voffB); PG8_STAGE(PG8_SB(0, 1), b2 + hstepB, voffB); PG8_STAGE(PG8_SA(0, 0), a2, voffA);
;             PG8_WAIT_V(8); PG8_WAIT_L(0); PG8_BAR; PG8_MMA(1, 0, At, B0); PG8_MMA(1, 1, At, B1); PG8_BAR; PG8_SCHED;
;             PG8_LDB(B0, 1, 0); PG8_LDB(B1, 1, 1); PG8_SCHED; PG8_LDA(At, 1, 0); PG8_STAGE(PG8_SA(0, 1), a2 + hstepA, voffA);
;             PG8_WAIT_V(8); PG8_WAIT_L(0); PG8_BAR; PG8_MMA(0, 0, At, B0); PG8_MMA(0, 1, At, B1); PG8_BAR; PG8_SCHED;
;             PG8_LDA(At, 1, 1); PG8_STAGE(PG8_SB(1, 0), b3, voffB); PG8_STAGE(PG8_SB(1, 1), b3 + hstepB, voffB); PG8_STAGE(PG8_SA(1, 0), a3, voffA);
;             PG8_WAIT_V(8); PG8_WAIT_L(0); PG8_BAR; PG8_MMA(1, 0, At, B0); PG8_MMA(1, 1, At, B1); PG8_BAR; PG8_SCHED;
	v_mfma_f32_16x16x32_bf16 v[66:69], v[78:81], v[162:165], v[66:69]
	v_mfma_f32_16x16x32_bf16 v[62:65], v[102:105], v[162:165], v[62:65]
	v_mfma_f32_16x16x32_bf16 v[50:53], v[78:81], v[170:173], v[50:53]
	v_mfma_f32_16x16x32_bf16 v[46:49], v[102:105], v[170:173], v[46:49]
	v_mfma_f32_16x16x32_bf16 v[34:37], v[78:81], v[182:185], v[34:37]
	v_mfma_f32_16x16x32_bf16 v[30:33], v[102:105], v[182:185], v[30:33]
	v_mfma_f32_16x16x32_bf16 v[18:21], v[78:81], v[190:193], v[18:21]
	v_mfma_f32_16x16x32_bf16 v[14:17], v[102:105], v[190:193], v[14:17]
	v_mfma_f32_16x16x32_bf16 v[66:69], v[82:85], v[166:169], v[66:69]
	v_mfma_f32_16x16x32_bf16 v[62:65], v[106:109], v[166:169], v[62:65]
	v_mfma_f32_16x16x32_bf16 v[50:53], v[82:85], v[178:181], v[50:53]
	v_mfma_f32_16x16x32_bf16 v[46:49], v[106:109], v[178:181], v[46:49]
	v_mfma_f32_16x16x32_bf16 v[34:37], v[82:85], v[186:189], v[34:37]
	v_mfma_f32_16x16x32_bf16 v[30:33], v[106:109], v[186:189], v[30:33]
	v_mfma_f32_16x16x32_bf16 v[18:21], v[82:85], v[194:197], v[18:21]
	v_mfma_f32_16x16x32_bf16 v[14:17], v[106:109], v[194:197], v[14:17]
	v_mfma_f32_16x16x32_bf16 v[58:61], v[134:137], v[162:165], v[58:61]
	v_mfma_f32_16x16x32_bf16 v[54:57], v[142:145], v[162:165], v[54:57]
	v_mfma_f32_16x16x32_bf16 v[42:45], v[134:137], v[170:173], v[42:45]
	v_mfma_f32_16x16x32_bf16 v[38:41], v[142:145], v[170:173], v[38:41]
	v_mfma_f32_16x16x32_bf16 v[26:29], v[134:137], v[182:185], v[26:29]
	v_mfma_f32_16x16x32_bf16 v[22:25], v[142:145], v[182:185], v[22:25]
	v_mfma_f32_16x16x32_bf16 v[10:13], v[134:137], v[190:193], v[10:13]
	v_mfma_f32_16x16x32_bf16 v[4:7], v[142:145], v[190:193], v[6:9]
	v_mfma_f32_16x16x32_bf16 v[58:61], v[138:141], v[166:169], v[58:61]
	v_mfma_f32_16x16x32_bf16 v[54:57], v[154:157], v[166:169], v[54:57]
	v_mfma_f32_16x16x32_bf16 v[42:45], v[138:141], v[178:181], v[42:45]
	v_mfma_f32_16x16x32_bf16 v[38:41], v[154:157], v[178:181], v[38:41]
	v_mfma_f32_16x16x32_bf16 v[26:29], v[138:141], v[186:189], v[26:29]
	v_mfma_f32_16x16x32_bf16 v[22:25], v[154:157], v[186:189], v[22:25]
	v_mfma_f32_16x16x32_bf16 v[10:13], v[138:141], v[194:197], v[10:13]
	v_mfma_f32_16x16x32_bf16 v[4:7], v[154:157], v[194:197], v[4:7]
	s_barrier
	s_setprio 0
	s_add_i32 s73, 0, 0x18000
	v_add_u32_e32 v3, s73, v235
	s_add_i32 s74, 0, 0x1c000
	ds_read_b128 v[78:81], v3
	ds_read_b128 v[82:85], v3 offset:1024
	ds_read_b128 v[102:105], v3 offset:2048
	ds_read_b128 v[106:109], v3 offset:3072
	v_add_u32_e32 v3, s74, v235
	ds_read_b128 v[134:137], v3
	ds_read_b128 v[138:141], v3 offset:1024
	ds_read_b128 v[142:145], v3 offset:2048
	ds_read_b128 v[154:157], v3 offset:3072
	s_add_u32 s68, s68, 0x80000
	s_addc_u32 s69, s69, 0
	s_mov_b32 m0, s42
	v_lshl_add_u64 v[8:9], s[68:69], 0, v[202:203]
	ds_read_b128 v[162:165], v237 offset:32768
	ds_read_b128 v[166:169], v237 offset:33792
	ds_read_b128 v[178:181], v237 offset:34816
	ds_read_b128 v[182:185], v237 offset:35840
	ds_read_b128 v[186:189], v237 offset:36864
	ds_read_b128 v[190:193], v237 offset:37888
	ds_read_b128 v[194:197], v237 offset:38912
	ds_read_b128 v[198:201], v237 offset:39936
	global_load_lds_dwordx4 v[8:9], off
	v_lshl_add_u64 v[8:9], s[68:69], 0, v[206:207]
	s_mov_b32 m0, s43
	s_nop 0
	global_load_lds_dwordx4 v[8:9], off
	s_waitcnt vmcnt(8)
	s_waitcnt lgkmcnt(0)
	s_setprio 1
	s_barrier
	v_mfma_f32_16x16x32_bf16 v[90:93], v[78:81], v[162:165], v[90:93]
	v_mfma_f32_16x16x32_bf16 v[86:89], v[102:105], v[162:165], v[86:89]
	v_mfma_f32_16x16x32_bf16 v[122:125], v[78:81], v[178:181], v[122:125]
	v_mfma_f32_16x16x32_bf16 v[118:121], v[102:105], v[178:181], v[118:121]
	v_mfma_f32_16x16x32_bf16 v[130:133], v[78:81], v[186:189], v[130:133]
	v_mfma_f32_16x16x32_bf16 v[126:129], v[102:105], v[186:189], v[126:129]
	v_mfma_f32_16x16x32_bf16 v[98:101], v[78:81], v[194:197], v[98:101]
	v_mfma_f32_16x16x32_bf16 v[94:97], v[102:105], v[194:197], v[94:97]
	v_mfma_f32_16x16x32_bf16 v[90:93], v[82:85], v[166:169], v[90:93]
	v_mfma_f32_16x16x32_bf16 v[86:89], v[106:109], v[166:169], v[86:89]
	v_mfma_f32_16x16x32_bf16 v[122:125], v[82:85], v[182:185], v[122:125]
	v_mfma_f32_16x16x32_bf16 v[118:121], v[106:109], v[182:185], v[118:121]
	v_mfma_f32_16x16x32_bf16 v[130:133], v[82:85], v[190:193], v[130:133]
	v_mfma_f32_16x16x32_bf16 v[126:129], v[106:109], v[190:193], v[126:129]
	v_mfma_f32_16x16x32_bf16 v[98:101], v[82:85], v[198:201], v[98:101]
	v_mfma_f32_16x16x32_bf16 v[94:97], v[106:109], v[198:201], v[94:97]
	v_mfma_f32_16x16x32_bf16 v[170:173], v[134:137], v[162:165], v[174:177]
	v_mfma_f32_16x16x32_bf16 v[158:161], v[142:145], v[162:165], v[158:161]
	v_mfma_f32_16x16x32_bf16 v[150:153], v[134:137], v[178:181], v[150:153]
	v_mfma_f32_16x16x32_bf16 v[146:149], v[142:145], v[178:181], v[146:149]
	v_mfma_f32_16x16x32_bf16 v[114:117], v[134:137], v[186:189], v[114:117]
	v_mfma_f32_16x16x32_bf16 v[110:113], v[142:145], v[186:189], v[110:113]
	v_mfma_f32_16x16x32_bf16 v[74:77], v[134:137], v[194:197], v[74:77]
	v_mfma_f32_16x16x32_bf16 v[70:73], v[142:145], v[194:197], v[70:73]
	v_mfma_f32_16x16x32_bf16 v[174:177], v[138:141], v[166:169], v[170:173]
	v_mfma_f32_16x16x32_bf16 v[170:173], v[154:157], v[166:169], v[158:161]
	v_mfma_f32_16x16x32_bf16 v[150:153], v[138:141], v[182:185], v[150:153]
	v_mfma_f32_16x16x32_bf16 v[146:149], v[154:157], v[182:185], v[146:149]
	v_mfma_f32_16x16x32_bf16 v[114:117], v[138:141], v[190:193], v[114:117]
	v_mfma_f32_16x16x32_bf16 v[110:113], v[154:157], v[190:193], v[110:113]
	v_mfma_f32_16x16x32_bf16 v[74:77], v[138:141], v[198:201], v[74:77]
	v_mfma_f32_16x16x32_bf16 v[70:73], v[154:157], v[198:201], v[70:73]
	s_barrier
; #define PG8_STAGE(bufoff, gbase, voff) do { _Pragma("unroll") for (int _i = 0; _i < 2; ++_i) \
;         __builtin_amdgcn_global_load_lds((const unsigned*)((const char*)(gbase) + (voff)[_i]), (PG8_LAS unsigned*)(lds + (bufoff) + ldsw + _i * 8192), 16, 0, 0); } while (0)
; #define PG8_LDA(dst, b, h) do { _Pragma("unroll") for (int m = 0; m < 4; ++m) _Pragma("unroll") for (int k = 0; k < 2; ++k) dst[m][k] = *(const PG8_LAS bf16x8*)(lds + PG8_SA(b, h) + aoff + m * 2048 + k * 1024); } while (0)
; #define PG8_LDB(dst, b, h) do { _Pragma("unroll") for (int n = 0; n < 2; ++n) _Pragma("unroll") for (int k = 0; k < 2; ++k) dst[n][k] = *(const PG8_LAS bf16x8*)(lds + PG8_SB(b, h) + boff + n * 2048 + k * 1024); } while (0)
; #define PG8_MMA(ai, bj, At, Bt) do { __builtin_amdgcn_s_setprio(1); _Pragma("unroll") for (int m = 0; m < 4; ++m) _Pragma("unroll") for (int n = 0; n < 2; ++n) _Pragma("unroll") for (int k = 0; k < 2; ++k) \
;         acc[ai][bj][m][n] = __builtin_amdgcn_mfma_f32_16x16x32_bf16(Bt[n][k], At[m][k], acc[ai][bj][m][n], 0, 0, 0); __builtin_amdgcn_s_setprio(0); } while (0)
; #define PG8_WAIT_V(n) asm volatile("s_waitcnt vmcnt(" #n ")" ::: "memory")
; template <class Epi, class Sched, bool ALIGN_EPI = false, bool SP2 = false>
; __device__ __forceinline__ void gemm_phase(PG8_LAS unsigned char* lds, const Gemm g, const Sched& S, const Epi& E) {
;     ...
;             PG8_LDB(B0, 0, 0); PG8_LDB(B1, 0, 1); PG8_SCHED; PG8_LDA(At, 0, 0); PG8_STAGE(PG8_SA(1, 1), a1 + hstepA, voffA);
;             PG8_WAIT_V(8); PG8_WAIT_L(0); PG8_BAR; PG8_MMA(0, 0, At, B0); PG8_MMA(0, 1, At, B1); PG8_BAR; PG8_SCHED;
;             PG8_LDA(At, 0, 1); PG8_STAGE(PG8_SB(0, 0), b2, voffB); PG8_STAGE(PG8_SB(0, 1), b2 + hstepB, voffB); PG8_STAGE(PG8_SA(0, 0), a2, voffA);
;             PG8_WAIT_V(8); PG8_WAIT_L(0); PG8_BAR; PG8_MMA(1, 0, At, B0); PG8_MMA(1, 1, At, B1); PG8_BAR; PG8_SCHED;
;             PG8_LDB(B0, 1, 0); PG8_LDB(B1, 1, 1); PG8_SCHED; PG8_LDA(At, 1, 0); PG8_STAGE(PG8_SA(0, 1), a2 + hstepA, voffA);
;             PG8_WAIT_V(8); PG8_WAIT_L(0); PG8_BAR; PG8_MMA(0, 0, At, B0); PG8_MMA(0, 1, At, B1); PG8_BAR; PG8_SCHED;
;             PG8_LDA(At, 1, 1); PG8_STAGE(PG8_SB(1, 0), b3, voffB); PG8_STAGE(PG8_SB(1, 1), b3 + hstepB, voffB); PG8_STAGE(PG8_SA(1, 0), a3, voffA);
;             PG8_WAIT_V(8); PG8_WAIT_L(0); PG8_BAR; PG8_MMA(1, 0, At, B0); PG8_MMA(1, 1, At, B1); PG8_BAR; PG8_SCHED;
	s_setprio 0
	s_add_i32 s68, s73, s5
	v_lshl_add_u64 v[8:9], v[218:219], 0, s[24:25]
	s_mov_b32 m0, s68
	ds_read_b128 v[158:161], v237 offset:49152
	ds_read_b128 v[162:165], v237 offset:50176
	ds_read_b128 v[166:169], v237 offset:51200
	ds_read_b128 v[178:181], v237 offset:52224
	ds_read_b128 v[182:185], v237 offset:53248
	ds_read_b128 v[186:189], v237 offset:54272
	ds_read_b128 v[190:193], v237 offset:55296
	ds_read_b128 v[194:197], v237 offset:56320
	global_load_lds_dwordx4 v[8:9], off
	s_add_i32 m0, s68, 0x2000
	s_add_u32 s66, s66, 0x40080
	v_lshl_add_u64 v[8:9], v[220:221], 0, s[24:25]
	s_addc_u32 s67, s67, 0
	s_add_i32 s68, s74, s5
	global_load_lds_dwordx4 v[8:9], off
	v_lshl_add_u64 v[8:9], s[66:67], 0, v[204:205]
	s_mov_b32 m0, s68
	s_nop 0
	global_load_lds_dwordx4 v[8:9], off
	v_lshl_add_u64 v[8:9], s[66:67], 0, v[208:209]
	s_add_i32 m0, s68, 0x2000
	s_nop 0
	global_load_lds_dwordx4 v[8:9], off
	v_lshl_add_u64 v[8:9], v[222:223], 0, s[24:25]
	s_mov_b32 m0, s45
	s_nop 0
	global_load_lds_dwordx4 v[8:9], off
	v_lshl_add_u64 v[8:9], v[224:225], 0, s[24:25]
	s_mov_b32 m0, s50
	s_nop 0
	global_load_lds_dwordx4 v[8:9], off
	s_waitcnt vmcnt(8)
	s_waitcnt lgkmcnt(0)
	s_setprio 1
	s_barrier
	v_mfma_f32_16x16x32_bf16 v[66:69], v[78:81], v[158:161], v[66:69]
	v_mfma_f32_16x16x32_bf16 v[62:65], v[102:105], v[158:161], v[62:65]
	v_mfma_f32_16x16x32_bf16 v[50:53], v[78:81], v[166:169], v[50:53]
	v_mfma_f32_16x16x32_bf16 v[46:49], v[102:105], v[166:169], v[46:49]
	v_mfma_f32_16x16x32_bf16 v[34:37], v[78:81], v[182:185], v[34:37]
	v_mfma_f32_16x16x32_bf16 v[30:33], v[102:105], v[182:185], v[30:33]
	v_mfma_f32_16x16x32_bf16 v[18:21], v[78:81], v[190:193], v[18:21]
	v_mfma_f32_16x16x32_bf16 v[14:17], v[102:105], v[190:193], v[14:17]
	v_mfma_f32_16x16x32_bf16 v[66:69], v[82:85], v[162:165], v[66:69]
	v_mfma_f32_16x16x32_bf16 v[62:65], v[106:109], v[162:165], v[62:65]
	v_mfma_f32_16x16x32_bf16 v[50:53], v[82:85], v[178:181], v[50:53]
	v_mfma_f32_16x16x32_bf16 v[46:49], v[106:109], v[178:181], v[46:49]
	v_mfma_f32_16x16x32_bf16 v[34:37], v[82:85], v[186:189], v[34:37]
	v_mfma_f32_16x16x32_bf16 v[30:33], v[106:109], v[186:189], v[30:33]
	v_mfma_f32_16x16x32_bf16 v[18:21], v[82:85], v[194:197], v[18:21]
	v_mfma_f32_16x16x32_bf16 v[14:17], v[106:109], v[194:197], v[14:17]
	v_mfma_f32_16x16x32_bf16 v[58:61], v[134:137], v[158:161], v[58:61]
	v_mfma_f32_16x16x32_bf16 v[54:57], v[142:145], v[158:161], v[54:57]
	v_mfma_f32_16x16x32_bf16 v[42:45], v[134:137], v[166:169], v[42:45]
	v_mfma_f32_16x16x32_bf16 v[38:41], v[142:145], v[166:169], v[38:41]
	v_mfma_f32_16x16x32_bf16 v[26:29], v[134:137], v[182:185], v[26:29]
	v_mfma_f32_16x16x32_bf16 v[22:25], v[142:145], v[182:185], v[22:25]
	v_mfma_f32_16x16x32_bf16 v[8:11], v[134:137], v[190:193], v[10:13]
	v_mfma_f32_16x16x32_bf16 v[4:7], v[142:145], v[190:193], v[4:7]
	v_mfma_f32_16x16x32_bf16 v[58:61], v[138:141], v[162:165], v[58:61]
	v_mfma_f32_16x16x32_bf16 v[54:57], v[154:157], v[162:165], v[54:57]
	v_mfma_f32_16x16x32_bf16 v[42:45], v[138:141], v[178:181], v[42:45]
	v_mfma_f32_16x16x32_bf16 v[38:41], v[154:157], v[178:181], v[38:41]
	v_mfma_f32_16x16x32_bf16 v[26:29], v[138:141], v[186:189], v[26:29]
	v_mfma_f32_16x16x32_bf16 v[22:25], v[154:157], v[186:189], v[22:25]
	v_mfma_f32_16x16x32_bf16 v[10:13], v[138:141], v[194:197], v[8:11]
	v_mfma_f32_16x16x32_bf16 v[6:9], v[154:157], v[194:197], v[4:7]
	s_barrier
	s_setprio 0
	s_add_i32 s72, s72, 2
	s_add_u32 s64, s64, 0x100
	s_addc_u32 s65, s65, 0
	s_add_u32 s70, s70, 0x100
	s_addc_u32 s71, s71, 0
	s_cmp_gt_u32 s72, 5
	s_cbranch_scc0 .LBB0_963
	s_and_b64 vcc, exec, s[28:29]
	s_cbranch_vccz .LBB0_966
	s_barrier

; #define PG8_STAGE(bufoff, gbase, voff) do { _Pragma("unroll") for (int _i = 0; _i < 2; ++_i) \
;         __builtin_amdgcn_global_load_lds((const unsigned*)((const char*)(gbase) + (voff)[_i]), (PG8_LAS unsigned*)(lds + (bufoff) + ldsw + _i * 8192), 16, 0, 0); } while (0)
; #define PG8_LDA(dst, b, h) do { _Pragma("unroll") for (int m = 0; m < 4; ++m) _Pragma("unroll") for (int k = 0; k < 2; ++k) dst[m][k] = *(const PG8_LAS bf16x8*)(lds + PG8_SA(b, h) + aoff + m * 2048 + k * 1024); } while (0)
; #define PG8_LDB(dst, b, h) do { _Pragma("unroll") for (int n = 0; n < 2; ++n) _Pragma("unroll") for (int k = 0; k < 2; ++k) dst[n][k] = *(const PG8_LAS bf16x8*)(lds + PG8_SB(b, h) + boff + n * 2048 + k * 1024); } while (0)
; #define PG8_MMA(ai, bj, At, Bt) do { __builtin_amdgcn_s_setprio(1); _Pragma("unroll") for (int m = 0; m < 4; ++m) _Pragma("unroll") for (int n = 0; n < 2; ++n) _Pragma("unroll") for (int k = 0; k < 2; ++k) \
;         acc[ai][bj][m][n] = __builtin_amdgcn_mfma_f32_16x16x32_bf16(Bt[n][k], At[m][k], acc[ai][bj][m][n], 0, 0, 0); __builtin_amdgcn_s_setprio(0); } while (0)
; #define PG8_WAIT_V(n) asm volatile("s_waitcnt vmcnt(" #n ")" ::: "memory")
; template <class Epi, class Sched, bool ALIGN_EPI = false, bool SP2 = false>
; __device__ __forceinline__ void gemm_phase(PG8_LAS unsigned char* lds, const Gemm g, const Sched& S, const Epi& E) {
;     ...
;             PG8_LDB(B0, 0, 0); PG8_LDB(B1, 0, 1); PG8_SCHED; PG8_LDA(At, 0, 0); PG8_STAGE(PG8_SA(1, 1), a1 + hstepA, voffA);
;             PG8_WAIT_V(8); PG8_WAIT_L(0); PG8_BAR; PG8_MMA(0, 0, At, B0); PG8_MMA(0, 1, At, B1); PG8_BAR; PG8_SCHED;
;             PG8_LDA(At, 0, 1); PG8_STAGE(PG8_SB(0, 0), b2, voffB); PG8_STAGE(PG8_SB(0, 1), b2 + hstepB, voffB); PG8_STAGE(PG8_SA(0, 0), a2, voffA);
;             PG8_WAIT_V(8); PG8_WAIT_L(0); PG8_BAR; PG8_MMA(1, 0, At, B0); PG8_MMA(1, 1, At, B1); PG8_BAR; PG8_SCHED;
;             PG8_LDB(B0, 1, 0); PG8_LDB(B1, 1, 1); PG8_SCHED; PG8_LDA(At, 1, 0); PG8_STAGE(PG8_SA(0, 1), a2 + hstepA, voffA);
;             PG8_WAIT_V(8); PG8_WAIT_L(0); PG8_BAR; PG8_MMA(0, 0, At, B0); PG8_MMA(0, 1, At, B1); PG8_BAR; PG8_SCHED;
;             PG8_LDA(At, 1, 1); PG8_STAGE(PG8_SB(1, 0), b3, voffB); PG8_STAGE(PG8_SB(1, 1), b3 + hstepB, voffB); PG8_STAGE(PG8_SA(1, 0), a3, voffA);
;             PG8_WAIT_V(8); PG8_WAIT_L(0); PG8_BAR; PG8_MMA(1, 0, At, B0); PG8_MMA(1, 1, At, B1); PG8_BAR; PG8_SCHED;
.LBB0_1088:
	v_add_u32_e32 v166, s64, v152
	v_add_u32_e32 v171, s65, v152
	s_add_u32 s46, s22, s40
	ds_read_b128 v[154:157], v166
	ds_read_b128 v[158:161], v166 offset:1024
	ds_read_b128 v[162:165], v166 offset:2048
	ds_read_b128 v[166:169], v166 offset:3072
	ds_read_b128 v[172:175], v171
	ds_read_b128 v[176:179], v171 offset:1024
	ds_read_b128 v[180:183], v171 offset:2048
	ds_read_b128 v[184:187], v171 offset:3072
	s_addc_u32 s47, s23, s41
	s_add_u32 s46, s46, 0x100
	s_addc_u32 s47, s47, 0
	s_add_u32 s72, s67, s40
	s_addc_u32 s73, s68, s41
	s_cmpk_eq_i32 s40, 0x700
	s_cselect_b32 s49, s31, s47
	s_cselect_b32 s48, s69, s46
	s_cselect_b32 s47, s29, s73
	s_cselect_b32 s46, s70, s72
	v_lshl_add_u64 v[220:221], v[146:147], 0, s[40:41]
	s_add_i32 m0, s43, 0xc000
	ds_read_b128 v[188:191], v153
	ds_read_b128 v[192:195], v153 offset:1024
	ds_read_b128 v[196:199], v153 offset:2048
	ds_read_b128 v[200:203], v153 offset:3072
	ds_read_b128 v[204:207], v153 offset:4096
	ds_read_b128 v[208:211], v153 offset:5120
	ds_read_b128 v[212:215], v153 offset:6144
	ds_read_b128 v[216:219], v153 offset:7168
	global_load_lds_dwordx4 v[220:221], off
	v_lshl_add_u64 v[220:221], v[148:149], 0, s[40:41]
	s_add_i32 m0, s43, 0xe000
	s_nop 0
	global_load_lds_dwordx4 v[220:221], off
	s_waitcnt vmcnt(8)
	s_waitcnt lgkmcnt(0)
	s_setprio 1
	s_barrier
	v_mfma_f32_16x16x32_bf16 v[122:125], v[154:157], v[188:191], v[122:125]
	v_mfma_f32_16x16x32_bf16 v[118:121], v[162:165], v[188:191], v[118:121]
	v_mfma_f32_16x16x32_bf16 v[114:117], v[154:157], v[196:199], v[114:117]
	v_mfma_f32_16x16x32_bf16 v[98:101], v[162:165], v[196:199], v[98:101]
	v_mfma_f32_16x16x32_bf16 v[134:137], v[154:157], v[204:207], v[134:137]
	v_mfma_f32_16x16x32_bf16 v[102:105], v[162:165], v[204:207], v[102:105]
	v_mfma_f32_16x16x32_bf16 v[110:113], v[154:157], v[212:215], v[110:113]
	v_mfma_f32_16x16x32_bf16 v[86:89], v[162:165], v[212:215], v[86:89]
	v_mfma_f32_16x16x32_bf16 v[122:125], v[158:161], v[192:195], v[122:125]
	v_mfma_f32_16x16x32_bf16 v[118:121], v[166:169], v[192:195], v[118:121]
	v_mfma_f32_16x16x32_bf16 v[114:117], v[158:161], v[200:203], v[114:117]
	v_mfma_f32_16x16x32_bf16 v[98:101], v[166:169], v[200:203], v[98:101]
	v_mfma_f32_16x16x32_bf16 v[134:137], v[158:161], v[208:211], v[134:137]
	v_mfma_f32_16x16x32_bf16 v[102:105], v[166:169], v[208:211], v[102:105]
	v_mfma_f32_16x16x32_bf16 v[110:113], v[158:161], v[216:219], v[110:113]
	v_mfma_f32_16x16x32_bf16 v[86:89], v[166:169], v[216:219], v[86:89]
	v_mfma_f32_16x16x32_bf16 v[106:109], v[172:175], v[188:191], v[106:109]
	v_mfma_f32_16x16x32_bf16 v[94:97], v[180:183], v[188:191], v[94:97]
	v_mfma_f32_16x16x32_bf16 v[90:93], v[172:175], v[196:199], v[90:93]
	v_mfma_f32_16x16x32_bf16 v[82:85], v[180:183], v[196:199], v[82:85]
	v_mfma_f32_16x16x32_bf16 v[78:81], v[172:175], v[204:207], v[78:81]
	v_mfma_f32_16x16x32_bf16 v[74:77], v[180:183], v[204:207], v[74:77]
	v_mfma_f32_16x16x32_bf16 v[70:73], v[172:175], v[212:215], v[70:73]
	v_mfma_f32_16x16x32_bf16 v[66:69], v[180:183], v[212:215], v[66:69]
	v_mfma_f32_16x16x32_bf16 v[106:109], v[176:179], v[192:195], v[106:109]
	v_mfma_f32_16x16x32_bf16 v[94:97], v[184:187], v[192:195], v[94:97]
	v_mfma_f32_16x16x32_bf16 v[90:93], v[176:179], v[200:203], v[90:93]
	v_mfma_f32_16x16x32_bf16 v[82:85], v[184:187], v[200:203], v[82:85]
	v_mfma_f32_16x16x32_bf16 v[78:81], v[176:179], v[208:211], v[78:81]
	v_mfma_f32_16x16x32_bf16 v[74:77], v[184:187], v[208:211], v[74:77]
	v_mfma_f32_16x16x32_bf16 v[70:73], v[176:179], v[216:219], v[70:73]
	v_mfma_f32_16x16x32_bf16 v[66:69], v[184:187], v[216:219], v[66:69]
	s_barrier
	s_setprio 0
	s_add_i32 s72, s64, s33
	v_lshl_add_u64 v[220:221], s[46:47], 0, v[126:127]
	s_mov_b32 m0, s72
	ds_read_b128 v[188:191], v153 offset:16384
	ds_read_b128 v[192:195], v153 offset:17408
	ds_read_b128 v[196:199], v153 offset:18432
	ds_read_b128 v[200:203], v153 offset:19456
	ds_read_b128 v[204:207], v153 offset:20480
	ds_read_b128 v[208:211], v153 offset:21504
	ds_read_b128 v[212:215], v153 offset:22528
	ds_read_b128 v[216:219], v153 offset:23552
	global_load_lds_dwordx4 v[220:221], off
	s_add_i32 m0, s72, 0x2000
	s_add_u32 s72, s46, 0x40000
	v_lshl_add_u64 v[222:223], s[46:47], 0, v[132:133]
	s_addc_u32 s73, s47, 0
	s_add_i32 s74, s65, s33
	global_load_lds_dwordx4 v[222:223], off
	v_lshl_add_u64 v[224:225], s[72:73], 0, v[126:127]
	s_mov_b32 m0, s74
	v_lshl_add_u64 v[226:227], s[48:49], 0, v[130:131]
	global_load_lds_dwordx4 v[224:225], off
	v_lshl_add_u64 v[224:225], s[72:73], 0, v[132:133]
	s_add_i32 m0, s74, 0x2000
	s_nop 0
	global_load_lds_dwordx4 v[224:225], off
	v_lshl_add_u64 v[224:225], s[48:49], 0, v[128:129]
	s_mov_b32 m0, s43
	s_nop 0
	global_load_lds_dwordx4 v[224:225], off
	s_mov_b32 m0, s44
	s_nop 0
	global_load_lds_dwordx4 v[226:227], off
	s_waitcnt vmcnt(8)
	s_waitcnt lgkmcnt(0)
	s_setprio 1
	s_barrier
; #define PG8_STAGE(bufoff, gbase, voff) do { _Pragma("unroll") for (int _i = 0; _i < 2; ++_i) \
;         __builtin_amdgcn_global_load_lds((const unsigned*)((const char*)(gbase) + (voff)[_i]), (PG8_LAS unsigned*)(lds + (bufoff) + ldsw + _i * 8192), 16, 0, 0); } while (0)
; #define PG8_LDA(dst, b, h) do { _Pragma("unroll") for (int m = 0; m < 4; ++m) _Pragma("unroll") for (int k = 0; k < 2; ++k) dst[m][k] = *(const PG8_LAS bf16x8*)(lds + PG8_SA(b, h) + aoff + m * 2048 + k * 1024); } while (0)
; #define PG8_LDB(dst, b, h) do { _Pragma("unroll") for (int n = 0; n < 2; ++n) _Pragma("unroll") for (int k = 0; k < 2; ++k) dst[n][k] = *(const PG8_LAS bf16x8*)(lds + PG8_SB(b, h) + boff + n * 2048 + k * 1024); } while (0)
; #define PG8_MMA(ai, bj, At, Bt) do { __builtin_amdgcn_s_setprio(1); _Pragma("unroll") for (int m = 0; m < 4; ++m) _Pragma("unroll") for (int n = 0; n < 2; ++n) _Pragma("unroll") for (int k = 0; k < 2; ++k) \
;         acc[ai][bj][m][n] = __builtin_amdgcn_mfma_f32_16x16x32_bf16(Bt[n][k], At[m][k], acc[ai][bj][m][n], 0, 0, 0); __builtin_amdgcn_s_setprio(0); } while (0)
; #define PG8_WAIT_V(n) asm volatile("s_waitcnt vmcnt(" #n ")" ::: "memory")
; template <class Epi, class Sched, bool ALIGN_EPI = false, bool SP2 = false>
; __device__ __forceinline__ void gemm_phase(PG8_LAS unsigned char* lds, const Gemm g, const Sched& S, const Epi& E) {
;     ...
;             PG8_LDB(B0, 0, 0); PG8_LDB(B1, 0, 1); PG8_SCHED; PG8_LDA(At, 0, 0); PG8_STAGE(PG8_SA(1, 1), a1 + hstepA, voffA);
;             PG8_WAIT_V(8); PG8_WAIT_L(0); PG8_BAR; PG8_MMA(0, 0, At, B0); PG8_MMA(0, 1, At, B1); PG8_BAR; PG8_SCHED;
;             PG8_LDA(At, 0, 1); PG8_STAGE(PG8_SB(0, 0), b2, voffB); PG8_STAGE(PG8_SB(0, 1), b2 + hstepB, voffB); PG8_STAGE(PG8_SA(0, 0), a2, voffA);
;             PG8_WAIT_V(8); PG8_WAIT_L(0); PG8_BAR; PG8_MMA(1, 0, At, B0); PG8_MMA(1, 1, At, B1); PG8_BAR; PG8_SCHED;
;             PG8_LDB(B0, 1, 0); PG8_LDB(B1, 1, 1); PG8_SCHED; PG8_LDA(At, 1, 0); PG8_STAGE(PG8_SA(0, 1), a2 + hstepA, voffA);
;             PG8_WAIT_V(8); PG8_WAIT_L(0); PG8_BAR; PG8_MMA(0, 0, At, B0); PG8_MMA(0, 1, At, B1); PG8_BAR; PG8_SCHED;
;             PG8_LDA(At, 1, 1); PG8_STAGE(PG8_SB(1, 0), b3, voffB); PG8_STAGE(PG8_SB(1, 1), b3 + hstepB, voffB); PG8_STAGE(PG8_SA(1, 0), a3, voffA);
;             PG8_WAIT_V(8); PG8_WAIT_L(0); PG8_BAR; PG8_MMA(1, 0, At, B0); PG8_MMA(1, 1, At, B1); PG8_BAR; PG8_SCHED;
	v_mfma_f32_16x16x32_bf16 v[62:65], v[154:157], v[188:191], v[62:65]
	v_mfma_f32_16x16x32_bf16 v[58:61], v[162:165], v[188:191], v[58:61]
	v_mfma_f32_16x16x32_bf16 v[54:57], v[154:157], v[196:199], v[54:57]
	v_mfma_f32_16x16x32_bf16 v[46:49], v[162:165], v[196:199], v[46:49]
	v_mfma_f32_16x16x32_bf16 v[38:41], v[154:157], v[204:207], v[38:41]
	v_mfma_f32_16x16x32_bf16 v[30:33], v[162:165], v[204:207], v[30:33]
	v_mfma_f32_16x16x32_bf16 v[14:17], v[154:157], v[212:215], v[14:17]
	v_mfma_f32_16x16x32_bf16 v[10:13], v[162:165], v[212:215], v[10:13]
	v_mfma_f32_16x16x32_bf16 v[62:65], v[158:161], v[192:195], v[62:65]
	v_mfma_f32_16x16x32_bf16 v[58:61], v[166:169], v[192:195], v[58:61]
	v_mfma_f32_16x16x32_bf16 v[54:57], v[158:161], v[200:203], v[54:57]
	v_mfma_f32_16x16x32_bf16 v[46:49], v[166:169], v[200:203], v[46:49]
	v_mfma_f32_16x16x32_bf16 v[38:41], v[158:161], v[208:211], v[38:41]
	v_mfma_f32_16x16x32_bf16 v[30:33], v[166:169], v[208:211], v[30:33]
	v_mfma_f32_16x16x32_bf16 v[14:17], v[158:161], v[216:219], v[14:17]
	v_mfma_f32_16x16x32_bf16 v[10:13], v[166:169], v[216:219], v[10:13]
	v_mfma_f32_16x16x32_bf16 v[50:53], v[172:175], v[188:191], v[50:53]
	v_mfma_f32_16x16x32_bf16 v[42:45], v[180:183], v[188:191], v[42:45]
	v_mfma_f32_16x16x32_bf16 v[34:37], v[172:175], v[196:199], v[34:37]
	v_mfma_f32_16x16x32_bf16 v[26:29], v[180:183], v[196:199], v[26:29]
	v_mfma_f32_16x16x32_bf16 v[22:25], v[172:175], v[204:207], v[22:25]
	v_mfma_f32_16x16x32_bf16 v[18:21], v[180:183], v[204:207], v[18:21]
	v_mfma_f32_16x16x32_bf16 v[6:9], v[172:175], v[212:215], v[6:9]
	v_mfma_f32_16x16x32_bf16 v[2:5], v[180:183], v[212:215], v[2:5]
	v_mfma_f32_16x16x32_bf16 v[50:53], v[176:179], v[192:195], v[50:53]
	v_mfma_f32_16x16x32_bf16 v[42:45], v[184:187], v[192:195], v[42:45]
	v_mfma_f32_16x16x32_bf16 v[34:37], v[176:179], v[200:203], v[34:37]
	v_mfma_f32_16x16x32_bf16 v[26:29], v[184:187], v[200:203], v[26:29]
	v_mfma_f32_16x16x32_bf16 v[22:25], v[176:179], v[208:211], v[22:25]
	v_mfma_f32_16x16x32_bf16 v[18:21], v[184:187], v[208:211], v[18:21]
	v_mfma_f32_16x16x32_bf16 v[6:9], v[176:179], v[216:219], v[6:9]
	v_mfma_f32_16x16x32_bf16 v[2:5], v[184:187], v[216:219], v[2:5]
	s_barrier
	s_setprio 0
	s_add_i32 s72, 0, 0x18000
	s_add_i32 s73, 0, 0x1c000
	v_add_u32_e32 v166, s72, v152
	v_add_u32_e32 v171, s73, v152
	ds_read_b128 v[154:157], v166
	ds_read_b128 v[158:161], v166 offset:1024
	ds_read_b128 v[162:165], v166 offset:2048
	ds_read_b128 v[166:169], v166 offset:3072
	ds_read_b128 v[172:175], v171
	ds_read_b128 v[176:179], v171 offset:1024
	ds_read_b128 v[180:183], v171 offset:2048
	ds_read_b128 v[184:187], v171 offset:3072
	s_add_u32 s48, s48, 0x40000
	s_addc_u32 s49, s49, 0
	s_mov_b32 m0, s45
	v_lshl_add_u64 v[228:229], s[48:49], 0, v[128:129]
	ds_read_b128 v[188:191], v153 offset:32768
	ds_read_b128 v[192:195], v153 offset:33792
	ds_read_b128 v[196:199], v153 offset:34816
	ds_read_b128 v[200:203], v153 offset:35840
	ds_read_b128 v[204:207], v153 offset:36864
	ds_read_b128 v[208:211], v153 offset:37888
	ds_read_b128 v[212:215], v153 offset:38912
	ds_read_b128 v[216:219], v153 offset:39936
	global_load_lds_dwordx4 v[228:229], off
	v_lshl_add_u64 v[228:229], s[48:49], 0, v[130:131]
	s_mov_b32 m0, s50
	s_nop 0
	global_load_lds_dwordx4 v[228:229], off
	s_waitcnt vmcnt(8)
	s_waitcnt lgkmcnt(0)
	s_setprio 1
	s_barrier
	v_mfma_f32_16x16x32_bf16 v[122:125], v[154:157], v[188:191], v[122:125]
	v_mfma_f32_16x16x32_bf16 v[118:121], v[162:165], v[188:191], v[118:121]
	v_mfma_f32_16x16x32_bf16 v[114:117], v[154:157], v[196:199], v[114:117]
	v_mfma_f32_16x16x32_bf16 v[98:101], v[162:165], v[196:199], v[98:101]
	v_mfma_f32_16x16x32_bf16 v[134:137], v[154:157], v[204:207], v[134:137]
	v_mfma_f32_16x16x32_bf16 v[102:105], v[162:165], v[204:207], v[102:105]
	v_mfma_f32_16x16x32_bf16 v[110:113], v[154:157], v[212:215], v[110:113]
	v_mfma_f32_16x16x32_bf16 v[86:89], v[162:165], v[212:215], v[86:89]
	v_mfma_f32_16x16x32_bf16 v[122:125], v[158:161], v[192:195], v[122:125]
	v_mfma_f32_16x16x32_bf16 v[118:121], v[166:169], v[192:195], v[118:121]
	v_mfma_f32_16x16x32_bf16 v[114:117], v[158:161], v[200:203], v[114:117]
	v_mfma_f32_16x16x32_bf16 v[98:101], v[166:169], v[200:203], v[98:101]
	v_mfma_f32_16x16x32_bf16 v[134:137], v[158:161], v[208:211], v[134:137]
	v_mfma_f32_16x16x32_bf16 v[102:105], v[166:169], v[208:211], v[102:105]
	v_mfma_f32_16x16x32_bf16 v[110:113], v[158:161], v[216:219], v[110:113]
	v_mfma_f32_16x16x32_bf16 v[86:89], v[166:169], v[216:219], v[86:89]
	v_mfma_f32_16x16x32_bf16 v[106:109], v[172:175], v[188:191], v[106:109]
	v_mfma_f32_16x16x32_bf16 v[94:97], v[180:183], v[188:191], v[94:97]
	v_mfma_f32_16x16x32_bf16 v[90:93], v[172:175], v[196:199], v[90:93]
	v_mfma_f32_16x16x32_bf16 v[82:85], v[180:183], v[196:199], v[82:85]
	v_mfma_f32_16x16x32_bf16 v[78:81], v[172:175], v[204:207], v[78:81]
	v_mfma_f32_16x16x32_bf16 v[74:77], v[180:183], v[204:207], v[74:77]
	v_mfma_f32_16x16x32_bf16 v[70:73], v[172:175], v[212:215], v[70:73]
	v_mfma_f32_16x16x32_bf16 v[66:69], v[180:183], v[212:215], v[66:69]
	v_mfma_f32_16x16x32_bf16 v[106:109], v[176:179], v[192:195], v[106:109]
	v_mfma_f32_16x16x32_bf16 v[94:97], v[184:187], v[192:195], v[94:97]
	v_mfma_f32_16x16x32_bf16 v[90:93], v[176:179], v[200:203], v[90:93]
	v_mfma_f32_16x16x32_bf16 v[82:85], v[184:187], v[200:203], v[82:85]
	v_mfma_f32_16x16x32_bf16 v[78:81], v[176:179], v[208:211], v[78:81]
	v_mfma_f32_16x16x32_bf16 v[74:77], v[184:187], v[208:211], v[74:77]
	v_mfma_f32_16x16x32_bf16 v[70:73], v[176:179], v[216:219], v[70:73]
	v_mfma_f32_16x16x32_bf16 v[66:69], v[184:187], v[216:219], v[66:69]
	s_barrier
; #define PG8_STAGE(bufoff, gbase, voff) do { _Pragma("unroll") for (int _i = 0; _i < 2; ++_i) \
;         __builtin_amdgcn_global_load_lds((const unsigned*)((const char*)(gbase) + (voff)[_i]), (PG8_LAS unsigned*)(lds + (bufoff) + ldsw + _i * 8192), 16, 0, 0); } while (0)
; #define PG8_LDA(dst, b, h) do { _Pragma("unroll") for (int m = 0; m < 4; ++m) _Pragma("unroll") for (int k = 0; k < 2; ++k) dst[m][k] = *(const PG8_LAS bf16x8*)(lds + PG8_SA(b, h) + aoff + m * 2048 + k * 1024); } while (0)
; #define PG8_LDB(dst, b, h) do { _Pragma("unroll") for (int n = 0; n < 2; ++n) _Pragma("unroll") for (int k = 0; k < 2; ++k) dst[n][k] = *(const PG8_LAS bf16x8*)(lds + PG8_SB(b, h) + boff + n * 2048 + k * 1024); } while (0)
; #define PG8_WAIT_V(n) asm volatile("s_waitcnt vmcnt(" #n ")" ::: "memory")
; template <class Epi, class Sched, bool ALIGN_EPI = false, bool SP2 = false>
; __device__ __forceinline__ void gemm_phase(PG8_LAS unsigned char* lds, const Gemm g, const Sched& S, const Epi& E) {
;     ...
;             PG8_LDB(B0, 0, 0); PG8_LDB(B1, 0, 1); PG8_SCHED; PG8_LDA(At, 0, 0); PG8_STAGE(PG8_SA(1, 1), a1 + hstepA, voffA);
;             PG8_WAIT_V(8); PG8_WAIT_L(0); PG8_BAR; PG8_MMA(0, 0, At, B0); PG8_MMA(0, 1, At, B1); PG8_BAR; PG8_SCHED;
;             PG8_LDA(At, 0, 1); PG8_STAGE(PG8_SB(0, 0), b2, voffB); PG8_STAGE(PG8_SB(0, 1), b2 + hstepB, voffB); PG8_STAGE(PG8_SA(0, 0), a2, voffA);
;             PG8_WAIT_V(8); PG8_WAIT_L(0); PG8_BAR; PG8_MMA(1, 0, At, B0); PG8_MMA(1, 1, At, B1); PG8_BAR; PG8_SCHED;
;             PG8_LDB(B0, 1, 0); PG8_LDB(B1, 1, 1); PG8_SCHED; PG8_LDA(At, 1, 0); PG8_STAGE(PG8_SA(0, 1), a2 + hstepA, voffA);
;             PG8_WAIT_V(8); PG8_WAIT_L(0); PG8_BAR; PG8_MMA(0, 0, At, B0); PG8_MMA(0, 1, At, B1); PG8_BAR; PG8_SCHED;
;             PG8_LDA(At, 1, 1); PG8_STAGE(PG8_SB(1, 0), b3, voffB); PG8_STAGE(PG8_SB(1, 1), b3 + hstepB, voffB); PG8_STAGE(PG8_SA(1, 0), a3, voffA);
;             PG8_WAIT_V(8); PG8_WAIT_L(0); PG8_BAR; PG8_MMA(1, 0, At, B0); PG8_MMA(1, 1, At, B1); PG8_BAR; PG8_SCHED;
;     ...
;         if (!has_next) break;
;         if (!keep_) {
; #pragma unroll
;         for (int a = 0; a < 2; ++a)
; #pragma unroll
;             for (int b = 0; b < 2; ++b)
; #pragma unroll
;                 for (int m = 0; m < 4; ++m)
; #pragma unroll
;                     for (int n = 0; n < 2; ++n) acc[a][b][m][n] = (f32x4){0.f, 0.f, 0.f, 0.f};
;         }
	s_setprio 0
	s_add_i32 s48, s72, s33
	v_lshl_add_u64 v[220:221], v[220:221], 0, s[24:25]
	s_mov_b32 m0, s48
	ds_read_b128 v[188:191], v153 offset:49152
	ds_read_b128 v[192:195], v153 offset:50176
	ds_read_b128 v[196:199], v153 offset:51200
	ds_read_b128 v[200:203], v153 offset:52224
	ds_read_b128 v[204:207], v153 offset:53248
	ds_read_b128 v[208:211], v153 offset:54272
	ds_read_b128 v[212:215], v153 offset:55296
	ds_read_b128 v[216:219], v153 offset:56320
	global_load_lds_dwordx4 v[220:221], off
	s_add_i32 m0, s48, 0x2000
	s_add_u32 s46, s46, 0x40080
	v_lshl_add_u64 v[220:221], v[222:223], 0, s[24:25]
	s_addc_u32 s47, s47, 0
	s_add_i32 s48, s73, s33
	global_load_lds_dwordx4 v[220:221], off
	v_lshl_add_u64 v[220:221], s[46:47], 0, v[126:127]
	s_mov_b32 m0, s48
	s_nop 0
	global_load_lds_dwordx4 v[220:221], off
	v_lshl_add_u64 v[220:221], s[46:47], 0, v[132:133]
	s_add_i32 m0, s48, 0x2000
	s_nop 0
	global_load_lds_dwordx4 v[220:221], off
	v_lshl_add_u64 v[220:221], v[224:225], 0, s[24:25]
	s_mov_b32 m0, s62
	s_nop 0
	global_load_lds_dwordx4 v[220:221], off
	v_lshl_add_u64 v[220:221], v[226:227], 0, s[24:25]
	s_mov_b32 m0, s63
	s_nop 0
	global_load_lds_dwordx4 v[220:221], off
	s_waitcnt vmcnt(8)
	s_waitcnt lgkmcnt(0)
	s_setprio 1
	s_barrier
	v_mfma_f32_16x16x32_bf16 v[62:65], v[154:157], v[188:191], v[62:65]
	v_mfma_f32_16x16x32_bf16 v[58:61], v[162:165], v[188:191], v[58:61]
	v_mfma_f32_16x16x32_bf16 v[54:57], v[154:157], v[196:199], v[54:57]
	v_mfma_f32_16x16x32_bf16 v[46:49], v[162:165], v[196:199], v[46:49]
	v_mfma_f32_16x16x32_bf16 v[38:41], v[154:157], v[204:207], v[38:41]
	v_mfma_f32_16x16x32_bf16 v[30:33], v[162:165], v[204:207], v[30:33]
	v_mfma_f32_16x16x32_bf16 v[14:17], v[154:157], v[212:215], v[14:17]
	v_mfma_f32_16x16x32_bf16 v[10:13], v[162:165], v[212:215], v[10:13]
	v_mfma_f32_16x16x32_bf16 v[62:65], v[158:161], v[192:195], v[62:65]
	v_mfma_f32_16x16x32_bf16 v[58:61], v[166:169], v[192:195], v[58:61]
	v_mfma_f32_16x16x32_bf16 v[54:57], v[158:161], v[200:203], v[54:57]
	v_mfma_f32_16x16x32_bf16 v[46:49], v[166:169], v[200:203], v[46:49]
	v_mfma_f32_16x16x32_bf16 v[38:41], v[158:161], v[208:211], v[38:41]
	v_mfma_f32_16x16x32_bf16 v[30:33], v[166:169], v[208:211], v[30:33]
	v_mfma_f32_16x16x32_bf16 v[14:17], v[158:161], v[216:219], v[14:17]
	v_mfma_f32_16x16x32_bf16 v[10:13], v[166:169], v[216:219], v[10:13]
	v_mfma_f32_16x16x32_bf16 v[50:53], v[172:175], v[188:191], v[50:53]
	v_mfma_f32_16x16x32_bf16 v[42:45], v[180:183], v[188:191], v[42:45]
	v_mfma_f32_16x16x32_bf16 v[34:37], v[172:175], v[196:199], v[34:37]
	v_mfma_f32_16x16x32_bf16 v[26:29], v[180:183], v[196:199], v[26:29]
	v_mfma_f32_16x16x32_bf16 v[22:25], v[172:175], v[204:207], v[22:25]
	v_mfma_f32_16x16x32_bf16 v[18:21], v[180:183], v[204:207], v[18:21]
	v_mfma_f32_16x16x32_bf16 v[6:9], v[172:175], v[212:215], v[6:9]
	v_mfma_f32_16x16x32_bf16 v[2:5], v[180:183], v[212:215], v[2:5]
	v_mfma_f32_16x16x32_bf16 v[50:53], v[176:179], v[192:195], v[50:53]
	v_mfma_f32_16x16x32_bf16 v[42:45], v[184:187], v[192:195], v[42:45]
	v_mfma_f32_16x16x32_bf16 v[34:37], v[176:179], v[200:203], v[34:37]
	v_mfma_f32_16x16x32_bf16 v[26:29], v[184:187], v[200:203], v[26:29]
	v_mfma_f32_16x16x32_bf16 v[22:25], v[176:179], v[208:211], v[22:25]
	v_mfma_f32_16x16x32_bf16 v[18:21], v[184:187], v[208:211], v[18:21]
	v_mfma_f32_16x16x32_bf16 v[6:9], v[176:179], v[216:219], v[6:9]
	v_mfma_f32_16x16x32_bf16 v[2:5], v[184:187], v[216:219], v[2:5]
	s_barrier
	s_setprio 0
	s_add_i32 s71, s71, 2
	s_add_u32 s40, s40, 0x100
	s_addc_u32 s41, s41, 0
	s_cmp_gt_u32 s71, 13
	s_cbranch_scc0 .LBB0_1088
	s_add_u32 s40, s67, 0xffffff00
	s_addc_u32 s41, s68, -1
	s_andn2_b64 vcc, exec, s[6:7]
	s_cbranch_vccnz .LBB0_1079
	v_mov_b32_e32 v2, 0
	s_mov_b32 s18, s28
	s_mov_b32 s10, s30
	s_mov_b64 s[22:23], s[38:39]
	s_mov_b32 s51, s66
	v_mov_b32_e32 v3, v2
	v_mov_b32_e32 v4, v2
	v_mov_b32_e32 v5, v2
	v_mov_b32_e32 v6, v2
	v_mov_b32_e32 v7, v2
	v_mov_b32_e32 v8, v2
	v_mov_b32_e32 v9, v2
	v_mov_b32_e32 v18, v2
	v_mov_b32_e32 v19, v2
	v_mov_b32_e32 v20, v2
	v_mov_b32_e32 v21, v2
	v_mov_b32_e32 v22, v2
	v_mov_b32_e32 v23, v2
	v_mov_b32_e32 v24, v2
	v_mov_b32_e32 v25, v2
	v_mov_b32_e32 v26, v2
	v_mov_b32_e32 v27, v2
	v_mov_b32_e32 v28, v2
	v_mov_b32_e32 v29, v2
	v_mov_b32_e32 v34, v2
	v_mov_b32_e32 v35, v2
	v_mov_b32_e32 v36, v2
	v_mov_b32_e32 v37, v2
	v_mov_b32_e32 v42, v2
	v_mov_b32_e32 v43, v2
	v_mov_b32_e32 v44, v2
	v_mov_b32_e32 v45, v2
	v_mov_b32_e32 v50, v2
	v_mov_b32_e32 v51, v2
	v_mov_b32_e32 v52, v2
	v_mov_b32_e32 v53, v2
	v_mov_b32_e32 v10, v2
	v_mov_b32_e32 v11, v2
	v_mov_b32_e32 v12, v2
	v_mov_b32_e32 v13, v2
	v_mov_b32_e32 v14, v2
	v_mov_b32_e32 v15, v2
	v_mov_b32_e32 v16, v2
	v_mov_b32_e32 v17, v2
	v_mov_b32_e32 v30, v2
	v_mov_b32_e32 v31, v2
	v_mov_b32_e32 v32, v2
	v_mov_b32_e32 v33, v2
	v_mov_b32_e32 v38, v2
	v_mov_b32_e32 v39, v2
	v_mov_b32_e32 v40, v2
	v_mov_b32_e32 v41, v2
	v_mov_b32_e32 v46, v2
	v_mov_b32_e32 v47, v2
	v_mov_b32_e32 v48, v2
	v_mov_b32_e32 v49, v2
	v_mov_b32_e32 v54, v2
	v_mov_b32_e32 v55, v2
	v_mov_b32_e32 v56, v2
	v_mov_b32_e32 v57, v2
	v_mov_b32_e32 v58, v2
	v_mov_b32_e32 v59, v2
	v_mov_b32_e32 v60, v2
	v_mov_b32_e32 v61, v2
	v_mov_b32_e32 v62, v2
	v_mov_b32_e32 v63, v2
	v_mov_b32_e32 v64, v2
	v_mov_b32_e32 v65, v2
	v_mov_b32_e32 v66, v2
	v_mov_b32_e32 v67, v2
	v_mov_b32_e32 v68, v2
	v_mov_b32_e32 v69, v2
	v_mov_b32_e32 v70, v2
	v_mov_b32_e32 v71, v2
	v_mov_b32_e32 v72, v2
	v_mov_b32_e32 v73, v2
	v_mov_b32_e32 v74, v2
	v_mov_b32_e32 v75, v2
	v_mov_b32_e32 v76, v2
	v_mov_b32_e32 v77, v2
	v_mov_b32_e32 v78, v2
	v_mov_b32_e32 v79, v2
	v_mov_b32_e32 v80, v2
	v_mov_b32_e32 v81, v2
	v_mov_b32_e32 v82, v2
	v_mov_b32_e32 v83, v2
	v_mov_b32_e32 v84, v2
	v_mov_b32_e32 v85, v2
	v_mov_b32_e32 v90, v2
	v_mov_b32_e32 v91, v2
	v_mov_b32_e32 v92, v2
	v_mov_b32_e32 v93, v2
	v_mov_b32_e32 v94, v2
	v_mov_b32_e32 v95, v2
	v_mov_b32_e32 v96, v2
	v_mov_b32_e32 v97, v2
	v_mov_b32_e32 v106, v2
	v_mov_b32_e32 v107, v2
	v_mov_b32_e32 v108, v2
	v_mov_b32_e32 v109, v2
	v_mov_b32_e32 v86, v2
	v_mov_b32_e32 v87, v2
	v_mov_b32_e32 v88, v2
	v_mov_b32_e32 v89, v2
	v_mov_b32_e32 v110, v2
	v_mov_b32_e32 v111, v2
	v_mov_b32_e32 v112, v2
	v_mov_b32_e32 v113, v2
	v_mov_b32_e32 v102, v2
	v_mov_b32_e32 v103, v2
	v_mov_b32_e32 v104, v2
	v_mov_b32_e32 v105, v2
	v_mov_b32_e32 v134, v2
	v_mov_b32_e32 v135, v2
	v_mov_b32_e32 v136, v2
	v_mov_b32_e32 v137, v2
	v_mov_b32_e32 v98, v2
	v_mov_b32_e32 v99, v2
	v_mov_b32_e32 v100, v2
	v_mov_b32_e32 v101, v2
	v_mov_b32_e32 v114, v2
	v_mov_b32_e32 v115, v2
	v_mov_b32_e32 v116, v2
	v_mov_b32_e32 v117, v2
	v_mov_b32_e32 v118, v2
	v_mov_b32_e32 v119, v2
	v_mov_b32_e32 v120, v2
	v_mov_b32_e32 v121, v2
	v_mov_b32_e32 v122, v2
	v_mov_b32_e32 v123, v2
	v_mov_b32_e32 v124, v2
	v_mov_b32_e32 v125, v2
	s_andn2_b64 vcc, exec, s[0:1]
	s_cbranch_vccnz .LBB0_1080

; #define PG8_STAGE(bufoff, gbase, voff) do { _Pragma("unroll") for (int _i = 0; _i < 2; ++_i) \
;         __builtin_amdgcn_global_load_lds((const unsigned*)((const char*)(gbase) + (voff)[_i]), (PG8_LAS unsigned*)(lds + (bufoff) + ldsw + _i * 8192), 16, 0, 0); } while (0)
; #define PG8_LDA(dst, b, h) do { _Pragma("unroll") for (int m = 0; m < 4; ++m) _Pragma("unroll") for (int k = 0; k < 2; ++k) dst[m][k] = *(const PG8_LAS bf16x8*)(lds + PG8_SA(b, h) + aoff + m * 2048 + k * 1024); } while (0)
; #define PG8_LDB(dst, b, h) do { _Pragma("unroll") for (int n = 0; n < 2; ++n) _Pragma("unroll") for (int k = 0; k < 2; ++k) dst[n][k] = *(const PG8_LAS bf16x8*)(lds + PG8_SB(b, h) + boff + n * 2048 + k * 1024); } while (0)
; #define PG8_MMA(ai, bj, At, Bt) do { __builtin_amdgcn_s_setprio(1); _Pragma("unroll") for (int m = 0; m < 4; ++m) _Pragma("unroll") for (int n = 0; n < 2; ++n) _Pragma("unroll") for (int k = 0; k < 2; ++k) \
;         acc[ai][bj][m][n] = __builtin_amdgcn_mfma_f32_16x16x32_bf16(Bt[n][k], At[m][k], acc[ai][bj][m][n], 0, 0, 0); __builtin_amdgcn_s_setprio(0); } while (0)
; #define PG8_WAIT_V(n) asm volatile("s_waitcnt vmcnt(" #n ")" ::: "memory")
; template <class Epi, class Sched, bool ALIGN_EPI = false, bool SP2 = false>
; __device__ __forceinline__ void gemm_phase(PG8_LAS unsigned char* lds, const Gemm g, const Sched& S, const Epi& E) {
;     ...
;             PG8_LDB(B0, 0, 0); PG8_LDB(B1, 0, 1); PG8_SCHED; PG8_LDA(At, 0, 0); PG8_STAGE(PG8_SA(1, 1), a1 + hstepA, voffA);
;             PG8_WAIT_V(8); PG8_WAIT_L(0); PG8_BAR; PG8_MMA(0, 0, At, B0); PG8_MMA(0, 1, At, B1); PG8_BAR; PG8_SCHED;
;             PG8_LDA(At, 0, 1); PG8_STAGE(PG8_SB(0, 0), b2, voffB); PG8_STAGE(PG8_SB(0, 1), b2 + hstepB, voffB); PG8_STAGE(PG8_SA(0, 0), a2, voffA);
;             PG8_WAIT_V(8); PG8_WAIT_L(0); PG8_BAR; PG8_MMA(1, 0, At, B0); PG8_MMA(1, 1, At, B1); PG8_BAR; PG8_SCHED;
;             PG8_LDB(B0, 1, 0); PG8_LDB(B1, 1, 1); PG8_SCHED; PG8_LDA(At, 1, 0); PG8_STAGE(PG8_SA(0, 1), a2 + hstepA, voffA);
;             PG8_WAIT_V(8); PG8_WAIT_L(0); PG8_BAR; PG8_MMA(0, 0, At, B0); PG8_MMA(0, 1, At, B1); PG8_BAR; PG8_SCHED;
;             PG8_LDA(At, 1, 1); PG8_STAGE(PG8_SB(1, 0), b3, voffB); PG8_STAGE(PG8_SB(1, 1), b3 + hstepB, voffB); PG8_STAGE(PG8_SA(1, 0), a3, voffA);
;             PG8_WAIT_V(8); PG8_WAIT_L(0); PG8_BAR; PG8_MMA(1, 0, At, B0); PG8_MMA(1, 1, At, B1); PG8_BAR; PG8_SCHED;
.LBB0_1244:
	ds_read_b128 v[158:161], v154
	ds_read_b128 v[162:165], v154 offset:1024
	ds_read_b128 v[166:169], v154 offset:2048
	ds_read_b128 v[170:173], v154 offset:3072
	ds_read_b128 v[174:177], v155
	ds_read_b128 v[178:181], v155 offset:1024
	ds_read_b128 v[182:185], v155 offset:2048
	ds_read_b128 v[186:189], v155 offset:3072
	s_add_u32 s36, s30, 0xfffc0080
	s_addc_u32 s37, s31, -1
	s_cmp_eq_u32 s65, 12
	s_cselect_b32 s39, s19, s37
	s_cselect_b32 s38, s51, s36
	s_cselect_b32 s37, s17, s64
	s_cselect_b32 s36, s62, s63
	v_lshl_add_u64 v[222:223], s[30:31], 0, v[146:147]
	s_add_i32 m0, s33, 0xc000
	ds_read_b128 v[190:193], v156
	ds_read_b128 v[194:197], v156 offset:1024
	ds_read_b128 v[198:201], v156 offset:2048
	ds_read_b128 v[202:205], v156 offset:3072
	ds_read_b128 v[206:209], v156 offset:4096
	ds_read_b128 v[210:213], v156 offset:5120
	ds_read_b128 v[214:217], v156 offset:6144
	ds_read_b128 v[218:221], v156 offset:7168
	global_load_lds_dwordx4 v[222:223], off
	v_lshl_add_u64 v[222:223], s[30:31], 0, v[148:149]
	s_add_i32 m0, s33, 0xe000
	s_nop 0
	global_load_lds_dwordx4 v[222:223], off
	s_waitcnt vmcnt(8)
	s_waitcnt lgkmcnt(0)
	s_setprio 1
	s_barrier
	v_mfma_f32_16x16x32_bf16 v[126:129], v[158:161], v[190:193], v[126:129]
	v_mfma_f32_16x16x32_bf16 v[122:125], v[166:169], v[190:193], v[122:125]
	v_mfma_f32_16x16x32_bf16 v[110:113], v[158:161], v[198:201], v[110:113]
	v_mfma_f32_16x16x32_bf16 v[106:109], v[166:169], v[198:201], v[106:109]
	v_mfma_f32_16x16x32_bf16 v[94:97], v[158:161], v[206:209], v[94:97]
	v_mfma_f32_16x16x32_bf16 v[90:93], v[166:169], v[206:209], v[90:93]
	v_mfma_f32_16x16x32_bf16 v[78:81], v[158:161], v[214:217], v[78:81]
	v_mfma_f32_16x16x32_bf16 v[74:77], v[166:169], v[214:217], v[74:77]
	v_mfma_f32_16x16x32_bf16 v[126:129], v[162:165], v[194:197], v[126:129]
	v_mfma_f32_16x16x32_bf16 v[122:125], v[170:173], v[194:197], v[122:125]
	v_mfma_f32_16x16x32_bf16 v[110:113], v[162:165], v[202:205], v[110:113]
	v_mfma_f32_16x16x32_bf16 v[106:109], v[170:173], v[202:205], v[106:109]
	v_mfma_f32_16x16x32_bf16 v[94:97], v[162:165], v[210:213], v[94:97]
	v_mfma_f32_16x16x32_bf16 v[90:93], v[170:173], v[210:213], v[90:93]
	v_mfma_f32_16x16x32_bf16 v[78:81], v[162:165], v[218:221], v[78:81]
	v_mfma_f32_16x16x32_bf16 v[74:77], v[170:173], v[218:221], v[74:77]
	v_mfma_f32_16x16x32_bf16 v[118:121], v[174:177], v[190:193], v[118:121]
	v_mfma_f32_16x16x32_bf16 v[114:117], v[182:185], v[190:193], v[114:117]
	v_mfma_f32_16x16x32_bf16 v[102:105], v[174:177], v[198:201], v[102:105]
	v_mfma_f32_16x16x32_bf16 v[98:101], v[182:185], v[198:201], v[98:101]
	v_mfma_f32_16x16x32_bf16 v[86:89], v[174:177], v[206:209], v[86:89]
	v_mfma_f32_16x16x32_bf16 v[82:85], v[182:185], v[206:209], v[82:85]
	v_mfma_f32_16x16x32_bf16 v[70:73], v[174:177], v[214:217], v[70:73]
	v_mfma_f32_16x16x32_bf16 v[66:69], v[182:185], v[214:217], v[66:69]
	v_mfma_f32_16x16x32_bf16 v[118:121], v[178:181], v[194:197], v[118:121]
	v_mfma_f32_16x16x32_bf16 v[114:117], v[186:189], v[194:197], v[114:117]
	v_mfma_f32_16x16x32_bf16 v[102:105], v[178:181], v[202:205], v[102:105]
	v_mfma_f32_16x16x32_bf16 v[98:101], v[186:189], v[202:205], v[98:101]
	v_mfma_f32_16x16x32_bf16 v[86:89], v[178:181], v[210:213], v[86:89]
	v_mfma_f32_16x16x32_bf16 v[82:85], v[186:189], v[210:213], v[82:85]
	v_mfma_f32_16x16x32_bf16 v[70:73], v[178:181], v[218:221], v[70:73]
	v_mfma_f32_16x16x32_bf16 v[66:69], v[186:189], v[218:221], v[66:69]
	s_barrier
	s_setprio 0
	s_add_i32 s66, s48, s4
	v_lshl_add_u64 v[222:223], s[36:37], 0, v[132:133]
	s_mov_b32 m0, s66
	ds_read_b128 v[190:193], v156 offset:16384
	ds_read_b128 v[194:197], v156 offset:17408
	ds_read_b128 v[198:201], v156 offset:18432
	ds_read_b128 v[202:205], v156 offset:19456
	ds_read_b128 v[206:209], v156 offset:20480
	ds_read_b128 v[210:213], v156 offset:21504
	ds_read_b128 v[214:217], v156 offset:22528
	ds_read_b128 v[218:221], v156 offset:23552
	global_load_lds_dwordx4 v[222:223], off
	s_add_i32 m0, s66, 0x2000
	s_add_u32 s66, s36, 0x40000
	v_lshl_add_u64 v[224:225], s[36:37], 0, v[136:137]
	s_addc_u32 s67, s37, 0
	s_add_i32 s68, s49, s4
	global_load_lds_dwordx4 v[224:225], off
	v_lshl_add_u64 v[226:227], s[66:67], 0, v[132:133]
	s_mov_b32 m0, s68
	v_lshl_add_u64 v[228:229], s[38:39], 0, v[134:135]
	global_load_lds_dwordx4 v[226:227], off
	v_lshl_add_u64 v[226:227], s[66:67], 0, v[136:137]
	s_add_i32 m0, s68, 0x2000
	s_nop 0
	global_load_lds_dwordx4 v[226:227], off
	v_lshl_add_u64 v[226:227], s[38:39], 0, v[130:131]
	s_mov_b32 m0, s33
	s_nop 0
	global_load_lds_dwordx4 v[226:227], off
	s_mov_b32 m0, s35
	s_nop 0
	global_load_lds_dwordx4 v[228:229], off
	s_waitcnt vmcnt(8)
	s_waitcnt lgkmcnt(0)
	s_setprio 1
	s_barrier
; #define PG8_STAGE(bufoff, gbase, voff) do { _Pragma("unroll") for (int _i = 0; _i < 2; ++_i) \
;         __builtin_amdgcn_global_load_lds((const unsigned*)((const char*)(gbase) + (voff)[_i]), (PG8_LAS unsigned*)(lds + (bufoff) + ldsw + _i * 8192), 16, 0, 0); } while (0)
; #define PG8_LDA(dst, b, h) do { _Pragma("unroll") for (int m = 0; m < 4; ++m) _Pragma("unroll") for (int k = 0; k < 2; ++k) dst[m][k] = *(const PG8_LAS bf16x8*)(lds + PG8_SA(b, h) + aoff + m * 2048 + k * 1024); } while (0)
; #define PG8_LDB(dst, b, h) do { _Pragma("unroll") for (int n = 0; n < 2; ++n) _Pragma("unroll") for (int k = 0; k < 2; ++k) dst[n][k] = *(const PG8_LAS bf16x8*)(lds + PG8_SB(b, h) + boff + n * 2048 + k * 1024); } while (0)
; #define PG8_MMA(ai, bj, At, Bt) do { __builtin_amdgcn_s_setprio(1); _Pragma("unroll") for (int m = 0; m < 4; ++m) _Pragma("unroll") for (int n = 0; n < 2; ++n) _Pragma("unroll") for (int k = 0; k < 2; ++k) \
;         acc[ai][bj][m][n] = __builtin_amdgcn_mfma_f32_16x16x32_bf16(Bt[n][k], At[m][k], acc[ai][bj][m][n], 0, 0, 0); __builtin_amdgcn_s_setprio(0); } while (0)
; #define PG8_WAIT_V(n) asm volatile("s_waitcnt vmcnt(" #n ")" ::: "memory")
; template <class Epi, class Sched, bool ALIGN_EPI = false, bool SP2 = false>
; __device__ __forceinline__ void gemm_phase(PG8_LAS unsigned char* lds, const Gemm g, const Sched& S, const Epi& E) {
;     ...
;             PG8_LDB(B0, 0, 0); PG8_LDB(B1, 0, 1); PG8_SCHED; PG8_LDA(At, 0, 0); PG8_STAGE(PG8_SA(1, 1), a1 + hstepA, voffA);
;             PG8_WAIT_V(8); PG8_WAIT_L(0); PG8_BAR; PG8_MMA(0, 0, At, B0); PG8_MMA(0, 1, At, B1); PG8_BAR; PG8_SCHED;
;             PG8_LDA(At, 0, 1); PG8_STAGE(PG8_SB(0, 0), b2, voffB); PG8_STAGE(PG8_SB(0, 1), b2 + hstepB, voffB); PG8_STAGE(PG8_SA(0, 0), a2, voffA);
;             PG8_WAIT_V(8); PG8_WAIT_L(0); PG8_BAR; PG8_MMA(1, 0, At, B0); PG8_MMA(1, 1, At, B1); PG8_BAR; PG8_SCHED;
;             PG8_LDB(B0, 1, 0); PG8_LDB(B1, 1, 1); PG8_SCHED; PG8_LDA(At, 1, 0); PG8_STAGE(PG8_SA(0, 1), a2 + hstepA, voffA);
;             PG8_WAIT_V(8); PG8_WAIT_L(0); PG8_BAR; PG8_MMA(0, 0, At, B0); PG8_MMA(0, 1, At, B1); PG8_BAR; PG8_SCHED;
;             PG8_LDA(At, 1, 1); PG8_STAGE(PG8_SB(1, 0), b3, voffB); PG8_STAGE(PG8_SB(1, 1), b3 + hstepB, voffB); PG8_STAGE(PG8_SA(1, 0), a3, voffA);
;             PG8_WAIT_V(8); PG8_WAIT_L(0); PG8_BAR; PG8_MMA(1, 0, At, B0); PG8_MMA(1, 1, At, B1); PG8_BAR; PG8_SCHED;
	v_mfma_f32_16x16x32_bf16 v[62:65], v[158:161], v[190:193], v[62:65]
	v_mfma_f32_16x16x32_bf16 v[58:61], v[166:169], v[190:193], v[58:61]
	v_mfma_f32_16x16x32_bf16 v[46:49], v[158:161], v[198:201], v[46:49]
	v_mfma_f32_16x16x32_bf16 v[42:45], v[166:169], v[198:201], v[42:45]
	v_mfma_f32_16x16x32_bf16 v[30:33], v[158:161], v[206:209], v[30:33]
	v_mfma_f32_16x16x32_bf16 v[26:29], v[166:169], v[206:209], v[26:29]
	v_mfma_f32_16x16x32_bf16 v[14:17], v[158:161], v[214:217], v[14:17]
	v_mfma_f32_16x16x32_bf16 v[10:13], v[166:169], v[214:217], v[10:13]
	v_mfma_f32_16x16x32_bf16 v[62:65], v[162:165], v[194:197], v[62:65]
	v_mfma_f32_16x16x32_bf16 v[58:61], v[170:173], v[194:197], v[58:61]
	v_mfma_f32_16x16x32_bf16 v[46:49], v[162:165], v[202:205], v[46:49]
	v_mfma_f32_16x16x32_bf16 v[42:45], v[170:173], v[202:205], v[42:45]
	v_mfma_f32_16x16x32_bf16 v[30:33], v[162:165], v[210:213], v[30:33]
	v_mfma_f32_16x16x32_bf16 v[26:29], v[170:173], v[210:213], v[26:29]
	v_mfma_f32_16x16x32_bf16 v[14:17], v[162:165], v[218:221], v[14:17]
	v_mfma_f32_16x16x32_bf16 v[10:13], v[170:173], v[218:221], v[10:13]
	v_mfma_f32_16x16x32_bf16 v[54:57], v[174:177], v[190:193], v[54:57]
	v_mfma_f32_16x16x32_bf16 v[50:53], v[182:185], v[190:193], v[50:53]
	v_mfma_f32_16x16x32_bf16 v[38:41], v[174:177], v[198:201], v[38:41]
	v_mfma_f32_16x16x32_bf16 v[34:37], v[182:185], v[198:201], v[34:37]
	v_mfma_f32_16x16x32_bf16 v[22:25], v[174:177], v[206:209], v[22:25]
	v_mfma_f32_16x16x32_bf16 v[18:21], v[182:185], v[206:209], v[18:21]
	v_mfma_f32_16x16x32_bf16 v[6:9], v[174:177], v[214:217], v[6:9]
	v_mfma_f32_16x16x32_bf16 v[2:5], v[182:185], v[214:217], v[2:5]
	v_mfma_f32_16x16x32_bf16 v[54:57], v[178:181], v[194:197], v[54:57]
	v_mfma_f32_16x16x32_bf16 v[50:53], v[186:189], v[194:197], v[50:53]
	v_mfma_f32_16x16x32_bf16 v[38:41], v[178:181], v[202:205], v[38:41]
	v_mfma_f32_16x16x32_bf16 v[34:37], v[186:189], v[202:205], v[34:37]
	v_mfma_f32_16x16x32_bf16 v[22:25], v[178:181], v[210:213], v[22:25]
	v_mfma_f32_16x16x32_bf16 v[18:21], v[186:189], v[210:213], v[18:21]
	v_mfma_f32_16x16x32_bf16 v[6:9], v[178:181], v[218:221], v[6:9]
	v_mfma_f32_16x16x32_bf16 v[2:5], v[186:189], v[218:221], v[2:5]
	s_barrier
	s_setprio 0
	s_add_i32 s66, 0, 0x18000
	v_add_u32_e32 v157, s66, v1
	s_add_i32 s67, 0, 0x1c000
	ds_read_b128 v[158:161], v157
	ds_read_b128 v[162:165], v157 offset:1024
	ds_read_b128 v[166:169], v157 offset:2048
	ds_read_b128 v[170:173], v157 offset:3072
	v_add_u32_e32 v157, s67, v1
	ds_read_b128 v[174:177], v157
	ds_read_b128 v[178:181], v157 offset:1024
	ds_read_b128 v[182:185], v157 offset:2048
	ds_read_b128 v[186:189], v157 offset:3072
	s_add_u32 s38, s38, 0x40000
	s_addc_u32 s39, s39, 0
	s_mov_b32 m0, s40
	v_lshl_add_u64 v[230:231], s[38:39], 0, v[130:131]
	ds_read_b128 v[190:193], v156 offset:32768
	ds_read_b128 v[194:197], v156 offset:33792
	ds_read_b128 v[198:201], v156 offset:34816
	ds_read_b128 v[202:205], v156 offset:35840
	ds_read_b128 v[206:209], v156 offset:36864
	ds_read_b128 v[210:213], v156 offset:37888
	ds_read_b128 v[214:217], v156 offset:38912
	ds_read_b128 v[218:221], v156 offset:39936
	global_load_lds_dwordx4 v[230:231], off
	v_lshl_add_u64 v[230:231], s[38:39], 0, v[134:135]
	s_mov_b32 m0, s41
	s_nop 0
	global_load_lds_dwordx4 v[230:231], off
	s_waitcnt vmcnt(8)
	s_waitcnt lgkmcnt(0)
	s_setprio 1
	s_barrier
	v_mfma_f32_16x16x32_bf16 v[126:129], v[158:161], v[190:193], v[126:129]
	v_mfma_f32_16x16x32_bf16 v[122:125], v[166:169], v[190:193], v[122:125]
	v_mfma_f32_16x16x32_bf16 v[110:113], v[158:161], v[198:201], v[110:113]
	v_mfma_f32_16x16x32_bf16 v[106:109], v[166:169], v[198:201], v[106:109]
	v_mfma_f32_16x16x32_bf16 v[94:97], v[158:161], v[206:209], v[94:97]
	v_mfma_f32_16x16x32_bf16 v[90:93], v[166:169], v[206:209], v[90:93]
	v_mfma_f32_16x16x32_bf16 v[78:81], v[158:161], v[214:217], v[78:81]
	v_mfma_f32_16x16x32_bf16 v[74:77], v[166:169], v[214:217], v[74:77]
	v_mfma_f32_16x16x32_bf16 v[126:129], v[162:165], v[194:197], v[126:129]
	v_mfma_f32_16x16x32_bf16 v[122:125], v[170:173], v[194:197], v[122:125]
	v_mfma_f32_16x16x32_bf16 v[110:113], v[162:165], v[202:205], v[110:113]
	v_mfma_f32_16x16x32_bf16 v[106:109], v[170:173], v[202:205], v[106:109]
	v_mfma_f32_16x16x32_bf16 v[94:97], v[162:165], v[210:213], v[94:97]
	v_mfma_f32_16x16x32_bf16 v[90:93], v[170:173], v[210:213], v[90:93]
	v_mfma_f32_16x16x32_bf16 v[78:81], v[162:165], v[218:221], v[78:81]
	v_mfma_f32_16x16x32_bf16 v[74:77], v[170:173], v[218:221], v[74:77]
	v_mfma_f32_16x16x32_bf16 v[118:121], v[174:177], v[190:193], v[118:121]
	v_mfma_f32_16x16x32_bf16 v[114:117], v[182:185], v[190:193], v[114:117]
	v_mfma_f32_16x16x32_bf16 v[102:105], v[174:177], v[198:201], v[102:105]
	v_mfma_f32_16x16x32_bf16 v[98:101], v[182:185], v[198:201], v[98:101]
	v_mfma_f32_16x16x32_bf16 v[86:89], v[174:177], v[206:209], v[86:89]
	v_mfma_f32_16x16x32_bf16 v[82:85], v[182:185], v[206:209], v[82:85]
	v_mfma_f32_16x16x32_bf16 v[70:73], v[174:177], v[214:217], v[70:73]
	v_mfma_f32_16x16x32_bf16 v[66:69], v[182:185], v[214:217], v[66:69]
	v_mfma_f32_16x16x32_bf16 v[118:121], v[178:181], v[194:197], v[118:121]
	v_mfma_f32_16x16x32_bf16 v[114:117], v[186:189], v[194:197], v[114:117]
	v_mfma_f32_16x16x32_bf16 v[102:105], v[178:181], v[202:205], v[102:105]
	v_mfma_f32_16x16x32_bf16 v[98:101], v[186:189], v[202:205], v[98:101]
	v_mfma_f32_16x16x32_bf16 v[86:89], v[178:181], v[210:213], v[86:89]
	v_mfma_f32_16x16x32_bf16 v[82:85], v[186:189], v[210:213], v[82:85]
	v_mfma_f32_16x16x32_bf16 v[70:73], v[178:181], v[218:221], v[70:73]
	v_mfma_f32_16x16x32_bf16 v[66:69], v[186:189], v[218:221], v[66:69]
	s_barrier
; #define PG8_STAGE(bufoff, gbase, voff) do { _Pragma("unroll") for (int _i = 0; _i < 2; ++_i) \
;         __builtin_amdgcn_global_load_lds((const unsigned*)((const char*)(gbase) + (voff)[_i]), (PG8_LAS unsigned*)(lds + (bufoff) + ldsw + _i * 8192), 16, 0, 0); } while (0)
; #define PG8_LDA(dst, b, h) do { _Pragma("unroll") for (int m = 0; m < 4; ++m) _Pragma("unroll") for (int k = 0; k < 2; ++k) dst[m][k] = *(const PG8_LAS bf16x8*)(lds + PG8_SA(b, h) + aoff + m * 2048 + k * 1024); } while (0)
; #define PG8_LDB(dst, b, h) do { _Pragma("unroll") for (int n = 0; n < 2; ++n) _Pragma("unroll") for (int k = 0; k < 2; ++k) dst[n][k] = *(const PG8_LAS bf16x8*)(lds + PG8_SB(b, h) + boff + n * 2048 + k * 1024); } while (0)
; #define PG8_MMA(ai, bj, At, Bt) do { __builtin_amdgcn_s_setprio(1); _Pragma("unroll") for (int m = 0; m < 4; ++m) _Pragma("unroll") for (int n = 0; n < 2; ++n) _Pragma("unroll") for (int k = 0; k < 2; ++k) \
;         acc[ai][bj][m][n] = __builtin_amdgcn_mfma_f32_16x16x32_bf16(Bt[n][k], At[m][k], acc[ai][bj][m][n], 0, 0, 0); __builtin_amdgcn_s_setprio(0); } while (0)
; #define PG8_WAIT_V(n) asm volatile("s_waitcnt vmcnt(" #n ")" ::: "memory")
; template <class Epi, class Sched, bool ALIGN_EPI = false, bool SP2 = false>
; __device__ __forceinline__ void gemm_phase(PG8_LAS unsigned char* lds, const Gemm g, const Sched& S, const Epi& E) {
;     ...
;             PG8_LDB(B0, 0, 0); PG8_LDB(B1, 0, 1); PG8_SCHED; PG8_LDA(At, 0, 0); PG8_STAGE(PG8_SA(1, 1), a1 + hstepA, voffA);
;             PG8_WAIT_V(8); PG8_WAIT_L(0); PG8_BAR; PG8_MMA(0, 0, At, B0); PG8_MMA(0, 1, At, B1); PG8_BAR; PG8_SCHED;
;             PG8_LDA(At, 0, 1); PG8_STAGE(PG8_SB(0, 0), b2, voffB); PG8_STAGE(PG8_SB(0, 1), b2 + hstepB, voffB); PG8_STAGE(PG8_SA(0, 0), a2, voffA);
;             PG8_WAIT_V(8); PG8_WAIT_L(0); PG8_BAR; PG8_MMA(1, 0, At, B0); PG8_MMA(1, 1, At, B1); PG8_BAR; PG8_SCHED;
;             PG8_LDB(B0, 1, 0); PG8_LDB(B1, 1, 1); PG8_SCHED; PG8_LDA(At, 1, 0); PG8_STAGE(PG8_SA(0, 1), a2 + hstepA, voffA);
;             PG8_WAIT_V(8); PG8_WAIT_L(0); PG8_BAR; PG8_MMA(0, 0, At, B0); PG8_MMA(0, 1, At, B1); PG8_BAR; PG8_SCHED;
;             PG8_LDA(At, 1, 1); PG8_STAGE(PG8_SB(1, 0), b3, voffB); PG8_STAGE(PG8_SB(1, 1), b3 + hstepB, voffB); PG8_STAGE(PG8_SA(1, 0), a3, voffA);
;             PG8_WAIT_V(8); PG8_WAIT_L(0); PG8_BAR; PG8_MMA(1, 0, At, B0); PG8_MMA(1, 1, At, B1); PG8_BAR; PG8_SCHED;
	s_setprio 0
	s_add_i32 s38, s66, s4
	v_lshl_add_u64 v[222:223], v[222:223], 0, s[8:9]
	s_mov_b32 m0, s38
	ds_read_b128 v[190:193], v156 offset:49152
	ds_read_b128 v[194:197], v156 offset:50176
	ds_read_b128 v[198:201], v156 offset:51200
	ds_read_b128 v[202:205], v156 offset:52224
	ds_read_b128 v[206:209], v156 offset:53248
	ds_read_b128 v[210:213], v156 offset:54272
	ds_read_b128 v[214:217], v156 offset:55296
	ds_read_b128 v[218:221], v156 offset:56320
	global_load_lds_dwordx4 v[222:223], off
	s_add_i32 m0, s38, 0x2000
	s_add_u32 s36, s36, 0x40080
	v_lshl_add_u64 v[222:223], v[224:225], 0, s[8:9]
	s_addc_u32 s37, s37, 0
	s_add_i32 s38, s67, s4
	global_load_lds_dwordx4 v[222:223], off
	v_lshl_add_u64 v[222:223], s[36:37], 0, v[132:133]
	s_mov_b32 m0, s38
	s_nop 0
	global_load_lds_dwordx4 v[222:223], off
	v_lshl_add_u64 v[222:223], s[36:37], 0, v[136:137]
	s_add_i32 m0, s38, 0x2000
	s_nop 0
	global_load_lds_dwordx4 v[222:223], off
	v_lshl_add_u64 v[222:223], v[226:227], 0, s[8:9]
	s_mov_b32 m0, s45
	s_nop 0
	global_load_lds_dwordx4 v[222:223], off
	v_lshl_add_u64 v[222:223], v[228:229], 0, s[8:9]
	s_mov_b32 m0, s46
	s_nop 0
	global_load_lds_dwordx4 v[222:223], off
	s_waitcnt vmcnt(8)
	s_waitcnt lgkmcnt(0)
	s_setprio 1
	s_barrier
	v_mfma_f32_16x16x32_bf16 v[62:65], v[158:161], v[190:193], v[62:65]
	v_mfma_f32_16x16x32_bf16 v[58:61], v[166:169], v[190:193], v[58:61]
	v_mfma_f32_16x16x32_bf16 v[46:49], v[158:161], v[198:201], v[46:49]
	v_mfma_f32_16x16x32_bf16 v[42:45], v[166:169], v[198:201], v[42:45]
	v_mfma_f32_16x16x32_bf16 v[30:33], v[158:161], v[206:209], v[30:33]
	v_mfma_f32_16x16x32_bf16 v[26:29], v[166:169], v[206:209], v[26:29]
	v_mfma_f32_16x16x32_bf16 v[14:17], v[158:161], v[214:217], v[14:17]
	v_mfma_f32_16x16x32_bf16 v[10:13], v[166:169], v[214:217], v[10:13]
	v_mfma_f32_16x16x32_bf16 v[62:65], v[162:165], v[194:197], v[62:65]
	v_mfma_f32_16x16x32_bf16 v[58:61], v[170:173], v[194:197], v[58:61]
	v_mfma_f32_16x16x32_bf16 v[46:49], v[162:165], v[202:205], v[46:49]
	v_mfma_f32_16x16x32_bf16 v[42:45], v[170:173], v[202:205], v[42:45]
	v_mfma_f32_16x16x32_bf16 v[30:33], v[162:165], v[210:213], v[30:33]
	v_mfma_f32_16x16x32_bf16 v[26:29], v[170:173], v[210:213], v[26:29]
	v_mfma_f32_16x16x32_bf16 v[14:17], v[162:165], v[218:221], v[14:17]
	v_mfma_f32_16x16x32_bf16 v[10:13], v[170:173], v[218:221], v[10:13]
	v_mfma_f32_16x16x32_bf16 v[54:57], v[174:177], v[190:193], v[54:57]
	v_mfma_f32_16x16x32_bf16 v[50:53], v[182:185], v[190:193], v[50:53]
	v_mfma_f32_16x16x32_bf16 v[38:41], v[174:177], v[198:201], v[38:41]
	v_mfma_f32_16x16x32_bf16 v[34:37], v[182:185], v[198:201], v[34:37]
	v_mfma_f32_16x16x32_bf16 v[22:25], v[174:177], v[206:209], v[22:25]
	v_mfma_f32_16x16x32_bf16 v[18:21], v[182:185], v[206:209], v[18:21]
	v_mfma_f32_16x16x32_bf16 v[6:9], v[174:177], v[214:217], v[6:9]
	v_mfma_f32_16x16x32_bf16 v[2:5], v[182:185], v[214:217], v[2:5]
	v_mfma_f32_16x16x32_bf16 v[54:57], v[178:181], v[194:197], v[54:57]
	v_mfma_f32_16x16x32_bf16 v[50:53], v[186:189], v[194:197], v[50:53]
	v_mfma_f32_16x16x32_bf16 v[38:41], v[178:181], v[202:205], v[38:41]
	v_mfma_f32_16x16x32_bf16 v[34:37], v[186:189], v[202:205], v[34:37]
	v_mfma_f32_16x16x32_bf16 v[22:25], v[178:181], v[210:213], v[22:25]
	v_mfma_f32_16x16x32_bf16 v[18:21], v[186:189], v[210:213], v[18:21]
	v_mfma_f32_16x16x32_bf16 v[6:9], v[178:181], v[218:221], v[6:9]
	v_mfma_f32_16x16x32_bf16 v[2:5], v[186:189], v[218:221], v[2:5]
	s_barrier
	s_setprio 0
	s_add_i32 s65, s65, 2
	s_add_u32 s30, s30, 0x100
	s_addc_u32 s31, s31, 0
	s_add_u32 s63, s63, 0x100
	s_addc_u32 s64, s64, 0
	s_cmp_gt_u32 s65, 13
	s_cbranch_scc0 .LBB0_1244
	s_and_b64 vcc, exec, s[10:11]
	s_cbranch_vccz .LBB0_1247
	s_barrier

; #define PG8_STAGE(bufoff, gbase, voff) do { _Pragma("unroll") for (int _i = 0; _i < 2; ++_i) \
;         __builtin_amdgcn_global_load_lds((const unsigned*)((const char*)(gbase) + (voff)[_i]), (PG8_LAS unsigned*)(lds + (bufoff) + ldsw + _i * 8192), 16, 0, 0); } while (0)
; #define PG8_LDA(dst, b, h) do { _Pragma("unroll") for (int m = 0; m < 4; ++m) _Pragma("unroll") for (int k = 0; k < 2; ++k) dst[m][k] = *(const PG8_LAS bf16x8*)(lds + PG8_SA(b, h) + aoff + m * 2048 + k * 1024); } while (0)
; #define PG8_LDB(dst, b, h) do { _Pragma("unroll") for (int n = 0; n < 2; ++n) _Pragma("unroll") for (int k = 0; k < 2; ++k) dst[n][k] = *(const PG8_LAS bf16x8*)(lds + PG8_SB(b, h) + boff + n * 2048 + k * 1024); } while (0)
; #define PG8_MMA(ai, bj, At, Bt) do { __builtin_amdgcn_s_setprio(1); _Pragma("unroll") for (int m = 0; m < 4; ++m) _Pragma("unroll") for (int n = 0; n < 2; ++n) _Pragma("unroll") for (int k = 0; k < 2; ++k) \
;         acc[ai][bj][m][n] = __builtin_amdgcn_mfma_f32_16x16x32_bf16(Bt[n][k], At[m][k], acc[ai][bj][m][n], 0, 0, 0); __builtin_amdgcn_s_setprio(0); } while (0)
; #define PG8_WAIT_V(n) asm volatile("s_waitcnt vmcnt(" #n ")" ::: "memory")
; template <class Epi, class Sched, bool ALIGN_EPI = false, bool SP2 = false>
; __device__ __forceinline__ void gemm_phase(PG8_LAS unsigned char* lds, const Gemm g, const Sched& S, const Epi& E) {
;     ...
;             PG8_LDB(B0, 0, 0); PG8_LDB(B1, 0, 1); PG8_SCHED; PG8_LDA(At, 0, 0); PG8_STAGE(PG8_SA(1, 1), a1 + hstepA, voffA);
;             PG8_WAIT_V(8); PG8_WAIT_L(0); PG8_BAR; PG8_MMA(0, 0, At, B0); PG8_MMA(0, 1, At, B1); PG8_BAR; PG8_SCHED;
;             PG8_LDA(At, 0, 1); PG8_STAGE(PG8_SB(0, 0), b2, voffB); PG8_STAGE(PG8_SB(0, 1), b2 + hstepB, voffB); PG8_STAGE(PG8_SA(0, 0), a2, voffA);
;             PG8_WAIT_V(8); PG8_WAIT_L(0); PG8_BAR; PG8_MMA(1, 0, At, B0); PG8_MMA(1, 1, At, B1); PG8_BAR; PG8_SCHED;
;             PG8_LDB(B0, 1, 0); PG8_LDB(B1, 1, 1); PG8_SCHED; PG8_LDA(At, 1, 0); PG8_STAGE(PG8_SA(0, 1), a2 + hstepA, voffA);
;             PG8_WAIT_V(8); PG8_WAIT_L(0); PG8_BAR; PG8_MMA(0, 0, At, B0); PG8_MMA(0, 1, At, B1); PG8_BAR; PG8_SCHED;
;             PG8_LDA(At, 1, 1); PG8_STAGE(PG8_SB(1, 0), b3, voffB); PG8_STAGE(PG8_SB(1, 1), b3 + hstepB, voffB); PG8_STAGE(PG8_SA(1, 0), a3, voffA);
;             PG8_WAIT_V(8); PG8_WAIT_L(0); PG8_BAR; PG8_MMA(1, 0, At, B0); PG8_MMA(1, 1, At, B1); PG8_BAR; PG8_SCHED;
.LBB0_1339:
	v_add_u32_e32 v153, s56, v151
	ds_read_b128 v[154:157], v153
	ds_read_b128 v[158:161], v153 offset:1024
	ds_read_b128 v[162:165], v153 offset:2048
	ds_read_b128 v[166:169], v153 offset:3072
	v_add_u32_e32 v153, s57, v151
	ds_read_b128 v[172:175], v153
	ds_read_b128 v[176:179], v153 offset:1024
	ds_read_b128 v[180:183], v153 offset:2048
	ds_read_b128 v[184:187], v153 offset:3072
	s_add_u32 s38, s14, s36
	s_addc_u32 s39, s15, s37
	s_cmp_eq_u32 s65, 60
	s_cselect_b32 s42, s59, s38
	s_cselect_b32 s43, s25, s39
	s_cselect_b32 s40, s62, s63
	s_cselect_b32 s41, s23, s64
	s_add_u32 s38, s42, 0x8000
	s_addc_u32 s39, s43, 0
	v_lshl_add_u64 v[220:221], s[14:15], 0, v[148:149]
	s_add_i32 m0, s45, 0xc000
	ds_read_b128 v[188:191], v152
	ds_read_b128 v[192:195], v152 offset:1024
	ds_read_b128 v[196:199], v152 offset:2048
	ds_read_b128 v[200:203], v152 offset:3072
	ds_read_b128 v[204:207], v152 offset:4096
	ds_read_b128 v[208:211], v152 offset:5120
	ds_read_b128 v[212:215], v152 offset:6144
	ds_read_b128 v[216:219], v152 offset:7168
	global_load_lds_dwordx4 v[220:221], off
	v_lshl_add_u64 v[220:221], s[14:15], 0, v[146:147]
	s_add_i32 m0, s45, 0xe000
	s_nop 0
	global_load_lds_dwordx4 v[220:221], off
	s_waitcnt vmcnt(8)
	s_waitcnt lgkmcnt(0)
	s_setprio 1
	s_barrier
	v_mfma_f32_16x16x32_bf16 v[122:125], v[154:157], v[188:191], v[122:125]
	v_mfma_f32_16x16x32_bf16 v[126:129], v[162:165], v[188:191], v[126:129]
	v_mfma_f32_16x16x32_bf16 v[118:121], v[154:157], v[196:199], v[118:121]
	v_mfma_f32_16x16x32_bf16 v[106:109], v[162:165], v[196:199], v[106:109]
	v_mfma_f32_16x16x32_bf16 v[98:101], v[154:157], v[204:207], v[98:101]
	v_mfma_f32_16x16x32_bf16 v[90:93], v[162:165], v[204:207], v[90:93]
	v_mfma_f32_16x16x32_bf16 v[110:113], v[154:157], v[212:215], v[110:113]
	v_mfma_f32_16x16x32_bf16 v[82:85], v[162:165], v[212:215], v[82:85]
	v_mfma_f32_16x16x32_bf16 v[122:125], v[158:161], v[192:195], v[122:125]
	v_mfma_f32_16x16x32_bf16 v[126:129], v[166:169], v[192:195], v[126:129]
	v_mfma_f32_16x16x32_bf16 v[118:121], v[158:161], v[200:203], v[118:121]
	v_mfma_f32_16x16x32_bf16 v[106:109], v[166:169], v[200:203], v[106:109]
	v_mfma_f32_16x16x32_bf16 v[98:101], v[158:161], v[208:211], v[98:101]
	v_mfma_f32_16x16x32_bf16 v[90:93], v[166:169], v[208:211], v[90:93]
	v_mfma_f32_16x16x32_bf16 v[110:113], v[158:161], v[216:219], v[110:113]
	v_mfma_f32_16x16x32_bf16 v[82:85], v[166:169], v[216:219], v[82:85]
	v_mfma_f32_16x16x32_bf16 v[114:117], v[172:175], v[188:191], v[114:117]
	v_mfma_f32_16x16x32_bf16 v[102:105], v[180:183], v[188:191], v[102:105]
	v_mfma_f32_16x16x32_bf16 v[94:97], v[172:175], v[196:199], v[94:97]
	v_mfma_f32_16x16x32_bf16 v[86:89], v[180:183], v[196:199], v[86:89]
	v_mfma_f32_16x16x32_bf16 v[78:81], v[172:175], v[204:207], v[78:81]
	v_mfma_f32_16x16x32_bf16 v[70:73], v[180:183], v[204:207], v[70:73]
	v_mfma_f32_16x16x32_bf16 v[66:69], v[172:175], v[212:215], v[66:69]
	v_mfma_f32_16x16x32_bf16 v[74:77], v[180:183], v[212:215], v[74:77]
	v_mfma_f32_16x16x32_bf16 v[114:117], v[176:179], v[192:195], v[114:117]
	v_mfma_f32_16x16x32_bf16 v[102:105], v[184:187], v[192:195], v[102:105]
	v_mfma_f32_16x16x32_bf16 v[94:97], v[176:179], v[200:203], v[94:97]
	v_mfma_f32_16x16x32_bf16 v[86:89], v[184:187], v[200:203], v[86:89]
	v_mfma_f32_16x16x32_bf16 v[78:81], v[176:179], v[208:211], v[78:81]
	v_mfma_f32_16x16x32_bf16 v[70:73], v[184:187], v[208:211], v[70:73]
	v_mfma_f32_16x16x32_bf16 v[66:69], v[176:179], v[216:219], v[66:69]
	v_mfma_f32_16x16x32_bf16 v[74:77], v[184:187], v[216:219], v[74:77]
	s_barrier
	s_setprio 0
	s_add_i32 s66, s56, s44
	v_lshl_add_u64 v[220:221], s[40:41], 0, v[132:133]
	s_mov_b32 m0, s66
	ds_read_b128 v[188:191], v152 offset:16384
	ds_read_b128 v[192:195], v152 offset:17408
	ds_read_b128 v[196:199], v152 offset:18432
	ds_read_b128 v[200:203], v152 offset:19456
	ds_read_b128 v[204:207], v152 offset:20480
	ds_read_b128 v[208:211], v152 offset:21504
	ds_read_b128 v[212:215], v152 offset:22528
	ds_read_b128 v[216:219], v152 offset:23552
	global_load_lds_dwordx4 v[220:221], off
	s_add_i32 m0, s66, 0x2000
	s_add_u32 s66, s40, 0x100000
	v_lshl_add_u64 v[222:223], s[40:41], 0, v[136:137]
	s_addc_u32 s67, s41, 0
	s_add_i32 s68, s57, s44
	global_load_lds_dwordx4 v[222:223], off
	v_lshl_add_u64 v[224:225], s[66:67], 0, v[132:133]
	s_mov_b32 m0, s68
	s_nop 0
	global_load_lds_dwordx4 v[224:225], off
	v_lshl_add_u64 v[224:225], s[66:67], 0, v[136:137]
	s_add_i32 m0, s68, 0x2000
	s_nop 0
	global_load_lds_dwordx4 v[224:225], off
	v_lshl_add_u64 v[224:225], s[42:43], 0, v[130:131]
	s_mov_b32 m0, s45
	s_nop 0
	global_load_lds_dwordx4 v[224:225], off
	v_lshl_add_u64 v[224:225], s[42:43], 0, v[134:135]
	s_mov_b32 m0, s46
	s_nop 0
	global_load_lds_dwordx4 v[224:225], off
	s_waitcnt vmcnt(8)
	s_waitcnt lgkmcnt(0)
	s_setprio 1
	s_barrier
; #define PG8_STAGE(bufoff, gbase, voff) do { _Pragma("unroll") for (int _i = 0; _i < 2; ++_i) \
;         __builtin_amdgcn_global_load_lds((const unsigned*)((const char*)(gbase) + (voff)[_i]), (PG8_LAS unsigned*)(lds + (bufoff) + ldsw + _i * 8192), 16, 0, 0); } while (0)
; #define PG8_LDA(dst, b, h) do { _Pragma("unroll") for (int m = 0; m < 4; ++m) _Pragma("unroll") for (int k = 0; k < 2; ++k) dst[m][k] = *(const PG8_LAS bf16x8*)(lds + PG8_SA(b, h) + aoff + m * 2048 + k * 1024); } while (0)
; #define PG8_LDB(dst, b, h) do { _Pragma("unroll") for (int n = 0; n < 2; ++n) _Pragma("unroll") for (int k = 0; k < 2; ++k) dst[n][k] = *(const PG8_LAS bf16x8*)(lds + PG8_SB(b, h) + boff + n * 2048 + k * 1024); } while (0)
; #define PG8_MMA(ai, bj, At, Bt) do { __builtin_amdgcn_s_setprio(1); _Pragma("unroll") for (int m = 0; m < 4; ++m) _Pragma("unroll") for (int n = 0; n < 2; ++n) _Pragma("unroll") for (int k = 0; k < 2; ++k) \
;         acc[ai][bj][m][n] = __builtin_amdgcn_mfma_f32_16x16x32_bf16(Bt[n][k], At[m][k], acc[ai][bj][m][n], 0, 0, 0); __builtin_amdgcn_s_setprio(0); } while (0)
; #define PG8_WAIT_V(n) asm volatile("s_waitcnt vmcnt(" #n ")" ::: "memory")
; template <class Epi, class Sched, bool ALIGN_EPI = false, bool SP2 = false>
; __device__ __forceinline__ void gemm_phase(PG8_LAS unsigned char* lds, const Gemm g, const Sched& S, const Epi& E) {
;     ...
;             PG8_LDB(B0, 0, 0); PG8_LDB(B1, 0, 1); PG8_SCHED; PG8_LDA(At, 0, 0); PG8_STAGE(PG8_SA(1, 1), a1 + hstepA, voffA);
;             PG8_WAIT_V(8); PG8_WAIT_L(0); PG8_BAR; PG8_MMA(0, 0, At, B0); PG8_MMA(0, 1, At, B1); PG8_BAR; PG8_SCHED;
;             PG8_LDA(At, 0, 1); PG8_STAGE(PG8_SB(0, 0), b2, voffB); PG8_STAGE(PG8_SB(0, 1), b2 + hstepB, voffB); PG8_STAGE(PG8_SA(0, 0), a2, voffA);
;             PG8_WAIT_V(8); PG8_WAIT_L(0); PG8_BAR; PG8_MMA(1, 0, At, B0); PG8_MMA(1, 1, At, B1); PG8_BAR; PG8_SCHED;
;             PG8_LDB(B0, 1, 0); PG8_LDB(B1, 1, 1); PG8_SCHED; PG8_LDA(At, 1, 0); PG8_STAGE(PG8_SA(0, 1), a2 + hstepA, voffA);
;             PG8_WAIT_V(8); PG8_WAIT_L(0); PG8_BAR; PG8_MMA(0, 0, At, B0); PG8_MMA(0, 1, At, B1); PG8_BAR; PG8_SCHED;
;             PG8_LDA(At, 1, 1); PG8_STAGE(PG8_SB(1, 0), b3, voffB); PG8_STAGE(PG8_SB(1, 1), b3 + hstepB, voffB); PG8_STAGE(PG8_SA(1, 0), a3, voffA);
;             PG8_WAIT_V(8); PG8_WAIT_L(0); PG8_BAR; PG8_MMA(1, 0, At, B0); PG8_MMA(1, 1, At, B1); PG8_BAR; PG8_SCHED;
	v_mfma_f32_16x16x32_bf16 v[62:65], v[154:157], v[188:191], v[62:65]
	v_mfma_f32_16x16x32_bf16 v[58:61], v[162:165], v[188:191], v[58:61]
	v_mfma_f32_16x16x32_bf16 v[54:57], v[154:157], v[196:199], v[54:57]
	v_mfma_f32_16x16x32_bf16 v[46:49], v[162:165], v[196:199], v[46:49]
	v_mfma_f32_16x16x32_bf16 v[38:41], v[154:157], v[204:207], v[38:41]
	v_mfma_f32_16x16x32_bf16 v[30:33], v[162:165], v[204:207], v[30:33]
	v_mfma_f32_16x16x32_bf16 v[14:17], v[154:157], v[212:215], v[14:17]
	v_mfma_f32_16x16x32_bf16 v[10:13], v[162:165], v[212:215], v[10:13]
	v_mfma_f32_16x16x32_bf16 v[62:65], v[158:161], v[192:195], v[62:65]
	v_mfma_f32_16x16x32_bf16 v[58:61], v[166:169], v[192:195], v[58:61]
	v_mfma_f32_16x16x32_bf16 v[54:57], v[158:161], v[200:203], v[54:57]
	v_mfma_f32_16x16x32_bf16 v[46:49], v[166:169], v[200:203], v[46:49]
	v_mfma_f32_16x16x32_bf16 v[38:41], v[158:161], v[208:211], v[38:41]
	v_mfma_f32_16x16x32_bf16 v[30:33], v[166:169], v[208:211], v[30:33]
	v_mfma_f32_16x16x32_bf16 v[14:17], v[158:161], v[216:219], v[14:17]
	v_mfma_f32_16x16x32_bf16 v[10:13], v[166:169], v[216:219], v[10:13]
	v_mfma_f32_16x16x32_bf16 v[50:53], v[172:175], v[188:191], v[50:53]
	v_mfma_f32_16x16x32_bf16 v[42:45], v[180:183], v[188:191], v[42:45]
	v_mfma_f32_16x16x32_bf16 v[34:37], v[172:175], v[196:199], v[34:37]
	v_mfma_f32_16x16x32_bf16 v[26:29], v[180:183], v[196:199], v[26:29]
	v_mfma_f32_16x16x32_bf16 v[22:25], v[172:175], v[204:207], v[22:25]
	v_mfma_f32_16x16x32_bf16 v[18:21], v[180:183], v[204:207], v[18:21]
	v_mfma_f32_16x16x32_bf16 v[6:9], v[172:175], v[212:215], v[6:9]
	v_mfma_f32_16x16x32_bf16 v[2:5], v[180:183], v[212:215], v[2:5]
	v_mfma_f32_16x16x32_bf16 v[50:53], v[176:179], v[192:195], v[50:53]
	v_mfma_f32_16x16x32_bf16 v[42:45], v[184:187], v[192:195], v[42:45]
	v_mfma_f32_16x16x32_bf16 v[34:37], v[176:179], v[200:203], v[34:37]
	v_mfma_f32_16x16x32_bf16 v[26:29], v[184:187], v[200:203], v[26:29]
	v_mfma_f32_16x16x32_bf16 v[22:25], v[176:179], v[208:211], v[22:25]
	v_mfma_f32_16x16x32_bf16 v[18:21], v[184:187], v[208:211], v[18:21]
	v_mfma_f32_16x16x32_bf16 v[6:9], v[176:179], v[216:219], v[6:9]
	v_mfma_f32_16x16x32_bf16 v[2:5], v[184:187], v[216:219], v[2:5]
	s_barrier
	s_setprio 0
	s_add_i32 s66, 0, 0x18000
	v_add_u32_e32 v153, s66, v151
	s_add_i32 s67, 0, 0x1c000
	ds_read_b128 v[154:157], v153
	ds_read_b128 v[158:161], v153 offset:1024
	ds_read_b128 v[162:165], v153 offset:2048
	ds_read_b128 v[166:169], v153 offset:3072
	v_add_u32_e32 v153, s67, v151
	ds_read_b128 v[172:175], v153
	ds_read_b128 v[176:179], v153 offset:1024
	ds_read_b128 v[180:183], v153 offset:2048
	ds_read_b128 v[184:187], v153 offset:3072
	s_add_u32 s42, s42, 0x4000
	s_addc_u32 s43, s43, 0
	s_mov_b32 m0, s47
	v_lshl_add_u64 v[224:225], s[42:43], 0, v[130:131]
	ds_read_b128 v[188:191], v152 offset:32768
	ds_read_b128 v[192:195], v152 offset:33792
	ds_read_b128 v[196:199], v152 offset:34816
	ds_read_b128 v[200:203], v152 offset:35840
	ds_read_b128 v[204:207], v152 offset:36864
	ds_read_b128 v[208:211], v152 offset:37888
	ds_read_b128 v[212:215], v152 offset:38912
	ds_read_b128 v[216:219], v152 offset:39936
	global_load_lds_dwordx4 v[224:225], off
	v_lshl_add_u64 v[224:225], s[42:43], 0, v[134:135]
	s_mov_b32 m0, s48
	s_nop 0
	global_load_lds_dwordx4 v[224:225], off
	s_waitcnt vmcnt(8)
	s_waitcnt lgkmcnt(0)
	s_setprio 1
	s_barrier
	v_mfma_f32_16x16x32_bf16 v[122:125], v[154:157], v[188:191], v[122:125]
	v_mfma_f32_16x16x32_bf16 v[126:129], v[162:165], v[188:191], v[126:129]
	v_mfma_f32_16x16x32_bf16 v[118:121], v[154:157], v[196:199], v[118:121]
	v_mfma_f32_16x16x32_bf16 v[106:109], v[162:165], v[196:199], v[106:109]
	v_mfma_f32_16x16x32_bf16 v[98:101], v[154:157], v[204:207], v[98:101]
	v_mfma_f32_16x16x32_bf16 v[90:93], v[162:165], v[204:207], v[90:93]
	v_mfma_f32_16x16x32_bf16 v[110:113], v[154:157], v[212:215], v[110:113]
	v_mfma_f32_16x16x32_bf16 v[82:85], v[162:165], v[212:215], v[82:85]
	v_mfma_f32_16x16x32_bf16 v[122:125], v[158:161], v[192:195], v[122:125]
	v_mfma_f32_16x16x32_bf16 v[126:129], v[166:169], v[192:195], v[126:129]
	v_mfma_f32_16x16x32_bf16 v[118:121], v[158:161], v[200:203], v[118:121]
	v_mfma_f32_16x16x32_bf16 v[106:109], v[166:169], v[200:203], v[106:109]
	v_mfma_f32_16x16x32_bf16 v[98:101], v[158:161], v[208:211], v[98:101]
	v_mfma_f32_16x16x32_bf16 v[90:93], v[166:169], v[208:211], v[90:93]
	v_mfma_f32_16x16x32_bf16 v[110:113], v[158:161], v[216:219], v[110:113]
	v_mfma_f32_16x16x32_bf16 v[82:85], v[166:169], v[216:219], v[82:85]
	v_mfma_f32_16x16x32_bf16 v[114:117], v[172:175], v[188:191], v[114:117]
	v_mfma_f32_16x16x32_bf16 v[102:105], v[180:183], v[188:191], v[102:105]
	v_mfma_f32_16x16x32_bf16 v[94:97], v[172:175], v[196:199], v[94:97]
	v_mfma_f32_16x16x32_bf16 v[86:89], v[180:183], v[196:199], v[86:89]
	v_mfma_f32_16x16x32_bf16 v[78:81], v[172:175], v[204:207], v[78:81]
	v_mfma_f32_16x16x32_bf16 v[70:73], v[180:183], v[204:207], v[70:73]
	v_mfma_f32_16x16x32_bf16 v[66:69], v[172:175], v[212:215], v[66:69]
	v_mfma_f32_16x16x32_bf16 v[74:77], v[180:183], v[212:215], v[74:77]
	v_mfma_f32_16x16x32_bf16 v[114:117], v[176:179], v[192:195], v[114:117]
	v_mfma_f32_16x16x32_bf16 v[102:105], v[184:187], v[192:195], v[102:105]
	v_mfma_f32_16x16x32_bf16 v[94:97], v[176:179], v[200:203], v[94:97]
	v_mfma_f32_16x16x32_bf16 v[86:89], v[184:187], v[200:203], v[86:89]
	v_mfma_f32_16x16x32_bf16 v[78:81], v[176:179], v[208:211], v[78:81]
	v_mfma_f32_16x16x32_bf16 v[70:73], v[184:187], v[208:211], v[70:73]
	v_mfma_f32_16x16x32_bf16 v[66:69], v[176:179], v[216:219], v[66:69]
	v_mfma_f32_16x16x32_bf16 v[74:77], v[184:187], v[216:219], v[74:77]
	s_barrier
; #define PG8_STAGE(bufoff, gbase, voff) do { _Pragma("unroll") for (int _i = 0; _i < 2; ++_i) \
;         __builtin_amdgcn_global_load_lds((const unsigned*)((const char*)(gbase) + (voff)[_i]), (PG8_LAS unsigned*)(lds + (bufoff) + ldsw + _i * 8192), 16, 0, 0); } while (0)
; #define PG8_LDA(dst, b, h) do { _Pragma("unroll") for (int m = 0; m < 4; ++m) _Pragma("unroll") for (int k = 0; k < 2; ++k) dst[m][k] = *(const PG8_LAS bf16x8*)(lds + PG8_SA(b, h) + aoff + m * 2048 + k * 1024); } while (0)
; #define PG8_LDB(dst, b, h) do { _Pragma("unroll") for (int n = 0; n < 2; ++n) _Pragma("unroll") for (int k = 0; k < 2; ++k) dst[n][k] = *(const PG8_LAS bf16x8*)(lds + PG8_SB(b, h) + boff + n * 2048 + k * 1024); } while (0)
; #define PG8_WAIT_V(n) asm volatile("s_waitcnt vmcnt(" #n ")" ::: "memory")
; template <class Epi, class Sched, bool ALIGN_EPI = false, bool SP2 = false>
; __device__ __forceinline__ void gemm_phase(PG8_LAS unsigned char* lds, const Gemm g, const Sched& S, const Epi& E) {
;     ...
;             PG8_LDB(B0, 0, 0); PG8_LDB(B1, 0, 1); PG8_SCHED; PG8_LDA(At, 0, 0); PG8_STAGE(PG8_SA(1, 1), a1 + hstepA, voffA);
;             PG8_WAIT_V(8); PG8_WAIT_L(0); PG8_BAR; PG8_MMA(0, 0, At, B0); PG8_MMA(0, 1, At, B1); PG8_BAR; PG8_SCHED;
;             PG8_LDA(At, 0, 1); PG8_STAGE(PG8_SB(0, 0), b2, voffB); PG8_STAGE(PG8_SB(0, 1), b2 + hstepB, voffB); PG8_STAGE(PG8_SA(0, 0), a2, voffA);
;             PG8_WAIT_V(8); PG8_WAIT_L(0); PG8_BAR; PG8_MMA(1, 0, At, B0); PG8_MMA(1, 1, At, B1); PG8_BAR; PG8_SCHED;
;             PG8_LDB(B0, 1, 0); PG8_LDB(B1, 1, 1); PG8_SCHED; PG8_LDA(At, 1, 0); PG8_STAGE(PG8_SA(0, 1), a2 + hstepA, voffA);
;             PG8_WAIT_V(8); PG8_WAIT_L(0); PG8_BAR; PG8_MMA(0, 0, At, B0); PG8_MMA(0, 1, At, B1); PG8_BAR; PG8_SCHED;
;             PG8_LDA(At, 1, 1); PG8_STAGE(PG8_SB(1, 0), b3, voffB); PG8_STAGE(PG8_SB(1, 1), b3 + hstepB, voffB); PG8_STAGE(PG8_SA(1, 0), a3, voffA);
;             PG8_WAIT_V(8); PG8_WAIT_L(0); PG8_BAR; PG8_MMA(1, 0, At, B0); PG8_MMA(1, 1, At, B1); PG8_BAR; PG8_SCHED;
;     ...
;         if (!has_next) break;
;         if (!keep_) {
; #pragma unroll
;         for (int a = 0; a < 2; ++a)
; #pragma unroll
;             for (int b = 0; b < 2; ++b)
; #pragma unroll
;                 for (int m = 0; m < 4; ++m)
; #pragma unroll
;                     for (int n = 0; n < 2; ++n) acc[a][b][m][n] = (f32x4){0.f, 0.f, 0.f, 0.f};
;         }
	s_setprio 0
	s_add_i32 s42, s66, s44
	v_lshl_add_u64 v[220:221], v[220:221], 0, s[16:17]
	s_mov_b32 m0, s42
	ds_read_b128 v[188:191], v152 offset:49152
	ds_read_b128 v[192:195], v152 offset:50176
	ds_read_b128 v[196:199], v152 offset:51200
	ds_read_b128 v[200:203], v152 offset:52224
	ds_read_b128 v[204:207], v152 offset:53248
	ds_read_b128 v[208:211], v152 offset:54272
	ds_read_b128 v[212:215], v152 offset:55296
	ds_read_b128 v[216:219], v152 offset:56320
	global_load_lds_dwordx4 v[220:221], off
	s_add_i32 m0, s42, 0x2000
	s_add_u32 s40, s40, 0x100080
	v_lshl_add_u64 v[220:221], v[222:223], 0, s[16:17]
	s_addc_u32 s41, s41, 0
	s_add_i32 s42, s67, s44
	global_load_lds_dwordx4 v[220:221], off
	v_lshl_add_u64 v[220:221], s[40:41], 0, v[132:133]
	s_mov_b32 m0, s42
	s_nop 0
	global_load_lds_dwordx4 v[220:221], off
	v_lshl_add_u64 v[220:221], s[40:41], 0, v[136:137]
	s_add_i32 m0, s42, 0x2000
	s_nop 0
	global_load_lds_dwordx4 v[220:221], off
	v_lshl_add_u64 v[220:221], s[38:39], 0, v[130:131]
	s_mov_b32 m0, s50
	s_nop 0
	global_load_lds_dwordx4 v[220:221], off
	v_lshl_add_u64 v[220:221], s[38:39], 0, v[134:135]
	s_mov_b32 m0, s51
	s_nop 0
	global_load_lds_dwordx4 v[220:221], off
	s_waitcnt vmcnt(8)
	s_waitcnt lgkmcnt(0)
	s_setprio 1
	s_barrier
	v_mfma_f32_16x16x32_bf16 v[62:65], v[154:157], v[188:191], v[62:65]
	v_mfma_f32_16x16x32_bf16 v[58:61], v[162:165], v[188:191], v[58:61]
	v_mfma_f32_16x16x32_bf16 v[54:57], v[154:157], v[196:199], v[54:57]
	v_mfma_f32_16x16x32_bf16 v[46:49], v[162:165], v[196:199], v[46:49]
	v_mfma_f32_16x16x32_bf16 v[38:41], v[154:157], v[204:207], v[38:41]
	v_mfma_f32_16x16x32_bf16 v[30:33], v[162:165], v[204:207], v[30:33]
	v_mfma_f32_16x16x32_bf16 v[14:17], v[154:157], v[212:215], v[14:17]
	v_mfma_f32_16x16x32_bf16 v[10:13], v[162:165], v[212:215], v[10:13]
	v_mfma_f32_16x16x32_bf16 v[62:65], v[158:161], v[192:195], v[62:65]
	v_mfma_f32_16x16x32_bf16 v[58:61], v[166:169], v[192:195], v[58:61]
	v_mfma_f32_16x16x32_bf16 v[54:57], v[158:161], v[200:203], v[54:57]
	v_mfma_f32_16x16x32_bf16 v[46:49], v[166:169], v[200:203], v[46:49]
	v_mfma_f32_16x16x32_bf16 v[38:41], v[158:161], v[208:211], v[38:41]
	v_mfma_f32_16x16x32_bf16 v[30:33], v[166:169], v[208:211], v[30:33]
	v_mfma_f32_16x16x32_bf16 v[14:17], v[158:161], v[216:219], v[14:17]
	v_mfma_f32_16x16x32_bf16 v[10:13], v[166:169], v[216:219], v[10:13]
	v_mfma_f32_16x16x32_bf16 v[50:53], v[172:175], v[188:191], v[50:53]
	v_mfma_f32_16x16x32_bf16 v[42:45], v[180:183], v[188:191], v[42:45]
	v_mfma_f32_16x16x32_bf16 v[34:37], v[172:175], v[196:199], v[34:37]
	v_mfma_f32_16x16x32_bf16 v[26:29], v[180:183], v[196:199], v[26:29]
	v_mfma_f32_16x16x32_bf16 v[22:25], v[172:175], v[204:207], v[22:25]
	v_mfma_f32_16x16x32_bf16 v[18:21], v[180:183], v[204:207], v[18:21]
	v_mfma_f32_16x16x32_bf16 v[6:9], v[172:175], v[212:215], v[6:9]
	v_mfma_f32_16x16x32_bf16 v[2:5], v[180:183], v[212:215], v[2:5]
	v_mfma_f32_16x16x32_bf16 v[50:53], v[176:179], v[192:195], v[50:53]
	v_mfma_f32_16x16x32_bf16 v[42:45], v[184:187], v[192:195], v[42:45]
	v_mfma_f32_16x16x32_bf16 v[34:37], v[176:179], v[200:203], v[34:37]
	v_mfma_f32_16x16x32_bf16 v[26:29], v[184:187], v[200:203], v[26:29]
	v_mfma_f32_16x16x32_bf16 v[22:25], v[176:179], v[208:211], v[22:25]
	v_mfma_f32_16x16x32_bf16 v[18:21], v[184:187], v[208:211], v[18:21]
	v_mfma_f32_16x16x32_bf16 v[6:9], v[176:179], v[216:219], v[6:9]
	v_mfma_f32_16x16x32_bf16 v[2:5], v[184:187], v[216:219], v[2:5]
	s_barrier
	s_setprio 0
	s_add_i32 s65, s65, 2
	s_add_u32 s63, s63, 0x100
	s_addc_u32 s64, s64, 0
	s_add_u32 s36, s36, 0x10000
	s_addc_u32 s37, s37, 0
	v_lshl_add_u64 v[148:149], v[148:149], 0, s[18:19]
	s_cmp_gt_u32 s65, 61
	v_lshl_add_u64 v[146:147], v[146:147], 0, s[18:19]
	s_cbranch_scc0 .LBB0_1339
	s_andn2_b64 vcc, exec, s[4:5]
	s_cbranch_vccnz .LBB0_1331
	v_mov_b32_e32 v2, 0
	s_mov_b32 s8, s22
	s_mov_b32 s6, s24
	s_mov_b64 s[10:11], s[30:31]
	s_mov_b64 s[14:15], s[28:29]
	s_mov_b32 s49, s58
	v_mov_b32_e32 v3, v2
	v_mov_b32_e32 v4, v2
	v_mov_b32_e32 v5, v2
	v_mov_b32_e32 v6, v2
	v_mov_b32_e32 v7, v2
	v_mov_b32_e32 v8, v2
	v_mov_b32_e32 v9, v2
	v_mov_b32_e32 v18, v2
	v_mov_b32_e32 v19, v2
	v_mov_b32_e32 v20, v2
	v_mov_b32_e32 v21, v2
	v_mov_b32_e32 v22, v2
	v_mov_b32_e32 v23, v2
	v_mov_b32_e32 v24, v2
	v_mov_b32_e32 v25, v2
	v_mov_b32_e32 v26, v2
	v_mov_b32_e32 v27, v2
	v_mov_b32_e32 v28, v2
	v_mov_b32_e32 v29, v2
	v_mov_b32_e32 v34, v2
	v_mov_b32_e32 v35, v2
	v_mov_b32_e32 v36, v2
	v_mov_b32_e32 v37, v2
	v_mov_b32_e32 v42, v2
	v_mov_b32_e32 v43, v2
	v_mov_b32_e32 v44, v2
	v_mov_b32_e32 v45, v2
	v_mov_b32_e32 v50, v2
	v_mov_b32_e32 v51, v2
	v_mov_b32_e32 v52, v2
	v_mov_b32_e32 v53, v2
	v_mov_b32_e32 v10, v2
	v_mov_b32_e32 v11, v2
	v_mov_b32_e32 v12, v2
	v_mov_b32_e32 v13, v2
	v_mov_b32_e32 v14, v2
	v_mov_b32_e32 v15, v2
	v_mov_b32_e32 v16, v2
	v_mov_b32_e32 v17, v2
	v_mov_b32_e32 v30, v2
	v_mov_b32_e32 v31, v2
	v_mov_b32_e32 v32, v2
	v_mov_b32_e32 v33, v2
	v_mov_b32_e32 v38, v2
	v_mov_b32_e32 v39, v2
	v_mov_b32_e32 v40, v2
	v_mov_b32_e32 v41, v2
	v_mov_b32_e32 v46, v2
	v_mov_b32_e32 v47, v2
	v_mov_b32_e32 v48, v2
	v_mov_b32_e32 v49, v2
	v_mov_b32_e32 v54, v2
	v_mov_b32_e32 v55, v2
	v_mov_b32_e32 v56, v2
	v_mov_b32_e32 v57, v2
	v_mov_b32_e32 v58, v2
	v_mov_b32_e32 v59, v2
	v_mov_b32_e32 v60, v2
	v_mov_b32_e32 v61, v2
	v_mov_b32_e32 v62, v2
	v_mov_b32_e32 v63, v2
	v_mov_b32_e32 v64, v2
	v_mov_b32_e32 v65, v2
	v_mov_b32_e32 v74, v2
	v_mov_b32_e32 v75, v2
	v_mov_b32_e32 v76, v2
	v_mov_b32_e32 v77, v2
	v_mov_b32_e32 v66, v2
	v_mov_b32_e32 v67, v2
	v_mov_b32_e32 v68, v2
	v_mov_b32_e32 v69, v2
	v_mov_b32_e32 v70, v2
	v_mov_b32_e32 v71, v2
	v_mov_b32_e32 v72, v2
	v_mov_b32_e32 v73, v2
	v_mov_b32_e32 v78, v2
	v_mov_b32_e32 v79, v2
	v_mov_b32_e32 v80, v2
	v_mov_b32_e32 v81, v2
	v_mov_b32_e32 v86, v2
	v_mov_b32_e32 v87, v2
	v_mov_b32_e32 v88, v2
	v_mov_b32_e32 v89, v2
	v_mov_b32_e32 v94, v2
	v_mov_b32_e32 v95, v2
	v_mov_b32_e32 v96, v2
	v_mov_b32_e32 v97, v2
	v_mov_b32_e32 v102, v2
	v_mov_b32_e32 v103, v2
	v_mov_b32_e32 v104, v2
	v_mov_b32_e32 v105, v2
	v_mov_b32_e32 v114, v2
	v_mov_b32_e32 v115, v2
	v_mov_b32_e32 v116, v2
	v_mov_b32_e32 v117, v2
	v_mov_b32_e32 v82, v2
	v_mov_b32_e32 v83, v2
	v_mov_b32_e32 v84, v2
	v_mov_b32_e32 v85, v2
	v_mov_b32_e32 v110, v2
	v_mov_b32_e32 v111, v2
	v_mov_b32_e32 v112, v2
	v_mov_b32_e32 v113, v2
	v_mov_b32_e32 v90, v2
	v_mov_b32_e32 v91, v2
	v_mov_b32_e32 v92, v2
	v_mov_b32_e32 v93, v2
	v_mov_b32_e32 v98, v2
	v_mov_b32_e32 v99, v2
	v_mov_b32_e32 v100, v2
	v_mov_b32_e32 v101, v2
	v_mov_b32_e32 v106, v2
	v_mov_b32_e32 v107, v2
	v_mov_b32_e32 v108, v2
	v_mov_b32_e32 v109, v2
	v_mov_b32_e32 v118, v2
	v_mov_b32_e32 v119, v2
	v_mov_b32_e32 v120, v2
	v_mov_b32_e32 v121, v2
	v_mov_b32_e32 v126, v2
	v_mov_b32_e32 v127, v2
	v_mov_b32_e32 v128, v2
	v_mov_b32_e32 v129, v2
	v_mov_b32_e32 v122, v2
	v_mov_b32_e32 v123, v2
	v_mov_b32_e32 v124, v2
	v_mov_b32_e32 v125, v2
	s_branch .LBB0_1331
